# plus: fp8 tables stored column-quarter-major; sort keys e<<8 so row offset is one v_and_or; single-accumulator u dot
# speedup vs baseline: 1.0321x; 1.0082x over previous
; __device__ void convert_tables(const P& p, int vb, int nvb) {
;     ...
;     for (size_t i = gid; i < (size_t)16384 * 1024 / 16; i += gsz) {
;       uint32_t w[4];
; #pragma unroll
;       for (int q = 0; q < 4; q++) {
;         const float4 a = u[i * 4 + q]; int x = 0;
;         x = __builtin_amdgcn_cvt_pk_fp8_f32(a.x * USCALE, a.y * USCALE, x, false);
;         x = __builtin_amdgcn_cvt_pk_fp8_f32(a.z * USCALE, a.w * USCALE, x, true);
;         w[q] = (uint32_t)x;
;       }
;       ou[i] = make_uint4(w[0], w[1], w[2], w[3]);
; #pragma unroll
;       for (int q = 0; q < 4; q++) {
;         const float4 a = v[i * 4 + q]; int x = 0;
;         x = __builtin_amdgcn_cvt_pk_fp8_f32(a.x * VSCALE, a.y * VSCALE, x, false);
;         x = __builtin_amdgcn_cvt_pk_fp8_f32(a.z * VSCALE, a.w * VSCALE, x, true);
;         w[q] = (uint32_t)x;
;       }
;       ov[i] = make_uint4(w[0], w[1], w[2], w[3]);
;     }
.LBB0_275:
	s_or_b64 exec, exec, s[0:1]
	s_bitcmp0_b32 s2, 0
	s_cselect_b64 s[0:1], -1, 0
	s_mov_b32 s29, 0
	v_mov_b32_e32 v6, v178
	s_and_b64 vcc, exec, s[0:1]
	s_waitcnt lgkmcnt(0)
	s_barrier
	s_cbranch_vccnz .LBB0_280
	v_mov_b32_e32 v4, v178
	v_readlane_b32 s26, v248, 2
	v_readlane_b32 s27, v248, 3
	v_ashrrev_i32_e32 v5, 31, v4
	s_nop 0
	v_lshl_add_u64 v[0:1], s[26:27], 0, v[4:5]
	s_mov_b64 s[26:27], 0x100000
	v_cmp_gt_u64_e32 vcc, s[26:27], v[0:1]
	s_and_saveexec_b64 s[26:27], vcc
	s_cbranch_execz .LBB0_279
	s_lshl_b64 s[30:31], s[2:3], 12
	s_add_u32 s98, s80, 0x864000
	s_addc_u32 s99, s81, 0
	s_add_u32 s100, s80, 0x1864000
	s_addc_u32 s101, s81, 0
	s_add_u32 s30, s80, s30
	s_addc_u32 s31, s81, s31
	v_readlane_b32 s36, v248, 10
	v_lshl_add_u64 v[2:3], v[4:5], 4, s[30:31]
	s_mov_b64 s[30:31], 0x1864000
	v_readlane_b32 s37, v248, 11
	v_lshl_add_u64 v[2:3], v[2:3], 0, s[30:31]
	s_lshl_b64 s[30:31], s[36:37], 12
	s_lshl_b64 s[38:39], s[2:3], 14
	s_add_u32 s34, s90, s38
	s_addc_u32 s35, s91, s39
	s_lshl_b64 s[36:37], s[36:37], 14
	s_add_u32 s38, s88, s38
	v_lshlrev_b64 v[4:5], 6, v[4:5]
	s_addc_u32 s39, s89, s39
	s_mov_b64 s[40:41], 0
	s_mov_b64 s[42:43], 0xfffff
.LBB0_278:
	v_bfe_u32 v24, v0, 4, 2
	v_lshrrev_b32_e32 v25, 6, v0
	v_and_b32_e32 v26, 15, v0
	v_lshlrev_b32_e32 v24, 22, v24
	v_lshl_add_u32 v24, v25, 8, v24
	v_lshl_add_u32 v24, v26, 4, v24
	v_lshl_add_u64 v[20:21], s[38:39], 0, v[4:5]
	global_load_dwordx4 v[8:11], v[20:21], off offset:48
	global_load_dwordx4 v[12:15], v[20:21], off offset:32
	global_load_dwordx4 v[16:19], v[20:21], off offset:16
	s_nop 0
	global_load_dwordx4 v[20:23], v[20:21], off
	s_mov_b32 s28, 0xff000000
	v_lshl_add_u64 v[0:1], v[0:1], 0, s[24:25]
	s_waitcnt vmcnt(0)
	v_mul_f32_e32 v7, 0x43800000, v20
	v_mul_f32_e32 v21, 0x43800000, v21
	v_mov_b32_e32 v20, 0
	v_cvt_pk_fp8_f32 v20, v7, v21
	v_mul_f32_e32 v7, 0x43800000, v22
	v_mul_f32_e32 v21, 0x43800000, v23
	v_mov_b32_e32 v22, 0
	v_cvt_pk_fp8_f32 v20, v7, v21 op_sel:[0,0,1]
	v_mul_f32_e32 v7, 0x43800000, v16
	v_mul_f32_e32 v16, 0x43800000, v17
	v_mov_b32_e32 v21, 0
	v_cvt_pk_fp8_f32 v21, v7, v16
	v_mul_f32_e32 v7, 0x43800000, v18
	v_mul_f32_e32 v16, 0x43800000, v19
	v_mov_b32_e32 v23, 0
	v_cvt_pk_fp8_f32 v21, v7, v16 op_sel:[0,0,1]
	v_mul_f32_e32 v7, 0x43800000, v12
	v_mul_f32_e32 v12, 0x43800000, v13
	v_cvt_pk_fp8_f32 v22, v7, v12
	v_mul_f32_e32 v7, 0x43800000, v14
	v_mul_f32_e32 v12, 0x43800000, v15
	v_cvt_pk_fp8_f32 v22, v7, v12 op_sel:[0,0,1]
	v_mul_f32_e32 v7, 0x43800000, v8
	v_mul_f32_e32 v8, 0x43800000, v9
	v_cvt_pk_fp8_f32 v23, v7, v8
	v_mul_f32_e32 v7, 0x43800000, v10
	v_mul_f32_e32 v8, 0x43800000, v11
	v_cvt_pk_fp8_f32 v23, v7, v8 op_sel:[0,0,1]
	v_add_co_u32_e32 v8, vcc, s28, v2
	s_nop 1
	v_addc_co_u32_e32 v9, vcc, -1, v3, vcc
	global_store_dwordx4 v24, v[20:23], s[98:99]
	v_cmp_lt_u64_e32 vcc, s[42:43], v[0:1]
	s_nop 0
	v_lshl_add_u64 v[20:21], s[34:35], 0, v[4:5]
	global_load_dwordx4 v[8:11], v[20:21], off offset:48
	global_load_dwordx4 v[12:15], v[20:21], off offset:32
	global_load_dwordx4 v[16:19], v[20:21], off offset:16
	s_nop 0
	global_load_dwordx4 v[20:23], v[20:21], off
	s_add_u32 s34, s34, s36
	s_addc_u32 s35, s35, s37
	s_add_u32 s38, s38, s36
	s_addc_u32 s39, s39, s37
	s_or_b64 s[40:41], vcc, s[40:41]
	s_waitcnt vmcnt(0)
	v_mul_f32_e32 v7, 0x42800000, v20
	v_mul_f32_e32 v21, 0x42800000, v21
	v_mov_b32_e32 v20, 0
	v_cvt_pk_fp8_f32 v20, v7, v21
	v_mul_f32_e32 v7, 0x42800000, v22
	v_mul_f32_e32 v21, 0x42800000, v23
	v_mov_b32_e32 v22, 0
	v_cvt_pk_fp8_f32 v20, v7, v21 op_sel:[0,0,1]
	v_mul_f32_e32 v7, 0x42800000, v16
	v_mul_f32_e32 v16, 0x42800000, v17
	v_mov_b32_e32 v21, 0
	v_cvt_pk_fp8_f32 v21, v7, v16
	v_mul_f32_e32 v7, 0x42800000, v18
	v_mul_f32_e32 v16, 0x42800000, v19
	v_mov_b32_e32 v23, 0
	v_cvt_pk_fp8_f32 v21, v7, v16 op_sel:[0,0,1]
	v_mul_f32_e32 v7, 0x42800000, v12
	v_mul_f32_e32 v12, 0x42800000, v13
	v_cvt_pk_fp8_f32 v22, v7, v12
	v_mul_f32_e32 v7, 0x42800000, v14
	v_mul_f32_e32 v12, 0x42800000, v15
	v_cvt_pk_fp8_f32 v22, v7, v12 op_sel:[0,0,1]
	v_mul_f32_e32 v7, 0x42800000, v8
	v_mul_f32_e32 v8, 0x42800000, v9
	v_cvt_pk_fp8_f32 v23, v7, v8
	v_mul_f32_e32 v7, 0x42800000, v10
	v_mul_f32_e32 v8, 0x42800000, v11
	v_cvt_pk_fp8_f32 v23, v7, v8 op_sel:[0,0,1]
	global_store_dwordx4 v24, v[20:23], s[100:101]
	v_lshl_add_u64 v[2:3], v[2:3], 0, s[30:31]
	s_andn2_b64 exec, exec, s[40:41]
	s_cbranch_execnz .LBB0_278

; __device__ void convert_tables(const P& p, int vb, int nvb) {
;     ...
;     for (size_t i = gid; i < (size_t)16384 * 1024 / 16; i += gsz) {
;       uint32_t w[4];
; #pragma unroll
;       for (int q = 0; q < 4; q++) {
;         const float4 a = u[i * 4 + q]; int x = 0;
;         x = __builtin_amdgcn_cvt_pk_fp8_f32(a.x * USCALE, a.y * USCALE, x, false);
;         x = __builtin_amdgcn_cvt_pk_fp8_f32(a.z * USCALE, a.w * USCALE, x, true);
;         w[q] = (uint32_t)x;
;       }
;       ou[i] = make_uint4(w[0], w[1], w[2], w[3]);
; #pragma unroll
;       for (int q = 0; q < 4; q++) {
;         const float4 a = v[i * 4 + q]; int x = 0;
;         x = __builtin_amdgcn_cvt_pk_fp8_f32(a.x * VSCALE, a.y * VSCALE, x, false);
;         x = __builtin_amdgcn_cvt_pk_fp8_f32(a.z * VSCALE, a.w * VSCALE, x, true);
;         w[q] = (uint32_t)x;
;       }
;       ov[i] = make_uint4(w[0], w[1], w[2], w[3]);
;     }
.LBB0_299:
	s_and_b64 vcc, exec, s[0:1]
	s_cbranch_vccz .LBB0_304
	v_mov_b32_e32 v4, v178
	v_readlane_b32 s0, v248, 2
	v_readlane_b32 s1, v248, 3
	v_ashrrev_i32_e32 v5, 31, v4
	s_nop 0
	v_lshl_add_u64 v[0:1], s[0:1], 0, v[4:5]
	s_mov_b64 s[0:1], 0x100000
	v_cmp_gt_u64_e32 vcc, s[0:1], v[0:1]
	s_and_saveexec_b64 s[0:1], vcc
	s_cbranch_execz .LBB0_303
	s_lshl_b64 s[28:29], s[2:3], 12
	s_add_u32 s98, s80, 0x864000
	s_addc_u32 s99, s81, 0
	s_add_u32 s100, s80, 0x1864000
	s_addc_u32 s101, s81, 0
	s_add_u32 s28, s80, s28
	s_addc_u32 s29, s81, s29
	v_readlane_b32 s34, v248, 10
	v_lshl_add_u64 v[2:3], v[4:5], 4, s[28:29]
	s_mov_b64 s[28:29], 0x1864000
	v_readlane_b32 s35, v248, 11
	v_lshl_add_u64 v[2:3], v[2:3], 0, s[28:29]
	s_lshl_b64 s[28:29], s[34:35], 12
	s_lshl_b64 s[36:37], s[2:3], 14
	s_add_u32 s30, s90, s36
	s_addc_u32 s31, s91, s37
	s_lshl_b64 s[34:35], s[34:35], 14
	s_add_u32 s36, s88, s36
	v_lshlrev_b64 v[4:5], 6, v[4:5]
	s_addc_u32 s37, s89, s37
	s_mov_b64 s[38:39], 0
	s_mov_b64 s[40:41], 0xfffff
.LBB0_302:
	v_bfe_u32 v24, v0, 4, 2
	v_lshrrev_b32_e32 v25, 6, v0
	v_and_b32_e32 v26, 15, v0
	v_lshlrev_b32_e32 v24, 22, v24
	v_lshl_add_u32 v24, v25, 8, v24
	v_lshl_add_u32 v24, v26, 4, v24
	v_lshl_add_u64 v[18:19], s[36:37], 0, v[4:5]
	global_load_dwordx4 v[6:9], v[18:19], off offset:48
	global_load_dwordx4 v[10:13], v[18:19], off offset:32
	global_load_dwordx4 v[14:17], v[18:19], off offset:16
	s_nop 0
	global_load_dwordx4 v[18:21], v[18:19], off
	s_mov_b32 s3, 0xff000000
	v_lshl_add_u64 v[0:1], v[0:1], 0, s[24:25]
	s_waitcnt vmcnt(3)
	v_mul_f32_e32 v6, 0x43800000, v6
	s_waitcnt vmcnt(2)
	v_mul_f32_e32 v10, 0x43800000, v10
	s_waitcnt vmcnt(1)
	v_mul_f32_e32 v14, 0x43800000, v14
	s_waitcnt vmcnt(0)
	v_mul_f32_e32 v22, 0x43800000, v18
	v_mul_f32_e32 v19, 0x43800000, v19
	v_mov_b32_e32 v18, 0
	v_cvt_pk_fp8_f32 v18, v22, v19
	v_mul_f32_e32 v19, 0x43800000, v20
	v_mul_f32_e32 v20, 0x43800000, v21
	v_mul_f32_e32 v15, 0x43800000, v15
	v_cvt_pk_fp8_f32 v18, v19, v20 op_sel:[0,0,1]
	v_mov_b32_e32 v19, 0
	v_mul_f32_e32 v11, 0x43800000, v11
	v_mov_b32_e32 v20, 0
	v_mul_f32_e32 v7, 0x43800000, v7
	v_mov_b32_e32 v21, 0
	v_cvt_pk_fp8_f32 v19, v14, v15
	v_cvt_pk_fp8_f32 v20, v10, v11
	v_cvt_pk_fp8_f32 v21, v6, v7
	v_mul_f32_e32 v14, 0x43800000, v16
	v_mul_f32_e32 v15, 0x43800000, v17
	v_mul_f32_e32 v10, 0x43800000, v12
	v_mul_f32_e32 v11, 0x43800000, v13
	v_mul_f32_e32 v6, 0x43800000, v8
	v_mul_f32_e32 v7, 0x43800000, v9
	v_cvt_pk_fp8_f32 v19, v14, v15 op_sel:[0,0,1]
	v_cvt_pk_fp8_f32 v20, v10, v11 op_sel:[0,0,1]
	v_cvt_pk_fp8_f32 v21, v6, v7 op_sel:[0,0,1]
	v_add_co_u32_e32 v6, vcc, s3, v2
	s_nop 1
	v_addc_co_u32_e32 v7, vcc, -1, v3, vcc
	global_store_dwordx4 v24, v[18:21], s[98:99]
	v_cmp_lt_u64_e32 vcc, s[40:41], v[0:1]
	s_nop 0
	v_lshl_add_u64 v[18:19], s[30:31], 0, v[4:5]
	global_load_dwordx4 v[6:9], v[18:19], off offset:48
	global_load_dwordx4 v[10:13], v[18:19], off offset:32
	global_load_dwordx4 v[14:17], v[18:19], off offset:16
	s_nop 0
	global_load_dwordx4 v[18:21], v[18:19], off
	s_add_u32 s30, s30, s34
	s_addc_u32 s31, s31, s35
	s_add_u32 s36, s36, s34
	s_addc_u32 s37, s37, s35
	s_or_b64 s[38:39], vcc, s[38:39]
	s_waitcnt vmcnt(3)
	v_mul_f32_e32 v6, 0x42800000, v6
	s_waitcnt vmcnt(2)
	v_mul_f32_e32 v10, 0x42800000, v10
	s_waitcnt vmcnt(1)
	v_mul_f32_e32 v14, 0x42800000, v14
	s_waitcnt vmcnt(0)
	v_mul_f32_e32 v22, 0x42800000, v18
	v_mul_f32_e32 v19, 0x42800000, v19
	v_mov_b32_e32 v18, 0
	v_cvt_pk_fp8_f32 v18, v22, v19
	v_mul_f32_e32 v19, 0x42800000, v20
	v_mul_f32_e32 v20, 0x42800000, v21
	v_mul_f32_e32 v15, 0x42800000, v15
	v_cvt_pk_fp8_f32 v18, v19, v20 op_sel:[0,0,1]
	v_mov_b32_e32 v19, 0
	v_mul_f32_e32 v11, 0x42800000, v11
	v_mov_b32_e32 v20, 0
	v_mul_f32_e32 v7, 0x42800000, v7
	v_mov_b32_e32 v21, 0
	v_cvt_pk_fp8_f32 v19, v14, v15
	v_cvt_pk_fp8_f32 v20, v10, v11
	v_cvt_pk_fp8_f32 v21, v6, v7
	v_mul_f32_e32 v14, 0x42800000, v16
	v_mul_f32_e32 v15, 0x42800000, v17
	v_mul_f32_e32 v10, 0x42800000, v12
	v_mul_f32_e32 v11, 0x42800000, v13
	v_mul_f32_e32 v6, 0x42800000, v8
	v_mul_f32_e32 v7, 0x42800000, v9
	v_cvt_pk_fp8_f32 v19, v14, v15 op_sel:[0,0,1]
	v_cvt_pk_fp8_f32 v20, v10, v11 op_sel:[0,0,1]
	v_cvt_pk_fp8_f32 v21, v6, v7 op_sel:[0,0,1]
	global_store_dwordx4 v24, v[18:21], s[100:101]
	v_lshl_add_u64 v[2:3], v[2:3], 0, s[28:29]
	s_andn2_b64 exec, exec, s[38:39]
	s_cbranch_execnz .LBB0_302

; DEVI int tid_opaque() { int t = threadIdx.x; asm volatile("" : "+v"(t)); return t; }
; DEVI float4 ldbf4(const uint16_t* p) { const uint2 v = *(const uint2*)p; return make_float4(bflo(v.x), bfhi(v.x), bflo(v.y), bfhi(v.y)); }
; __device__ void phase_gather(const P& p, int vb, int nvb, char* smem) {
;   const int t = tid_opaque(), wave = t >> 6, lane = t & 63, g = lane >> 4, j = lane & 15;
;   const uint16_t* h2 = (const uint16_t*)(p.ws + WS_HB);
;   const int* seli = (const int*)(p.ws + WS_SELI); const float* selg = (const float*)(p.ws + WS_SELG);
;   const uint8_t* U = (const uint8_t*)(p.ws + WS_U8); const uint8_t* V = (const uint8_t*)(p.ws + WS_V8);
;   const float* gf = p.in[15]; const float* gfin = p.in[20];
;   uint32_t* kl = (uint32_t*)smem + wave * 1024;
;   float* wl = (float*)(kl + 512);
;   for (int base = (vb * 4 + wave) * 4; base < NREAL; base += nvb * 16) {
;     const int rr = base + g;
;     const uint16_t* hr = h2 + (size_t)rr * DM;
;     f32x2 xf[32];
;     {
;       float ss = 0.f;
; #pragma unroll
;       for (int i = 0; i < 4; i++)
; #pragma unroll
;         for (int q = 0; q < 4; q++) {
;           const float4 a = ldbf4(hr + i * 256 + 16 * j + 4 * q);
;           ss += a.x * a.x + a.y * a.y + a.z * a.z + a.w * a.w;
;         }
;       const float rstd = rsqrtf(wsum16(ss) * (1.f / 1024.f) + EPS);
.LBB0_494:
	s_or_b64 exec, exec, s[0:1]
	s_waitcnt lgkmcnt(0)
	s_barrier
	s_mov_b32 s66, 0xffffff00
	s_lshl_b32 s0, s2, 4
	s_add_u32 s98, s80, 0x864000
	s_addc_u32 s99, s81, 0
	s_add_u32 s100, s80, 0x1864000
	s_addc_u32 s101, s81, 0
	s_nop 0
	v_ashrrev_i32_e32 v0, 6, v178
	s_mov_b32 s83, 0
	v_lshl_add_u32 v126, v0, 2, s0
	s_mov_b32 s0, 0x8000
	v_cmp_gt_i32_e32 vcc, s0, v126
	s_and_saveexec_b64 s[0:1], vcc
	s_cbranch_execz .LBB0_535
	v_and_b32_e32 v1, 64, v162
	v_lshlrev_b32_e32 v4, 12, v0
	v_xor_b32_e32 v0, 1, v162
	v_add_u32_e32 v1, 64, v1
	v_cmp_lt_i32_e32 vcc, v0, v1
	v_bfe_u32 v127, v178, 4, 2
	v_and_b32_e32 v6, 15, v178
	v_cndmask_b32_e32 v0, v162, v0, vcc
	v_lshlrev_b32_e32 v128, 2, v0
	v_xor_b32_e32 v0, 2, v162
	v_cmp_lt_i32_e32 vcc, v0, v1
	v_lshlrev_b32_e32 v12, 4, v6
	v_mov_b32_e32 v13, 0
	v_cndmask_b32_e32 v0, v162, v0, vcc
	v_lshlrev_b32_e32 v129, 2, v0
	v_xor_b32_e32 v0, 4, v162
	v_cmp_lt_i32_e32 vcc, v0, v1
	v_lshlrev_b32_e32 v5, 9, v127
	v_and_b32_e32 v8, 8, v178
	v_cndmask_b32_e32 v0, v162, v0, vcc
	v_lshlrev_b32_e32 v130, 2, v0
	v_xor_b32_e32 v0, 8, v162
	v_cmp_lt_i32_e32 vcc, v0, v1
	v_mov_b32_e32 v1, v13
	v_lshlrev_b32_e32 v2, 5, v6
	v_cndmask_b32_e32 v0, v162, v0, vcc
	v_lshlrev_b32_e32 v131, 2, v0
	v_lshlrev_b32_e32 v0, 6, v6
	v_add3_u32 v133, 16, v4, v5
	v_lshl_add_u64 v[4:5], s[80:81], 0, v[12:13]
	s_mov_b64 s[0:1], 0x864000
	v_cmp_eq_u32_e32 vcc, 0, v8
	v_and_b32_e32 v8, 4, v178
	v_and_b32_e32 v9, 2, v178
	v_and_b32_e32 v10, 1, v178
	s_mov_b64 s[6:7], 0x1864000
	v_lshl_add_u64 v[14:15], s[58:59], 0, v[0:1]
	v_lshlrev_b32_e32 v132, 3, v6
	v_mov_b32_e32 v3, v13
	v_add_u32_e32 v134, v133, v2
	v_mul_i32_i24_e32 v7, 0xffffffe4, v6
	v_lshl_add_u64 v[18:19], v[4:5], 0, s[0:1]
	v_cmp_eq_u32_e64 s[0:1], 0, v8
	v_cmp_eq_u32_e64 s[2:3], 0, v9
	v_cmp_eq_u32_e64 s[4:5], 0, v10
	v_lshl_add_u64 v[20:21], v[4:5], 0, s[6:7]
	v_lshl_add_u64 v[22:23], s[76:77], 0, v[0:1]
	v_cmp_ne_u32_e64 s[6:7], 0, v9
	v_cmp_ne_u32_e64 s[10:11], 0, v8
	v_cmp_lt_u32_e64 s[16:17], 7, v6
	v_lshl_add_u64 v[26:27], s[78:79], 0, v[0:1]
	v_lshlrev_b32_e32 v0, 1, v178
	s_lshl_b32 s28, s82, 4
	v_lshl_add_u64 v[16:17], s[24:25], 0, v[2:3]
	v_lshl_add_u64 v[24:25], s[52:53], 0, v[2:3]
	v_or_b32_e32 v135, 1, v132
	v_or_b32_e32 v136, 2, v132
	v_or_b32_e32 v137, 3, v132
	v_or_b32_e32 v138, 4, v132
	v_or_b32_e32 v139, 5, v132
	v_or_b32_e32 v140, 6, v132
	v_or_b32_e32 v141, 7, v132
	s_xor_b64 s[6:7], s[4:5], s[6:7]
	s_xor_b64 s[8:9], s[2:3], s[10:11]
	s_xor_b64 s[10:11], s[4:5], s[10:11]
	s_xor_b64 s[12:13], s[0:1], s[16:17]
	s_xor_b64 s[14:15], s[2:3], s[16:17]
	s_xor_b64 s[16:17], s[4:5], s[16:17]
	v_cmp_gt_u32_e64 s[18:19], 8, v6
	v_and_b32_e32 v142, 28, v0
	s_mov_b64 s[24:25], 0
	v_mov_b32_e32 v143, 0x358637bd
	s_mov_b32 s29, 0x800000
	s_movk_i32 s30, 0x7fff
	v_add_u32_e32 v144, v134, v7
	s_mov_b32 s31, 0x378e98ab
	s_mov_b32 s33, 0x3b7cd369
	s_mov_b32 s34, 0xbcc618b2
	s_mov_b32 s35, 0x3dda74e4
	s_mov_b32 s36, 0x3f228afd
	s_mov_b32 s37, 0x3e03c728
	s_mov_b32 s38, 0xbfb8aa3b
	s_mov_b32 s39, 0x42ce8ed0
	s_mov_b32 s40, 0xc2b17218
	v_mov_b32_e32 v145, 0x3ba10414
	s_brev_b32 s41, -2
	v_mov_b32_e32 v146, 1
	v_mov_b32_e32 v147, 0xb9c68948
	v_mov_b32_e32 v148, 0x7f800000
.LBB0_496:
	v_or_b32_e32 v0, v126, v127
	v_ashrrev_i32_e32 v1, 31, v0
	v_lshlrev_b64 v[2:3], 11, v[0:1]
	v_lshl_add_u64 v[28:29], v[24:25], 0, v[2:3]
	global_load_dwordx4 v[2:5], v[28:29], off
	global_load_dwordx4 v[6:9], v[28:29], off offset:16
	global_load_dwordx4 v[30:33], v[28:29], off offset:512
	global_load_dwordx4 v[34:37], v[28:29], off offset:528
	global_load_dwordx4 v[38:41], v[28:29], off offset:1024
	global_load_dwordx4 v[42:45], v[28:29], off offset:1040
	global_load_dwordx4 v[46:49], v[28:29], off offset:1536
	global_load_dwordx4 v[50:53], v[28:29], off offset:1552
	s_waitcnt vmcnt(7)
	v_lshlrev_b32_e32 v58, 16, v4
	v_and_b32_e32 v59, 0xffff0000, v4
	v_lshlrev_b32_e32 v60, 16, v5
	v_and_b32_e32 v61, 0xffff0000, v5
	s_waitcnt vmcnt(6)
	v_lshlrev_b32_e32 v62, 16, v6
	v_and_b32_e32 v63, 0xffff0000, v6
	v_lshlrev_b32_e32 v64, 16, v7
	v_and_b32_e32 v65, 0xffff0000, v7
	v_lshlrev_b32_e32 v6, 16, v8
	v_and_b32_e32 v7, 0xffff0000, v8
	v_lshlrev_b32_e32 v4, 16, v9
	v_and_b32_e32 v5, 0xffff0000, v9
	s_waitcnt vmcnt(2)
	v_and_b32_e32 v9, 0xffff0000, v44
	v_and_b32_e32 v8, 0xffff0000, v42
	v_lshlrev_b32_e32 v54, 16, v2
	v_and_b32_e32 v55, 0xffff0000, v2
	v_lshlrev_b32_e32 v56, 16, v3
	v_and_b32_e32 v57, 0xffff0000, v3
	v_lshlrev_b32_e32 v3, 16, v44
	v_lshlrev_b32_e32 v2, 16, v42
	v_pk_mul_f32 v[8:9], v[8:9], v[8:9]
	v_lshlrev_b32_e32 v69, 16, v32
	v_and_b32_e32 v32, 0xffff0000, v32
	v_lshlrev_b32_e32 v72, 16, v34
	v_and_b32_e32 v34, 0xffff0000, v34
	v_pk_fma_f32 v[2:3], v[2:3], v[2:3], v[8:9]
	s_waitcnt vmcnt(1)
; DEVI uint32_t f2bf(float f) { uint32_t u = __float_as_uint(f); return (u + 0x7fffu + ((u >> 16) & 1u)) >> 16; }
; DEVI float bf1(uint16_t h) { return __uint_as_float(((uint32_t)h) << 16); }
; DEVI float4 ldbf4(const uint16_t* p) { const uint2 v = *(const uint2*)p; return make_float4(bflo(v.x), bfhi(v.x), bflo(v.y), bfhi(v.y)); }
; __device__ void phase_gather(const P& p, int vb, int nvb, char* smem) {
;     ...
;       float ss = 0.f;
; #pragma unroll
;       for (int i = 0; i < 4; i++)
; #pragma unroll
;         for (int q = 0; q < 4; q++) {
;           const float4 a = ldbf4(hr + i * 256 + 16 * j + 4 * q);
;           ss += a.x * a.x + a.y * a.y + a.z * a.z + a.w * a.w;
;         }
;       const float rstd = rsqrtf(wsum16(ss) * (1.f / 1024.f) + EPS);
; #pragma unroll
;       for (int i = 0; i < 4; i++) {
; #pragma unroll
;         for (int q = 0; q < 4; q++) {
;           const float4 a = ldbf4(hr + i * 256 + 16 * j + 4 * q);
;           const float4 ga = *(const float4*)(gf + i * 256 + 16 * j + 4 * q);
;           xf[i * 8 + q * 2 + 0] = f32x2{bf1((uint16_t)f2bf(a.x * rstd * ga.x)), bf1((uint16_t)f2bf(a.y * rstd * ga.y))};
;           xf[i * 8 + q * 2 + 1] = f32x2{bf1((uint16_t)f2bf(a.z * rstd * ga.z)), bf1((uint16_t)f2bf(a.w * rstd * ga.w))};
;         }
	v_and_b32_e32 v9, 0xffff0000, v48
	v_and_b32_e32 v8, 0xffff0000, v46
	v_lshlrev_b32_e32 v70, 16, v33
	v_and_b32_e32 v71, 0xffff0000, v33
	v_lshlrev_b32_e32 v11, 16, v45
	v_lshlrev_b32_e32 v10, 16, v43
	v_lshlrev_b32_e32 v33, 16, v48
	v_mul_f32_e32 v81, v32, v32
	v_mul_f32_e32 v82, v34, v34
	v_lshlrev_b32_e32 v32, 16, v46
	v_pk_mul_f32 v[8:9], v[8:9], v[8:9]
	v_lshlrev_b32_e32 v12, 16, v30
	v_and_b32_e32 v66, 0xffff0000, v30
	v_lshlrev_b32_e32 v67, 16, v31
	v_and_b32_e32 v68, 0xffff0000, v31
	v_lshlrev_b32_e32 v73, 16, v35
	v_and_b32_e32 v31, 0xffff0000, v45
	v_and_b32_e32 v30, 0xffff0000, v43
	v_fmac_f32_e32 v82, v72, v72
	v_pk_fma_f32 v[2:3], v[10:11], v[10:11], v[2:3]
	v_lshlrev_b32_e32 v11, 16, v49
	v_lshlrev_b32_e32 v10, 16, v47
	v_pk_fma_f32 v[8:9], v[32:33], v[32:33], v[8:9]
	v_and_b32_e32 v35, 0xffff0000, v35
	v_fmac_f32_e32 v82, v73, v73
	v_pk_fma_f32 v[2:3], v[30:31], v[30:31], v[2:3]
	v_and_b32_e32 v31, 0xffff0000, v49
	v_and_b32_e32 v30, 0xffff0000, v47
	v_pk_fma_f32 v[8:9], v[10:11], v[10:11], v[8:9]
	v_fmac_f32_e32 v82, v35, v35
	v_pk_fma_f32 v[30:31], v[30:31], v[30:31], v[8:9]
	global_load_dwordx4 v[8:11], v[14:15], off offset:16
	global_load_dwordx4 v[32:35], v[14:15], off
	v_lshlrev_b32_e32 v76, 16, v38
	v_and_b32_e32 v38, 0xffff0000, v38
	v_lshlrev_b32_e32 v74, 16, v36
	v_and_b32_e32 v36, 0xffff0000, v36
	v_mul_f32_e32 v84, v38, v38
	v_lshlrev_b32_e32 v77, 16, v39
	v_lshlrev_b32_e32 v78, 16, v40
	v_and_b32_e32 v40, 0xffff0000, v40
	v_mul_f32_e32 v83, v36, v36
	v_fmac_f32_e32 v84, v76, v76
	v_lshlrev_b32_e32 v75, 16, v37
	v_and_b32_e32 v39, 0xffff0000, v39
	v_mul_f32_e32 v85, v40, v40
	v_fmac_f32_e32 v83, v74, v74
	v_fmac_f32_e32 v84, v77, v77
	v_and_b32_e32 v37, 0xffff0000, v37
	v_lshlrev_b32_e32 v79, 16, v41
	v_fmac_f32_e32 v85, v78, v78
	v_fmac_f32_e32 v83, v75, v75
	v_fmac_f32_e32 v84, v39, v39
	s_waitcnt vmcnt(2)
	v_and_b32_e32 v39, 0xffff0000, v52
	v_and_b32_e32 v38, 0xffff0000, v50
	v_and_b32_e32 v41, 0xffff0000, v41
	v_fmac_f32_e32 v85, v79, v79
	v_fmac_f32_e32 v83, v37, v37
	v_lshlrev_b32_e32 v37, 16, v52
	v_lshlrev_b32_e32 v36, 16, v50
	v_pk_mul_f32 v[38:39], v[38:39], v[38:39]
	v_fmac_f32_e32 v85, v41, v41
	v_lshlrev_b32_e32 v41, 16, v53
	v_lshlrev_b32_e32 v40, 16, v51
	v_pk_fma_f32 v[36:37], v[36:37], v[36:37], v[38:39]
	v_and_b32_e32 v43, 0xffff0000, v53
	v_and_b32_e32 v42, 0xffff0000, v51
	v_pk_fma_f32 v[36:37], v[40:41], v[40:41], v[36:37]
	v_mul_f32_e32 v80, v66, v66
	v_pk_fma_f32 v[36:37], v[42:43], v[42:43], v[36:37]
	global_load_dwordx4 v[40:43], v[14:15], off offset:32
	v_fmac_f32_e32 v80, v12, v12
	v_fmac_f32_e32 v80, v67, v67
	v_pk_mul_f32 v[52:53], v[58:59], v[58:59]
	v_fmac_f32_e32 v81, v69, v69
	v_fmac_f32_e32 v80, v68, v68
	v_pk_mul_f32 v[50:51], v[60:61], v[60:61]
	v_pk_mul_f32 v[68:69], v[54:55], v[54:55]
	v_add_f32_e32 v12, v52, v53
	v_pk_mul_f32 v[48:49], v[62:63], v[62:63]
	v_pk_mul_f32 v[66:67], v[56:57], v[56:57]
	v_add_f32_e32 v12, v12, v50
	v_add_f32_e32 v50, v68, v69
	v_pk_mul_f32 v[46:47], v[64:65], v[64:65]
	v_add_f32_e32 v50, v50, v66
	v_add_f32_e32 v48, v48, v49
	v_pk_mul_f32 v[44:45], v[6:7], v[6:7]
	v_add_f32_e32 v12, v51, v12
	v_add_f32_e32 v50, v67, v50
	v_add_f32_e32 v46, v48, v46
	v_pk_mul_f32 v[38:39], v[4:5], v[4:5]
	v_add_f32_e32 v12, v50, v12
	v_add_f32_e32 v46, v47, v46
	v_add_f32_e32 v44, v44, v45
	v_add_f32_e32 v12, v12, v46
	v_add_f32_e32 v38, v44, v38
	global_load_dwordx4 v[44:47], v[14:15], off offset:48
	v_add_f32_e32 v38, v39, v38
	v_fmac_f32_e32 v81, v70, v70
	v_add_f32_e32 v12, v12, v38
	v_fmac_f32_e32 v81, v71, v71
	v_add_f32_e32 v12, v12, v80
	v_add_f32_e32 v12, v12, v81
	v_add_f32_e32 v12, v12, v82
	v_add_f32_e32 v12, v12, v83
	v_add_f32_e32 v12, v12, v84
	v_add_f32_e32 v12, v12, v85
	v_add_f32_e32 v2, v12, v2
	v_add_f32_e32 v2, v2, v3
	v_add_f32_e32 v2, v2, v30
	v_add_f32_e32 v2, v2, v31
	v_add_f32_e32 v2, v2, v36
	v_add_f32_e32 v2, v2, v37
	ds_bpermute_b32 v3, v128, v2
	v_lshlrev_b64 v[30:31], 10, v[0:1]
	s_waitcnt lgkmcnt(0)
	v_add_f32_e32 v2, v2, v3
	ds_bpermute_b32 v3, v129, v2
	s_waitcnt lgkmcnt(0)
	v_add_f32_e32 v2, v2, v3
	ds_bpermute_b32 v3, v130, v2
	s_waitcnt lgkmcnt(0)
	v_add_f32_e32 v2, v2, v3
	ds_bpermute_b32 v3, v131, v2
	s_waitcnt lgkmcnt(0)
	v_add_f32_e32 v2, v2, v3
	v_fmamk_f32 v2, v2, 0x3a800000, v143
	v_mul_f32_e32 v3, 0x4b800000, v2
	v_cmp_gt_f32_e64 s[20:21], s29, v2
	s_nop 1
	v_cndmask_b32_e64 v2, v2, v3, s[20:21]
	v_rsq_f32_e32 v2, v2
	s_nop 0
	v_mul_f32_e32 v3, 0x45800000, v2
	v_cndmask_b32_e64 v2, v2, v3, s[20:21]
	v_pk_mul_f32 v[36:37], v[2:3], v[54:55] op_sel_hi:[0,1]
	s_waitcnt vmcnt(2)
	v_pk_mul_f32 v[32:33], v[32:33], v[36:37]
	s_nop 0
	v_and_b32_sdwa v3, v33, v146 dst_sel:DWORD dst_unused:UNUSED_PAD src0_sel:WORD_1 src1_sel:DWORD
	v_add3_u32 v3, v33, v3, s30
	v_pk_mul_f32 v[36:37], v[2:3], v[56:57] op_sel_hi:[0,1]
	v_pk_mul_f32 v[34:35], v[34:35], v[36:37]
	v_and_b32_sdwa v12, v32, v146 dst_sel:DWORD dst_unused:UNUSED_PAD src0_sel:WORD_1 src1_sel:DWORD
	v_and_b32_e32 v33, 0xffff0000, v3
	v_and_b32_sdwa v3, v35, v146 dst_sel:DWORD dst_unused:UNUSED_PAD src0_sel:WORD_1 src1_sel:DWORD
	v_add3_u32 v12, v32, v12, s30
	v_add3_u32 v3, v35, v3, s30
	v_and_b32_e32 v32, 0xffff0000, v12
	v_and_b32_sdwa v12, v34, v146 dst_sel:DWORD dst_unused:UNUSED_PAD src0_sel:WORD_1 src1_sel:DWORD
	v_pk_mul_f32 v[36:37], v[2:3], v[58:59] op_sel_hi:[0,1]
	v_add3_u32 v12, v34, v12, s30
	v_pk_mul_f32 v[8:9], v[8:9], v[36:37]
	v_and_b32_e32 v35, 0xffff0000, v3
	v_and_b32_e32 v34, 0xffff0000, v12
	v_and_b32_sdwa v3, v9, v146 dst_sel:DWORD dst_unused:UNUSED_PAD src0_sel:WORD_1 src1_sel:DWORD
	v_and_b32_sdwa v12, v8, v146 dst_sel:DWORD dst_unused:UNUSED_PAD src0_sel:WORD_1 src1_sel:DWORD
	v_add3_u32 v3, v9, v3, s30
	v_add3_u32 v8, v8, v12, s30
	v_and_b32_e32 v36, 0xffff0000, v8
	v_pk_mul_f32 v[8:9], v[2:3], v[60:61] op_sel_hi:[0,1]
	v_pk_mul_f32 v[8:9], v[10:11], v[8:9]
	v_and_b32_e32 v37, 0xffff0000, v3
	v_and_b32_sdwa v3, v9, v146 dst_sel:DWORD dst_unused:UNUSED_PAD src0_sel:WORD_1 src1_sel:DWORD
	v_and_b32_sdwa v10, v8, v146 dst_sel:DWORD dst_unused:UNUSED_PAD src0_sel:WORD_1 src1_sel:DWORD
	v_add3_u32 v3, v9, v3, s30
	v_add3_u32 v8, v8, v10, s30
	v_and_b32_e32 v38, 0xffff0000, v8
	v_pk_mul_f32 v[8:9], v[2:3], v[62:63] op_sel_hi:[0,1]
	s_waitcnt vmcnt(1)
; DEVI uint32_t f2bf(float f) { uint32_t u = __float_as_uint(f); return (u + 0x7fffu + ((u >> 16) & 1u)) >> 16; }
; DEVI float bf1(uint16_t h) { return __uint_as_float(((uint32_t)h) << 16); }
; DEVI float4 ldbf4(const uint16_t* p) { const uint2 v = *(const uint2*)p; return make_float4(bflo(v.x), bfhi(v.x), bflo(v.y), bfhi(v.y)); }
; __device__ void phase_gather(const P& p, int vb, int nvb, char* smem) {
;     ...
; #pragma unroll
;       for (int i = 0; i < 4; i++) {
; #pragma unroll
;         for (int q = 0; q < 4; q++) {
;           const float4 a = ldbf4(hr + i * 256 + 16 * j + 4 * q);
;           const float4 ga = *(const float4*)(gf + i * 256 + 16 * j + 4 * q);
;           xf[i * 8 + q * 2 + 0] = f32x2{bf1((uint16_t)f2bf(a.x * rstd * ga.x)), bf1((uint16_t)f2bf(a.y * rstd * ga.y))};
;           xf[i * 8 + q * 2 + 1] = f32x2{bf1((uint16_t)f2bf(a.z * rstd * ga.z)), bf1((uint16_t)f2bf(a.w * rstd * ga.w))};
;         }
;         __builtin_amdgcn_sched_barrier(0);
;       }
	v_pk_mul_f32 v[8:9], v[40:41], v[8:9]
	v_and_b32_e32 v39, 0xffff0000, v3
	v_and_b32_sdwa v3, v9, v146 dst_sel:DWORD dst_unused:UNUSED_PAD src0_sel:WORD_1 src1_sel:DWORD
	v_and_b32_sdwa v10, v8, v146 dst_sel:DWORD dst_unused:UNUSED_PAD src0_sel:WORD_1 src1_sel:DWORD
	v_add3_u32 v3, v9, v3, s30
	v_add3_u32 v8, v8, v10, s30
	v_and_b32_e32 v40, 0xffff0000, v8
	v_pk_mul_f32 v[8:9], v[2:3], v[64:65] op_sel_hi:[0,1]
	v_pk_mul_f32 v[8:9], v[42:43], v[8:9]
	v_and_b32_e32 v41, 0xffff0000, v3
	v_and_b32_sdwa v3, v9, v146 dst_sel:DWORD dst_unused:UNUSED_PAD src0_sel:WORD_1 src1_sel:DWORD
	v_add3_u32 v3, v9, v3, s30
	v_pk_mul_f32 v[6:7], v[2:3], v[6:7] op_sel_hi:[0,1]
	s_waitcnt vmcnt(0)
	v_pk_mul_f32 v[6:7], v[44:45], v[6:7]
	v_and_b32_sdwa v10, v8, v146 dst_sel:DWORD dst_unused:UNUSED_PAD src0_sel:WORD_1 src1_sel:DWORD
	v_and_b32_e32 v43, 0xffff0000, v3
	v_and_b32_sdwa v3, v7, v146 dst_sel:DWORD dst_unused:UNUSED_PAD src0_sel:WORD_1 src1_sel:DWORD
	v_add3_u32 v8, v8, v10, s30
	v_add3_u32 v3, v7, v3, s30
	v_and_b32_e32 v42, 0xffff0000, v8
	v_and_b32_sdwa v8, v6, v146 dst_sel:DWORD dst_unused:UNUSED_PAD src0_sel:WORD_1 src1_sel:DWORD
	v_pk_mul_f32 v[4:5], v[2:3], v[4:5] op_sel_hi:[0,1]
	v_add3_u32 v6, v6, v8, s30
	v_pk_mul_f32 v[4:5], v[4:5], v[46:47]
	v_and_b32_e32 v45, 0xffff0000, v3
	v_and_b32_e32 v44, 0xffff0000, v6
	v_and_b32_sdwa v3, v5, v146 dst_sel:DWORD dst_unused:UNUSED_PAD src0_sel:WORD_1 src1_sel:DWORD
	v_and_b32_sdwa v6, v4, v146 dst_sel:DWORD dst_unused:UNUSED_PAD src0_sel:WORD_1 src1_sel:DWORD
	v_add3_u32 v3, v5, v3, s30
	v_add3_u32 v4, v4, v6, s30
	v_and_b32_e32 v47, 0xffff0000, v3
	v_and_b32_e32 v46, 0xffff0000, v4
	global_load_dwordx4 v[4:7], v[28:29], off offset:512
	global_load_dwordx4 v[8:11], v[28:29], off offset:528
	global_load_dwordx4 v[48:51], v[14:15], off offset:1024
	global_load_dwordx4 v[52:55], v[14:15], off offset:1040
	global_load_dwordx4 v[56:59], v[14:15], off offset:1056
	global_load_dwordx4 v[60:63], v[14:15], off offset:1072
	s_waitcnt vmcnt(5)
	v_lshlrev_b32_e32 v64, 16, v4
	v_and_b32_e32 v65, 0xffff0000, v4
	v_lshlrev_b32_e32 v4, 16, v5
	v_and_b32_e32 v5, 0xffff0000, v5
	v_lshlrev_b32_e32 v66, 16, v6
	v_and_b32_e32 v67, 0xffff0000, v6
	v_lshlrev_b32_e32 v6, 16, v7
	v_and_b32_e32 v7, 0xffff0000, v7
	s_waitcnt vmcnt(4)
	v_lshlrev_b32_e32 v68, 16, v8
	v_and_b32_e32 v69, 0xffff0000, v8
	v_lshlrev_b32_e32 v8, 16, v9
	v_and_b32_e32 v9, 0xffff0000, v9
	v_lshlrev_b32_e32 v70, 16, v10
	v_and_b32_e32 v71, 0xffff0000, v10
	v_lshlrev_b32_e32 v10, 16, v11
	v_and_b32_e32 v11, 0xffff0000, v11
	v_pk_mul_f32 v[64:65], v[2:3], v[64:65] op_sel_hi:[0,1]
	v_pk_mul_f32 v[4:5], v[2:3], v[4:5] op_sel_hi:[0,1]
	v_pk_mul_f32 v[66:67], v[2:3], v[66:67] op_sel_hi:[0,1]
	v_pk_mul_f32 v[6:7], v[2:3], v[6:7] op_sel_hi:[0,1]
	v_pk_mul_f32 v[68:69], v[2:3], v[68:69] op_sel_hi:[0,1]
	v_pk_mul_f32 v[8:9], v[2:3], v[8:9] op_sel_hi:[0,1]
	v_pk_mul_f32 v[70:71], v[2:3], v[70:71] op_sel_hi:[0,1]
	v_pk_mul_f32 v[10:11], v[2:3], v[10:11] op_sel_hi:[0,1]
	s_waitcnt vmcnt(3)
	v_pk_mul_f32 v[48:49], v[48:49], v[64:65]
	v_pk_mul_f32 v[4:5], v[4:5], v[50:51]
	s_waitcnt vmcnt(2)
	v_pk_mul_f32 v[50:51], v[52:53], v[66:67]
	v_pk_mul_f32 v[6:7], v[6:7], v[54:55]
	s_waitcnt vmcnt(1)
	v_pk_mul_f32 v[52:53], v[56:57], v[68:69]
	v_pk_mul_f32 v[8:9], v[8:9], v[58:59]
	s_waitcnt vmcnt(0)
	v_pk_mul_f32 v[54:55], v[60:61], v[70:71]
	v_pk_mul_f32 v[10:11], v[10:11], v[62:63]
	v_and_b32_sdwa v3, v49, v146 dst_sel:DWORD dst_unused:UNUSED_PAD src0_sel:WORD_1 src1_sel:DWORD
	v_and_b32_sdwa v12, v48, v146 dst_sel:DWORD dst_unused:UNUSED_PAD src0_sel:WORD_1 src1_sel:DWORD
	v_and_b32_sdwa v56, v5, v146 dst_sel:DWORD dst_unused:UNUSED_PAD src0_sel:WORD_1 src1_sel:DWORD
	v_and_b32_sdwa v57, v4, v146 dst_sel:DWORD dst_unused:UNUSED_PAD src0_sel:WORD_1 src1_sel:DWORD
	v_and_b32_sdwa v58, v51, v146 dst_sel:DWORD dst_unused:UNUSED_PAD src0_sel:WORD_1 src1_sel:DWORD
	v_and_b32_sdwa v59, v50, v146 dst_sel:DWORD dst_unused:UNUSED_PAD src0_sel:WORD_1 src1_sel:DWORD
	v_and_b32_sdwa v60, v7, v146 dst_sel:DWORD dst_unused:UNUSED_PAD src0_sel:WORD_1 src1_sel:DWORD
	v_and_b32_sdwa v61, v6, v146 dst_sel:DWORD dst_unused:UNUSED_PAD src0_sel:WORD_1 src1_sel:DWORD
	v_and_b32_sdwa v62, v53, v146 dst_sel:DWORD dst_unused:UNUSED_PAD src0_sel:WORD_1 src1_sel:DWORD
	v_and_b32_sdwa v63, v52, v146 dst_sel:DWORD dst_unused:UNUSED_PAD src0_sel:WORD_1 src1_sel:DWORD
	v_and_b32_sdwa v64, v9, v146 dst_sel:DWORD dst_unused:UNUSED_PAD src0_sel:WORD_1 src1_sel:DWORD
	v_and_b32_sdwa v65, v8, v146 dst_sel:DWORD dst_unused:UNUSED_PAD src0_sel:WORD_1 src1_sel:DWORD
	v_and_b32_sdwa v66, v55, v146 dst_sel:DWORD dst_unused:UNUSED_PAD src0_sel:WORD_1 src1_sel:DWORD
	v_and_b32_sdwa v67, v54, v146 dst_sel:DWORD dst_unused:UNUSED_PAD src0_sel:WORD_1 src1_sel:DWORD
	v_and_b32_sdwa v68, v11, v146 dst_sel:DWORD dst_unused:UNUSED_PAD src0_sel:WORD_1 src1_sel:DWORD
	v_and_b32_sdwa v69, v10, v146 dst_sel:DWORD dst_unused:UNUSED_PAD src0_sel:WORD_1 src1_sel:DWORD
	v_add3_u32 v3, v49, v3, s30
	v_add3_u32 v12, v48, v12, s30
	v_add3_u32 v5, v5, v56, s30
	v_add3_u32 v4, v4, v57, s30
	v_add3_u32 v56, v51, v58, s30
	v_add3_u32 v57, v50, v59, s30
	v_add3_u32 v7, v7, v60, s30
	v_add3_u32 v6, v6, v61, s30
	v_add3_u32 v58, v53, v62, s30
	v_add3_u32 v59, v52, v63, s30
	v_add3_u32 v9, v9, v64, s30
	v_add3_u32 v8, v8, v65, s30
	v_add3_u32 v60, v55, v66, s30
	v_add3_u32 v62, v54, v67, s30
	v_add3_u32 v11, v11, v68, s30
	v_add3_u32 v10, v10, v69, s30
	v_and_b32_e32 v49, 0xffff0000, v3
	v_and_b32_e32 v48, 0xffff0000, v12
	v_and_b32_e32 v51, 0xffff0000, v5
	v_and_b32_e32 v50, 0xffff0000, v4
	v_and_b32_e32 v53, 0xffff0000, v56
	v_and_b32_e32 v52, 0xffff0000, v57
	v_and_b32_e32 v55, 0xffff0000, v7
	v_and_b32_e32 v54, 0xffff0000, v6
	v_and_b32_e32 v57, 0xffff0000, v58
	v_and_b32_e32 v56, 0xffff0000, v59
	v_and_b32_e32 v59, 0xffff0000, v9
	v_and_b32_e32 v58, 0xffff0000, v8
	v_and_b32_e32 v61, 0xffff0000, v60
	v_and_b32_e32 v60, 0xffff0000, v62
	v_and_b32_e32 v63, 0xffff0000, v11
	v_and_b32_e32 v62, 0xffff0000, v10
	global_load_dwordx4 v[4:7], v[28:29], off offset:1024
	global_load_dwordx4 v[8:11], v[28:29], off offset:1040
	global_load_dwordx4 v[64:67], v[14:15], off offset:2048
	global_load_dwordx4 v[68:71], v[14:15], off offset:2064
	global_load_dwordx4 v[72:75], v[14:15], off offset:2080
	global_load_dwordx4 v[76:79], v[14:15], off offset:2096
	s_waitcnt vmcnt(5)
; DEVI uint32_t f2bf(float f) { uint32_t u = __float_as_uint(f); return (u + 0x7fffu + ((u >> 16) & 1u)) >> 16; }
; DEVI float bf1(uint16_t h) { return __uint_as_float(((uint32_t)h) << 16); }
; DEVI float4 ldbf4(const uint16_t* p) { const uint2 v = *(const uint2*)p; return make_float4(bflo(v.x), bfhi(v.x), bflo(v.y), bfhi(v.y)); }
; __device__ void phase_gather(const P& p, int vb, int nvb, char* smem) {
;     ...
; #pragma unroll
;       for (int i = 0; i < 4; i++) {
; #pragma unroll
;         for (int q = 0; q < 4; q++) {
;           const float4 a = ldbf4(hr + i * 256 + 16 * j + 4 * q);
;           const float4 ga = *(const float4*)(gf + i * 256 + 16 * j + 4 * q);
;           xf[i * 8 + q * 2 + 0] = f32x2{bf1((uint16_t)f2bf(a.x * rstd * ga.x)), bf1((uint16_t)f2bf(a.y * rstd * ga.y))};
;           xf[i * 8 + q * 2 + 1] = f32x2{bf1((uint16_t)f2bf(a.z * rstd * ga.z)), bf1((uint16_t)f2bf(a.w * rstd * ga.w))};
;         }
;         __builtin_amdgcn_sched_barrier(0);
;       }
	v_lshlrev_b32_e32 v80, 16, v4
	v_and_b32_e32 v81, 0xffff0000, v4
	v_lshlrev_b32_e32 v4, 16, v5
	v_and_b32_e32 v5, 0xffff0000, v5
	v_lshlrev_b32_e32 v82, 16, v6
	v_and_b32_e32 v83, 0xffff0000, v6
	v_lshlrev_b32_e32 v6, 16, v7
	v_and_b32_e32 v7, 0xffff0000, v7
	s_waitcnt vmcnt(4)
	v_lshlrev_b32_e32 v84, 16, v8
	v_and_b32_e32 v85, 0xffff0000, v8
	v_lshlrev_b32_e32 v8, 16, v9
	v_and_b32_e32 v9, 0xffff0000, v9
	v_lshlrev_b32_e32 v86, 16, v10
	v_and_b32_e32 v87, 0xffff0000, v10
	v_lshlrev_b32_e32 v10, 16, v11
	v_and_b32_e32 v11, 0xffff0000, v11
	v_pk_mul_f32 v[80:81], v[2:3], v[80:81] op_sel_hi:[0,1]
	v_pk_mul_f32 v[4:5], v[2:3], v[4:5] op_sel_hi:[0,1]
	v_pk_mul_f32 v[82:83], v[2:3], v[82:83] op_sel_hi:[0,1]
	v_pk_mul_f32 v[6:7], v[2:3], v[6:7] op_sel_hi:[0,1]
	v_pk_mul_f32 v[84:85], v[2:3], v[84:85] op_sel_hi:[0,1]
	v_pk_mul_f32 v[8:9], v[2:3], v[8:9] op_sel_hi:[0,1]
	v_pk_mul_f32 v[86:87], v[2:3], v[86:87] op_sel_hi:[0,1]
	v_pk_mul_f32 v[10:11], v[2:3], v[10:11] op_sel_hi:[0,1]
	s_waitcnt vmcnt(3)
	v_pk_mul_f32 v[64:65], v[64:65], v[80:81]
	v_pk_mul_f32 v[4:5], v[4:5], v[66:67]
	s_waitcnt vmcnt(2)
	v_pk_mul_f32 v[66:67], v[68:69], v[82:83]
	v_pk_mul_f32 v[6:7], v[6:7], v[70:71]
	s_waitcnt vmcnt(1)
	v_pk_mul_f32 v[68:69], v[72:73], v[84:85]
	v_pk_mul_f32 v[8:9], v[8:9], v[74:75]
	s_waitcnt vmcnt(0)
	v_pk_mul_f32 v[70:71], v[76:77], v[86:87]
	v_pk_mul_f32 v[10:11], v[10:11], v[78:79]
	v_and_b32_sdwa v3, v65, v146 dst_sel:DWORD dst_unused:UNUSED_PAD src0_sel:WORD_1 src1_sel:DWORD
	v_and_b32_sdwa v12, v64, v146 dst_sel:DWORD dst_unused:UNUSED_PAD src0_sel:WORD_1 src1_sel:DWORD
	v_and_b32_sdwa v72, v5, v146 dst_sel:DWORD dst_unused:UNUSED_PAD src0_sel:WORD_1 src1_sel:DWORD
	v_and_b32_sdwa v73, v4, v146 dst_sel:DWORD dst_unused:UNUSED_PAD src0_sel:WORD_1 src1_sel:DWORD
	v_and_b32_sdwa v74, v67, v146 dst_sel:DWORD dst_unused:UNUSED_PAD src0_sel:WORD_1 src1_sel:DWORD
	v_and_b32_sdwa v75, v66, v146 dst_sel:DWORD dst_unused:UNUSED_PAD src0_sel:WORD_1 src1_sel:DWORD
	v_and_b32_sdwa v76, v7, v146 dst_sel:DWORD dst_unused:UNUSED_PAD src0_sel:WORD_1 src1_sel:DWORD
	v_and_b32_sdwa v77, v6, v146 dst_sel:DWORD dst_unused:UNUSED_PAD src0_sel:WORD_1 src1_sel:DWORD
	v_and_b32_sdwa v78, v69, v146 dst_sel:DWORD dst_unused:UNUSED_PAD src0_sel:WORD_1 src1_sel:DWORD
	v_and_b32_sdwa v79, v68, v146 dst_sel:DWORD dst_unused:UNUSED_PAD src0_sel:WORD_1 src1_sel:DWORD
	v_and_b32_sdwa v80, v9, v146 dst_sel:DWORD dst_unused:UNUSED_PAD src0_sel:WORD_1 src1_sel:DWORD
	v_and_b32_sdwa v81, v8, v146 dst_sel:DWORD dst_unused:UNUSED_PAD src0_sel:WORD_1 src1_sel:DWORD
	v_and_b32_sdwa v82, v71, v146 dst_sel:DWORD dst_unused:UNUSED_PAD src0_sel:WORD_1 src1_sel:DWORD
	v_and_b32_sdwa v83, v70, v146 dst_sel:DWORD dst_unused:UNUSED_PAD src0_sel:WORD_1 src1_sel:DWORD
	v_and_b32_sdwa v84, v11, v146 dst_sel:DWORD dst_unused:UNUSED_PAD src0_sel:WORD_1 src1_sel:DWORD
	v_and_b32_sdwa v85, v10, v146 dst_sel:DWORD dst_unused:UNUSED_PAD src0_sel:WORD_1 src1_sel:DWORD
	v_add3_u32 v3, v65, v3, s30
	v_add3_u32 v12, v64, v12, s30
	v_add3_u32 v5, v5, v72, s30
	v_add3_u32 v4, v4, v73, s30
	v_add3_u32 v72, v67, v74, s30
	v_add3_u32 v73, v66, v75, s30
	v_add3_u32 v7, v7, v76, s30
	v_add3_u32 v6, v6, v77, s30
	v_add3_u32 v74, v69, v78, s30
	v_add3_u32 v75, v68, v79, s30
	v_add3_u32 v9, v9, v80, s30
	v_add3_u32 v8, v8, v81, s30
	v_add3_u32 v76, v71, v82, s30
	v_add3_u32 v78, v70, v83, s30
	v_add3_u32 v11, v11, v84, s30
	v_add3_u32 v10, v10, v85, s30
	v_and_b32_e32 v65, 0xffff0000, v3
	v_and_b32_e32 v64, 0xffff0000, v12
	v_and_b32_e32 v67, 0xffff0000, v5
	v_and_b32_e32 v66, 0xffff0000, v4
	v_and_b32_e32 v69, 0xffff0000, v72
	v_and_b32_e32 v68, 0xffff0000, v73
	v_and_b32_e32 v71, 0xffff0000, v7
	v_and_b32_e32 v70, 0xffff0000, v6
	v_and_b32_e32 v73, 0xffff0000, v74
	v_and_b32_e32 v72, 0xffff0000, v75
	v_and_b32_e32 v75, 0xffff0000, v9
	v_and_b32_e32 v74, 0xffff0000, v8
	v_and_b32_e32 v77, 0xffff0000, v76
	v_and_b32_e32 v76, 0xffff0000, v78
	v_and_b32_e32 v79, 0xffff0000, v11
	v_and_b32_e32 v78, 0xffff0000, v10
	global_load_dwordx4 v[4:7], v[28:29], off offset:1536
	global_load_dwordx4 v[8:11], v[28:29], off offset:1552
	global_load_dwordx4 v[80:83], v[14:15], off offset:3072
	global_load_dwordx4 v[84:87], v[14:15], off offset:3088
	global_load_dwordx4 v[88:91], v[14:15], off offset:3104
	global_load_dwordx4 v[92:95], v[14:15], off offset:3120
	s_waitcnt vmcnt(5)
	v_lshlrev_b32_e32 v96, 16, v4
	v_and_b32_e32 v97, 0xffff0000, v4
	v_lshlrev_b32_e32 v4, 16, v5
	v_and_b32_e32 v5, 0xffff0000, v5
	v_lshlrev_b32_e32 v98, 16, v6
	v_and_b32_e32 v99, 0xffff0000, v6
	v_lshlrev_b32_e32 v6, 16, v7
	v_and_b32_e32 v7, 0xffff0000, v7
	s_waitcnt vmcnt(4)
	v_lshlrev_b32_e32 v100, 16, v8
	v_and_b32_e32 v101, 0xffff0000, v8
	v_lshlrev_b32_e32 v8, 16, v9
	v_and_b32_e32 v9, 0xffff0000, v9
	v_lshlrev_b32_e32 v102, 16, v10
	v_and_b32_e32 v103, 0xffff0000, v10
	v_lshlrev_b32_e32 v10, 16, v11
	v_and_b32_e32 v11, 0xffff0000, v11
	v_pk_mul_f32 v[96:97], v[2:3], v[96:97] op_sel_hi:[0,1]
	v_pk_mul_f32 v[4:5], v[2:3], v[4:5] op_sel_hi:[0,1]
	v_pk_mul_f32 v[98:99], v[2:3], v[98:99] op_sel_hi:[0,1]
	v_pk_mul_f32 v[6:7], v[2:3], v[6:7] op_sel_hi:[0,1]
	v_pk_mul_f32 v[100:101], v[2:3], v[100:101] op_sel_hi:[0,1]
	v_pk_mul_f32 v[8:9], v[2:3], v[8:9] op_sel_hi:[0,1]
	v_pk_mul_f32 v[102:103], v[2:3], v[102:103] op_sel_hi:[0,1]
	v_pk_mul_f32 v[2:3], v[2:3], v[10:11] op_sel_hi:[0,1]
	s_waitcnt vmcnt(3)
	v_pk_mul_f32 v[10:11], v[80:81], v[96:97]
	v_pk_mul_f32 v[4:5], v[4:5], v[82:83]
	s_waitcnt vmcnt(2)
	v_pk_mul_f32 v[80:81], v[84:85], v[98:99]
	v_pk_mul_f32 v[6:7], v[6:7], v[86:87]
	s_waitcnt vmcnt(1)
; DEVI uint32_t f2bf(float f) { uint32_t u = __float_as_uint(f); return (u + 0x7fffu + ((u >> 16) & 1u)) >> 16; }
; DEVI float bf1(uint16_t h) { return __uint_as_float(((uint32_t)h) << 16); }
; DEVI float4 ldbf4(const uint16_t* p) { const uint2 v = *(const uint2*)p; return make_float4(bflo(v.x), bfhi(v.x), bflo(v.y), bfhi(v.y)); }
; __device__ void phase_gather(const P& p, int vb, int nvb, char* smem) {
;     ...
;       for (int i = 0; i < 4; i++) {
; #pragma unroll
;         for (int q = 0; q < 4; q++) {
;           const float4 a = ldbf4(hr + i * 256 + 16 * j + 4 * q);
;           const float4 ga = *(const float4*)(gf + i * 256 + 16 * j + 4 * q);
;           xf[i * 8 + q * 2 + 0] = f32x2{bf1((uint16_t)f2bf(a.x * rstd * ga.x)), bf1((uint16_t)f2bf(a.y * rstd * ga.y))};
;           xf[i * 8 + q * 2 + 1] = f32x2{bf1((uint16_t)f2bf(a.z * rstd * ga.z)), bf1((uint16_t)f2bf(a.w * rstd * ga.w))};
;         }
;         __builtin_amdgcn_sched_barrier(0);
;       }
;     }
;     {
;       uint32_t ks[8];
;       {
;         const int4 a0 = *(const int4*)(seli + (size_t)rr * 128 + j * 8), a1 = *(const int4*)(seli + (size_t)rr * 128 + j * 8 + 4);
;         const int ev[8] = {a0.x, a0.y, a0.z, a0.w, a1.x, a1.y, a1.z, a1.w};
; #pragma unroll
;         for (int r = 0; r < 8; r++) ks[r] = ((uint32_t)ev[r] << 7) | (uint32_t)(j * 8 + r);
;       }
; #pragma unroll
;       for (int k = 2; k <= 128; k <<= 1) {
; #pragma unroll
;         for (int d = k >> 1; d > 0; d >>= 1) {
;           if (d >= 8) {
; #pragma unroll
;             for (int r = 0; r < 8; r++) {
;               const uint32_t o = (uint32_t)__shfl_xor((int)ks[r], d >> 3);
;               const bool up = (((j * 8 + r) & k) == 0), lower = (((j * 8) & d) == 0);
;               const uint32_t mn = ks[r] < o ? ks[r] : o, mx = ks[r] < o ? o : ks[r];
;               ks[r] = (lower == up) ? mn : mx;
;             }
;           } else {
; #pragma unroll
;             for (int r = 0; r < 8; r++) {
;               if ((r & d) == 0) {
;                 const bool up = (((j * 8 + r) & k) == 0);
;                 const uint32_t x0 = ks[r], x1 = ks[r | d];
;                 const uint32_t mn = x0 < x1 ? x0 : x1, mx = x0 < x1 ? x1 : x0;
;                 ks[r] = up ? mn : mx; ks[r | d] = up ? mx : mn;
;               }
;             }
;           }
;         }
;       }
	v_pk_mul_f32 v[82:83], v[88:89], v[100:101]
	v_pk_mul_f32 v[8:9], v[8:9], v[90:91]
	s_waitcnt vmcnt(0)
	v_pk_mul_f32 v[84:85], v[92:93], v[102:103]
	v_pk_mul_f32 v[2:3], v[2:3], v[94:95]
	v_and_b32_sdwa v12, v11, v146 dst_sel:DWORD dst_unused:UNUSED_PAD src0_sel:WORD_1 src1_sel:DWORD
	v_and_b32_sdwa v86, v10, v146 dst_sel:DWORD dst_unused:UNUSED_PAD src0_sel:WORD_1 src1_sel:DWORD
	v_and_b32_sdwa v87, v5, v146 dst_sel:DWORD dst_unused:UNUSED_PAD src0_sel:WORD_1 src1_sel:DWORD
	v_and_b32_sdwa v88, v4, v146 dst_sel:DWORD dst_unused:UNUSED_PAD src0_sel:WORD_1 src1_sel:DWORD
	v_and_b32_sdwa v89, v81, v146 dst_sel:DWORD dst_unused:UNUSED_PAD src0_sel:WORD_1 src1_sel:DWORD
	v_and_b32_sdwa v90, v80, v146 dst_sel:DWORD dst_unused:UNUSED_PAD src0_sel:WORD_1 src1_sel:DWORD
	v_and_b32_sdwa v91, v7, v146 dst_sel:DWORD dst_unused:UNUSED_PAD src0_sel:WORD_1 src1_sel:DWORD
	v_and_b32_sdwa v92, v6, v146 dst_sel:DWORD dst_unused:UNUSED_PAD src0_sel:WORD_1 src1_sel:DWORD
	v_and_b32_sdwa v93, v83, v146 dst_sel:DWORD dst_unused:UNUSED_PAD src0_sel:WORD_1 src1_sel:DWORD
	v_and_b32_sdwa v94, v82, v146 dst_sel:DWORD dst_unused:UNUSED_PAD src0_sel:WORD_1 src1_sel:DWORD
	v_and_b32_sdwa v95, v9, v146 dst_sel:DWORD dst_unused:UNUSED_PAD src0_sel:WORD_1 src1_sel:DWORD
	v_and_b32_sdwa v96, v8, v146 dst_sel:DWORD dst_unused:UNUSED_PAD src0_sel:WORD_1 src1_sel:DWORD
	v_and_b32_sdwa v97, v85, v146 dst_sel:DWORD dst_unused:UNUSED_PAD src0_sel:WORD_1 src1_sel:DWORD
	v_and_b32_sdwa v98, v84, v146 dst_sel:DWORD dst_unused:UNUSED_PAD src0_sel:WORD_1 src1_sel:DWORD
	v_and_b32_sdwa v99, v3, v146 dst_sel:DWORD dst_unused:UNUSED_PAD src0_sel:WORD_1 src1_sel:DWORD
	v_and_b32_sdwa v100, v2, v146 dst_sel:DWORD dst_unused:UNUSED_PAD src0_sel:WORD_1 src1_sel:DWORD
	v_add3_u32 v11, v11, v12, s30
	v_add3_u32 v10, v10, v86, s30
	v_add3_u32 v5, v5, v87, s30
	v_add3_u32 v4, v4, v88, s30
	v_add3_u32 v12, v81, v89, s30
	v_add3_u32 v86, v80, v90, s30
	v_add3_u32 v7, v7, v91, s30
	v_add3_u32 v6, v6, v92, s30
	v_add3_u32 v88, v83, v93, s30
	v_add3_u32 v90, v82, v94, s30
	v_add3_u32 v9, v9, v95, s30
	v_add3_u32 v8, v8, v96, s30
	v_add3_u32 v92, v85, v97, s30
	v_add3_u32 v94, v84, v98, s30
	v_add3_u32 v3, v3, v99, s30
	v_add3_u32 v2, v2, v100, s30
	v_and_b32_e32 v81, 0xffff0000, v11
	v_and_b32_e32 v80, 0xffff0000, v10
	v_and_b32_e32 v83, 0xffff0000, v5
	v_and_b32_e32 v82, 0xffff0000, v4
	v_and_b32_e32 v85, 0xffff0000, v12
	v_and_b32_e32 v84, 0xffff0000, v86
	v_and_b32_e32 v87, 0xffff0000, v7
	v_and_b32_e32 v86, 0xffff0000, v6
	v_and_b32_e32 v89, 0xffff0000, v88
	v_and_b32_e32 v88, 0xffff0000, v90
	v_and_b32_e32 v91, 0xffff0000, v9
	v_and_b32_e32 v90, 0xffff0000, v8
	v_and_b32_e32 v93, 0xffff0000, v92
	v_and_b32_e32 v92, 0xffff0000, v94
	v_and_b32_e32 v95, 0xffff0000, v3
	v_and_b32_e32 v94, 0xffff0000, v2
	v_lshlrev_b64 v[0:1], 9, v[0:1]
	v_lshl_add_u64 v[10:11], v[16:17], 0, v[0:1]
	global_load_dwordx4 v[2:5], v[10:11], off
	global_load_dwordx4 v[6:9], v[10:11], off offset:16
	v_lshl_add_u64 v[0:1], s[22:23], 0, v[0:1]
	s_mov_b32 s26, -8
	s_waitcnt vmcnt(1)
	v_lshl_or_b32 v2, v2, 8, v132
	v_lshl_or_b32 v3, v3, 8, v135
	v_lshl_or_b32 v4, v4, 8, v136
	v_lshl_or_b32 v5, v5, 8, v137
	s_waitcnt vmcnt(0)
	v_lshl_or_b32 v6, v6, 8, v138
	v_lshl_or_b32 v7, v7, 8, v139
	v_lshl_or_b32 v8, v8, 8, v140
	v_lshl_or_b32 v9, v9, 8, v141
	v_min_u32_e32 v10, v2, v3
	v_max_u32_e32 v2, v2, v3
	v_min_u32_e32 v3, v4, v5
	v_max_u32_e32 v4, v4, v5
	v_min_u32_e32 v5, v6, v7
	v_max_u32_e32 v6, v6, v7
	v_min_u32_e32 v7, v8, v9
	v_max_u32_e32 v8, v8, v9
	v_min_u32_e32 v9, v10, v4
	v_max_u32_e32 v4, v10, v4
	v_min_u32_e32 v10, v2, v3
	v_max_u32_e32 v2, v2, v3
	v_min_u32_e32 v3, v5, v8
	v_max_u32_e32 v5, v5, v8
	v_min_u32_e32 v8, v6, v7
	v_max_u32_e32 v6, v6, v7
	v_min_u32_e32 v7, v9, v10
	v_max_u32_e32 v9, v9, v10
	v_min_u32_e32 v10, v4, v2
	v_max_u32_e32 v2, v4, v2
	v_min_u32_e32 v4, v5, v6
	v_max_u32_e32 v5, v5, v6
	v_min_u32_e32 v6, v3, v8
	v_max_u32_e32 v3, v3, v8
	v_min_u32_e32 v8, v7, v5
	v_max_u32_e32 v5, v7, v5
	v_min_u32_e32 v7, v9, v4
	v_max_u32_e32 v4, v9, v4
	v_min_u32_e32 v9, v10, v3
	v_max_u32_e32 v3, v10, v3
	v_min_u32_e32 v10, v2, v6
	v_max_u32_e32 v2, v2, v6
	v_cndmask_b32_e64 v6, v5, v8, s[4:5]
	v_cndmask_b32_e64 v5, v8, v5, s[4:5]
	v_cndmask_b32_e64 v8, v4, v7, s[4:5]
	v_cndmask_b32_e64 v4, v7, v4, s[4:5]
	v_cndmask_b32_e64 v7, v3, v9, s[4:5]
	v_cndmask_b32_e64 v3, v9, v3, s[4:5]
	v_cndmask_b32_e64 v9, v2, v10, s[4:5]
	v_cndmask_b32_e64 v2, v10, v2, s[4:5]
	v_min_u32_e32 v10, v6, v7
	v_max_u32_e32 v6, v6, v7
	v_min_u32_e32 v7, v8, v9
	v_max_u32_e32 v8, v8, v9
	v_min_u32_e32 v9, v5, v3
	v_max_u32_e32 v3, v5, v3
	v_min_u32_e32 v5, v4, v2
	v_max_u32_e32 v2, v4, v2
	v_cndmask_b32_e64 v4, v6, v10, s[4:5]
	v_cndmask_b32_e64 v6, v10, v6, s[4:5]
	v_cndmask_b32_e64 v10, v8, v7, s[4:5]
	v_cndmask_b32_e64 v7, v7, v8, s[4:5]
	v_cndmask_b32_e64 v8, v3, v9, s[4:5]
	v_cndmask_b32_e64 v3, v9, v3, s[4:5]
	v_cndmask_b32_e64 v9, v2, v5, s[4:5]
	v_cndmask_b32_e64 v2, v5, v2, s[4:5]
	v_min_u32_e32 v5, v4, v10
	v_max_u32_e32 v4, v4, v10
	v_min_u32_e32 v10, v6, v7
	v_max_u32_e32 v6, v6, v7
	v_min_u32_e32 v7, v8, v9
	v_max_u32_e32 v8, v8, v9
	v_min_u32_e32 v9, v3, v2
	v_max_u32_e32 v2, v3, v2
	v_cndmask_b32_e64 v3, v4, v5, s[4:5]
	v_cndmask_b32_e64 v4, v5, v4, s[4:5]
	v_cndmask_b32_e64 v5, v6, v10, s[4:5]
	v_cndmask_b32_e64 v6, v10, v6, s[4:5]
	v_cndmask_b32_e64 v10, v8, v7, s[4:5]
	v_cndmask_b32_e64 v7, v7, v8, s[4:5]
	v_cndmask_b32_e64 v8, v2, v9, s[4:5]
	v_cndmask_b32_e64 v2, v9, v2, s[4:5]
	ds_bpermute_b32 v9, v128, v3
	ds_bpermute_b32 v11, v128, v4
	ds_bpermute_b32 v12, v128, v5
	ds_bpermute_b32 v96, v128, v6
	ds_bpermute_b32 v97, v128, v10
	s_waitcnt lgkmcnt(4)
; __device__ void phase_gather(const P& p, int vb, int nvb, char* smem) {
;     ...
; #pragma unroll
;       for (int k = 2; k <= 128; k <<= 1) {
; #pragma unroll
;         for (int d = k >> 1; d > 0; d >>= 1) {
;           if (d >= 8) {
; #pragma unroll
;             for (int r = 0; r < 8; r++) {
;               const uint32_t o = (uint32_t)__shfl_xor((int)ks[r], d >> 3);
;               const bool up = (((j * 8 + r) & k) == 0), lower = (((j * 8) & d) == 0);
;               const uint32_t mn = ks[r] < o ? ks[r] : o, mx = ks[r] < o ? o : ks[r];
;               ks[r] = (lower == up) ? mn : mx;
;             }
;           } else {
; #pragma unroll
;             for (int r = 0; r < 8; r++) {
;               if ((r & d) == 0) {
;                 const bool up = (((j * 8 + r) & k) == 0);
;                 const uint32_t x0 = ks[r], x1 = ks[r | d];
;                 const uint32_t mn = x0 < x1 ? x0 : x1, mx = x0 < x1 ? x1 : x0;
;                 ks[r] = up ? mn : mx; ks[r | d] = up ? mx : mn;
;               }
;             }
;           }
;         }
;       }
	v_min_u32_e32 v98, v3, v9
	v_max_u32_e32 v3, v3, v9
	s_waitcnt lgkmcnt(3)
	v_min_u32_e32 v9, v4, v11
	v_max_u32_e32 v4, v4, v11
	v_cndmask_b32_e64 v4, v4, v9, s[6:7]
	ds_bpermute_b32 v9, v128, v7
	s_waitcnt lgkmcnt(3)
	v_min_u32_e32 v11, v5, v12
	v_max_u32_e32 v5, v5, v12
	s_waitcnt lgkmcnt(2)
	v_min_u32_e32 v12, v6, v96
	v_cndmask_b32_e64 v5, v5, v11, s[6:7]
	v_max_u32_e32 v6, v6, v96
	s_waitcnt lgkmcnt(1)
	v_min_u32_e32 v11, v10, v97
	v_max_u32_e32 v10, v10, v97
	v_cndmask_b32_e64 v6, v6, v12, s[6:7]
	v_cndmask_b32_e64 v10, v10, v11, s[6:7]
	ds_bpermute_b32 v11, v128, v8
	s_waitcnt lgkmcnt(1)
	v_min_u32_e32 v12, v7, v9
	v_max_u32_e32 v7, v7, v9
	ds_bpermute_b32 v9, v128, v2
	v_cndmask_b32_e64 v3, v3, v98, s[6:7]
	v_cndmask_b32_e64 v7, v7, v12, s[6:7]
	s_waitcnt lgkmcnt(1)
	v_min_u32_e32 v12, v8, v11
	v_max_u32_e32 v8, v8, v11
	s_waitcnt lgkmcnt(0)
	v_min_u32_e32 v11, v2, v9
	v_max_u32_e32 v2, v2, v9
	v_min_u32_e32 v9, v3, v10
	v_max_u32_e32 v3, v3, v10
	v_cndmask_b32_e64 v8, v8, v12, s[6:7]
	v_cndmask_b32_e64 v10, v3, v9, s[2:3]
	v_cndmask_b32_e64 v3, v9, v3, s[2:3]
	v_min_u32_e32 v9, v4, v7
	v_max_u32_e32 v4, v4, v7
	v_cndmask_b32_e64 v2, v2, v11, s[6:7]
	v_cndmask_b32_e64 v7, v4, v9, s[2:3]
	v_cndmask_b32_e64 v4, v9, v4, s[2:3]
	v_min_u32_e32 v9, v5, v8
	v_max_u32_e32 v5, v5, v8
	v_cndmask_b32_e64 v8, v5, v9, s[2:3]
	v_cndmask_b32_e64 v5, v9, v5, s[2:3]
	v_min_u32_e32 v9, v6, v2
	v_max_u32_e32 v2, v6, v2
	v_cndmask_b32_e64 v6, v2, v9, s[2:3]
	v_cndmask_b32_e64 v2, v9, v2, s[2:3]
	v_min_u32_e32 v9, v10, v8
	v_max_u32_e32 v8, v10, v8
	v_cndmask_b32_e64 v10, v8, v9, s[2:3]
	v_cndmask_b32_e64 v8, v9, v8, s[2:3]
	v_min_u32_e32 v9, v7, v6
	v_max_u32_e32 v6, v7, v6
	v_cndmask_b32_e64 v7, v6, v9, s[2:3]
	v_cndmask_b32_e64 v6, v9, v6, s[2:3]
	v_min_u32_e32 v9, v3, v5
	v_max_u32_e32 v3, v3, v5
	v_cndmask_b32_e64 v5, v3, v9, s[2:3]
	v_cndmask_b32_e64 v3, v9, v3, s[2:3]
	v_min_u32_e32 v9, v4, v2
	v_max_u32_e32 v2, v4, v2
	v_cndmask_b32_e64 v4, v2, v9, s[2:3]
	v_cndmask_b32_e64 v2, v9, v2, s[2:3]
	v_min_u32_e32 v9, v10, v7
	v_max_u32_e32 v7, v10, v7
	v_cndmask_b32_e64 v10, v7, v9, s[2:3]
	v_cndmask_b32_e64 v7, v9, v7, s[2:3]
	v_min_u32_e32 v9, v8, v6
	v_max_u32_e32 v6, v8, v6
	v_cndmask_b32_e64 v8, v6, v9, s[2:3]
	v_cndmask_b32_e64 v6, v9, v6, s[2:3]
	v_min_u32_e32 v9, v5, v4
	v_max_u32_e32 v4, v5, v4
	v_cndmask_b32_e64 v5, v4, v9, s[2:3]
	v_cndmask_b32_e64 v4, v9, v4, s[2:3]
	v_min_u32_e32 v9, v3, v2
	ds_bpermute_b32 v11, v129, v10
	v_max_u32_e32 v2, v3, v2
	v_cndmask_b32_e64 v3, v2, v9, s[2:3]
	v_cndmask_b32_e64 v2, v9, v2, s[2:3]
	ds_bpermute_b32 v9, v129, v7
	s_waitcnt lgkmcnt(1)
	v_min_u32_e32 v12, v10, v11
	v_max_u32_e32 v10, v10, v11
	ds_bpermute_b32 v11, v129, v8
	v_cndmask_b32_e64 v10, v10, v12, s[8:9]
	s_waitcnt lgkmcnt(1)
	v_min_u32_e32 v12, v7, v9
	v_max_u32_e32 v7, v7, v9
	ds_bpermute_b32 v9, v129, v6
	v_cndmask_b32_e64 v7, v7, v12, s[8:9]
	s_waitcnt lgkmcnt(1)
	v_min_u32_e32 v12, v8, v11
	v_max_u32_e32 v8, v8, v11
	ds_bpermute_b32 v11, v129, v5
	v_cndmask_b32_e64 v8, v8, v12, s[8:9]
	s_waitcnt lgkmcnt(1)
	v_min_u32_e32 v12, v6, v9
	v_max_u32_e32 v6, v6, v9
	ds_bpermute_b32 v9, v129, v4
	v_cndmask_b32_e64 v6, v6, v12, s[8:9]
	s_waitcnt lgkmcnt(1)
	v_min_u32_e32 v12, v5, v11
	v_max_u32_e32 v5, v5, v11
	ds_bpermute_b32 v11, v129, v3
	v_cndmask_b32_e64 v5, v5, v12, s[8:9]
	s_waitcnt lgkmcnt(1)
	v_min_u32_e32 v12, v4, v9
	v_max_u32_e32 v4, v4, v9
	ds_bpermute_b32 v9, v129, v2
	v_cndmask_b32_e64 v4, v4, v12, s[8:9]
	s_waitcnt lgkmcnt(1)
	v_min_u32_e32 v12, v3, v11
	v_max_u32_e32 v3, v3, v11
	ds_bpermute_b32 v11, v128, v10
	v_cndmask_b32_e64 v3, v3, v12, s[8:9]
	s_waitcnt lgkmcnt(1)
	v_min_u32_e32 v12, v2, v9
	v_max_u32_e32 v2, v2, v9
	ds_bpermute_b32 v9, v128, v7
	v_cndmask_b32_e64 v2, v2, v12, s[8:9]
	s_waitcnt lgkmcnt(1)
	v_min_u32_e32 v12, v10, v11
	v_max_u32_e32 v10, v10, v11
	ds_bpermute_b32 v11, v128, v8
	v_cndmask_b32_e64 v10, v10, v12, s[10:11]
	s_waitcnt lgkmcnt(1)
	v_min_u32_e32 v12, v7, v9
	v_max_u32_e32 v7, v7, v9
	ds_bpermute_b32 v9, v128, v6
	v_cndmask_b32_e64 v7, v7, v12, s[10:11]
	s_waitcnt lgkmcnt(1)
	v_min_u32_e32 v12, v8, v11
	v_max_u32_e32 v8, v8, v11
	ds_bpermute_b32 v11, v128, v5
	v_cndmask_b32_e64 v8, v8, v12, s[10:11]
	s_waitcnt lgkmcnt(1)
	v_min_u32_e32 v12, v6, v9
	v_max_u32_e32 v6, v6, v9
	ds_bpermute_b32 v9, v128, v4
	v_cndmask_b32_e64 v6, v6, v12, s[10:11]
	s_waitcnt lgkmcnt(1)
	v_min_u32_e32 v12, v5, v11
	v_max_u32_e32 v5, v5, v11
	v_cndmask_b32_e64 v5, v5, v12, s[10:11]
	ds_bpermute_b32 v11, v128, v3
	s_waitcnt lgkmcnt(1)
	v_min_u32_e32 v12, v4, v9
	v_max_u32_e32 v4, v4, v9
	ds_bpermute_b32 v9, v128, v2
	v_cndmask_b32_e64 v4, v4, v12, s[10:11]
	s_waitcnt lgkmcnt(1)
	v_min_u32_e32 v12, v3, v11
	v_max_u32_e32 v3, v3, v11
	v_cndmask_b32_e64 v3, v3, v12, s[10:11]
	s_waitcnt lgkmcnt(0)
; __device__ void phase_gather(const P& p, int vb, int nvb, char* smem) {
;     ...
; #pragma unroll
;       for (int k = 2; k <= 128; k <<= 1) {
; #pragma unroll
;         for (int d = k >> 1; d > 0; d >>= 1) {
;           if (d >= 8) {
; #pragma unroll
;             for (int r = 0; r < 8; r++) {
;               const uint32_t o = (uint32_t)__shfl_xor((int)ks[r], d >> 3);
;               const bool up = (((j * 8 + r) & k) == 0), lower = (((j * 8) & d) == 0);
;               const uint32_t mn = ks[r] < o ? ks[r] : o, mx = ks[r] < o ? o : ks[r];
;               ks[r] = (lower == up) ? mn : mx;
;             }
;           } else {
; #pragma unroll
;             for (int r = 0; r < 8; r++) {
;               if ((r & d) == 0) {
;                 const bool up = (((j * 8 + r) & k) == 0);
;                 const uint32_t x0 = ks[r], x1 = ks[r | d];
;                 const uint32_t mn = x0 < x1 ? x0 : x1, mx = x0 < x1 ? x1 : x0;
;                 ks[r] = up ? mn : mx; ks[r | d] = up ? mx : mn;
;               }
;             }
;           }
;         }
;       }
	v_min_u32_e32 v11, v2, v9
	v_max_u32_e32 v2, v2, v9
	v_min_u32_e32 v9, v10, v5
	v_max_u32_e32 v5, v10, v5
	v_cndmask_b32_e64 v10, v5, v9, s[0:1]
	v_cndmask_b32_e64 v5, v9, v5, s[0:1]
	v_min_u32_e32 v9, v7, v4
	v_max_u32_e32 v4, v7, v4
	v_cndmask_b32_e64 v2, v2, v11, s[10:11]
	v_cndmask_b32_e64 v7, v4, v9, s[0:1]
	v_cndmask_b32_e64 v4, v9, v4, s[0:1]
	v_min_u32_e32 v9, v8, v3
	v_max_u32_e32 v3, v8, v3
	v_cndmask_b32_e64 v8, v3, v9, s[0:1]
	v_cndmask_b32_e64 v3, v9, v3, s[0:1]
	v_min_u32_e32 v9, v6, v2
	v_max_u32_e32 v2, v6, v2
	v_cndmask_b32_e64 v6, v2, v9, s[0:1]
	v_cndmask_b32_e64 v2, v9, v2, s[0:1]
	v_min_u32_e32 v9, v10, v8
	v_max_u32_e32 v8, v10, v8
	v_cndmask_b32_e64 v10, v8, v9, s[0:1]
	v_cndmask_b32_e64 v8, v9, v8, s[0:1]
	v_min_u32_e32 v9, v7, v6
	v_max_u32_e32 v6, v7, v6
	v_cndmask_b32_e64 v7, v6, v9, s[0:1]
	v_cndmask_b32_e64 v6, v9, v6, s[0:1]
	v_min_u32_e32 v9, v5, v3
	v_max_u32_e32 v3, v5, v3
	v_cndmask_b32_e64 v5, v3, v9, s[0:1]
	v_cndmask_b32_e64 v3, v9, v3, s[0:1]
	v_min_u32_e32 v9, v4, v2
	v_max_u32_e32 v2, v4, v2
	v_cndmask_b32_e64 v4, v2, v9, s[0:1]
	v_cndmask_b32_e64 v2, v9, v2, s[0:1]
	v_min_u32_e32 v9, v10, v7
	v_max_u32_e32 v7, v10, v7
	v_cndmask_b32_e64 v10, v7, v9, s[0:1]
	v_cndmask_b32_e64 v7, v9, v7, s[0:1]
	v_min_u32_e32 v9, v8, v6
	v_max_u32_e32 v6, v8, v6
	v_cndmask_b32_e64 v8, v6, v9, s[0:1]
	v_cndmask_b32_e64 v6, v9, v6, s[0:1]
	v_min_u32_e32 v9, v5, v4
	v_max_u32_e32 v4, v5, v4
	v_cndmask_b32_e64 v5, v4, v9, s[0:1]
	v_cndmask_b32_e64 v4, v9, v4, s[0:1]
	v_min_u32_e32 v9, v3, v2
	ds_bpermute_b32 v11, v130, v10
	v_max_u32_e32 v2, v3, v2
	v_cndmask_b32_e64 v3, v2, v9, s[0:1]
	v_cndmask_b32_e64 v2, v9, v2, s[0:1]
	ds_bpermute_b32 v9, v130, v7
	s_waitcnt lgkmcnt(1)
	v_min_u32_e32 v12, v10, v11
	v_max_u32_e32 v10, v10, v11
	ds_bpermute_b32 v11, v130, v8
	v_cndmask_b32_e64 v10, v10, v12, s[12:13]
	s_waitcnt lgkmcnt(1)
	v_min_u32_e32 v12, v7, v9
	v_max_u32_e32 v7, v7, v9
	ds_bpermute_b32 v9, v130, v6
	v_cndmask_b32_e64 v7, v7, v12, s[12:13]
	s_waitcnt lgkmcnt(1)
	v_min_u32_e32 v12, v8, v11
	v_max_u32_e32 v8, v8, v11
	ds_bpermute_b32 v11, v130, v5
	v_cndmask_b32_e64 v8, v8, v12, s[12:13]
	s_waitcnt lgkmcnt(1)
	v_min_u32_e32 v12, v6, v9
	v_max_u32_e32 v6, v6, v9
	ds_bpermute_b32 v9, v130, v4
	v_cndmask_b32_e64 v6, v6, v12, s[12:13]
	s_waitcnt lgkmcnt(1)
	v_min_u32_e32 v12, v5, v11
	v_max_u32_e32 v5, v5, v11
	ds_bpermute_b32 v11, v130, v3
	v_cndmask_b32_e64 v5, v5, v12, s[12:13]
	s_waitcnt lgkmcnt(1)
	v_min_u32_e32 v12, v4, v9
	v_max_u32_e32 v4, v4, v9
	ds_bpermute_b32 v9, v130, v2
	v_cndmask_b32_e64 v4, v4, v12, s[12:13]
	s_waitcnt lgkmcnt(1)
	v_min_u32_e32 v12, v3, v11
	v_max_u32_e32 v3, v3, v11
	ds_bpermute_b32 v11, v129, v10
	v_cndmask_b32_e64 v3, v3, v12, s[12:13]
	s_waitcnt lgkmcnt(1)
	v_min_u32_e32 v12, v2, v9
	v_max_u32_e32 v2, v2, v9
	ds_bpermute_b32 v9, v129, v7
	v_cndmask_b32_e64 v2, v2, v12, s[12:13]
	s_waitcnt lgkmcnt(1)
	v_min_u32_e32 v12, v10, v11
	v_max_u32_e32 v10, v10, v11
	ds_bpermute_b32 v11, v129, v8
	v_cndmask_b32_e64 v10, v10, v12, s[14:15]
	s_waitcnt lgkmcnt(1)
	v_min_u32_e32 v12, v7, v9
	v_max_u32_e32 v7, v7, v9
	ds_bpermute_b32 v9, v129, v6
	v_cndmask_b32_e64 v7, v7, v12, s[14:15]
	s_waitcnt lgkmcnt(1)
	v_min_u32_e32 v12, v8, v11
	v_max_u32_e32 v8, v8, v11
	ds_bpermute_b32 v11, v129, v5
	v_cndmask_b32_e64 v8, v8, v12, s[14:15]
	s_waitcnt lgkmcnt(1)
	v_min_u32_e32 v12, v6, v9
	v_max_u32_e32 v6, v6, v9
	ds_bpermute_b32 v9, v129, v4
	v_cndmask_b32_e64 v6, v6, v12, s[14:15]
	s_waitcnt lgkmcnt(1)
	v_min_u32_e32 v12, v5, v11
	v_max_u32_e32 v5, v5, v11
	ds_bpermute_b32 v11, v129, v3
	v_cndmask_b32_e64 v5, v5, v12, s[14:15]
	s_waitcnt lgkmcnt(1)
	v_min_u32_e32 v12, v4, v9
	v_max_u32_e32 v4, v4, v9
	ds_bpermute_b32 v9, v129, v2
	v_cndmask_b32_e64 v4, v4, v12, s[14:15]
	s_waitcnt lgkmcnt(1)
	v_min_u32_e32 v12, v3, v11
	v_max_u32_e32 v3, v3, v11
	ds_bpermute_b32 v11, v128, v10
	v_cndmask_b32_e64 v3, v3, v12, s[14:15]
	s_waitcnt lgkmcnt(1)
	v_min_u32_e32 v12, v2, v9
	v_max_u32_e32 v2, v2, v9
	ds_bpermute_b32 v9, v128, v7
	v_cndmask_b32_e64 v2, v2, v12, s[14:15]
	s_waitcnt lgkmcnt(1)
	v_min_u32_e32 v12, v10, v11
	v_max_u32_e32 v10, v10, v11
	ds_bpermute_b32 v11, v128, v8
	v_cndmask_b32_e64 v10, v10, v12, s[16:17]
	s_waitcnt lgkmcnt(1)
	v_min_u32_e32 v12, v7, v9
	v_max_u32_e32 v7, v7, v9
	ds_bpermute_b32 v9, v128, v6
	v_cndmask_b32_e64 v7, v7, v12, s[16:17]
	s_waitcnt lgkmcnt(1)
	v_min_u32_e32 v12, v8, v11
	v_max_u32_e32 v8, v8, v11
	ds_bpermute_b32 v11, v128, v5
	v_cndmask_b32_e64 v8, v8, v12, s[16:17]
	s_waitcnt lgkmcnt(1)
	v_min_u32_e32 v12, v6, v9
	v_max_u32_e32 v6, v6, v9
	ds_bpermute_b32 v9, v128, v4
	v_cndmask_b32_e64 v6, v6, v12, s[16:17]
	s_waitcnt lgkmcnt(1)
	v_min_u32_e32 v12, v5, v11
	v_max_u32_e32 v5, v5, v11
	v_cndmask_b32_e64 v5, v5, v12, s[16:17]
	ds_bpermute_b32 v11, v128, v3
	s_waitcnt lgkmcnt(1)
	v_min_u32_e32 v12, v4, v9
	v_max_u32_e32 v4, v4, v9
	ds_bpermute_b32 v9, v128, v2
	v_cndmask_b32_e64 v4, v4, v12, s[16:17]
	s_waitcnt lgkmcnt(1)
	v_min_u32_e32 v12, v3, v11
	v_max_u32_e32 v3, v3, v11
	v_cndmask_b32_e64 v3, v3, v12, s[16:17]
	s_waitcnt lgkmcnt(0)
; __device__ void phase_gather(const P& p, int vb, int nvb, char* smem) {
;     ...
; #pragma unroll
;       for (int k = 2; k <= 128; k <<= 1) {
; #pragma unroll
;         for (int d = k >> 1; d > 0; d >>= 1) {
;           if (d >= 8) {
; #pragma unroll
;             for (int r = 0; r < 8; r++) {
;               const uint32_t o = (uint32_t)__shfl_xor((int)ks[r], d >> 3);
;               const bool up = (((j * 8 + r) & k) == 0), lower = (((j * 8) & d) == 0);
;               const uint32_t mn = ks[r] < o ? ks[r] : o, mx = ks[r] < o ? o : ks[r];
;               ks[r] = (lower == up) ? mn : mx;
;             }
;           } else {
; #pragma unroll
;             for (int r = 0; r < 8; r++) {
;               if ((r & d) == 0) {
;                 const bool up = (((j * 8 + r) & k) == 0);
;                 const uint32_t x0 = ks[r], x1 = ks[r | d];
;                 const uint32_t mn = x0 < x1 ? x0 : x1, mx = x0 < x1 ? x1 : x0;
;                 ks[r] = up ? mn : mx; ks[r | d] = up ? mx : mn;
;               }
;             }
;           }
;         }
;       }
	v_min_u32_e32 v11, v2, v9
	v_max_u32_e32 v2, v2, v9
	v_min_u32_e32 v9, v10, v5
	v_max_u32_e32 v5, v10, v5
	v_cndmask_b32_e64 v10, v5, v9, s[18:19]
	v_cndmask_b32_e64 v5, v9, v5, s[18:19]
	v_min_u32_e32 v9, v7, v4
	v_max_u32_e32 v4, v7, v4
	v_cndmask_b32_e64 v2, v2, v11, s[16:17]
	v_cndmask_b32_e64 v7, v4, v9, s[18:19]
	v_cndmask_b32_e64 v4, v9, v4, s[18:19]
	v_min_u32_e32 v9, v8, v3
	v_max_u32_e32 v3, v8, v3
	v_cndmask_b32_e64 v8, v3, v9, s[18:19]
	v_cndmask_b32_e64 v3, v9, v3, s[18:19]
	v_min_u32_e32 v9, v6, v2
	v_max_u32_e32 v2, v6, v2
	v_cndmask_b32_e64 v6, v2, v9, s[18:19]
	v_cndmask_b32_e64 v2, v9, v2, s[18:19]
	v_min_u32_e32 v9, v10, v8
	v_max_u32_e32 v8, v10, v8
	v_cndmask_b32_e64 v10, v8, v9, s[18:19]
	v_cndmask_b32_e64 v8, v9, v8, s[18:19]
	v_min_u32_e32 v9, v7, v6
	v_max_u32_e32 v6, v7, v6
	v_cndmask_b32_e64 v7, v6, v9, s[18:19]
	v_cndmask_b32_e64 v6, v9, v6, s[18:19]
	v_min_u32_e32 v9, v5, v3
	v_max_u32_e32 v3, v5, v3
	v_cndmask_b32_e64 v5, v3, v9, s[18:19]
	v_cndmask_b32_e64 v3, v9, v3, s[18:19]
	v_min_u32_e32 v9, v4, v2
	v_max_u32_e32 v2, v4, v2
	v_cndmask_b32_e64 v4, v2, v9, s[18:19]
	v_cndmask_b32_e64 v2, v9, v2, s[18:19]
	v_min_u32_e32 v9, v10, v7
	v_max_u32_e32 v7, v10, v7
	v_cndmask_b32_e64 v10, v7, v9, s[18:19]
	v_cndmask_b32_e64 v7, v9, v7, s[18:19]
	v_min_u32_e32 v9, v8, v6
	v_max_u32_e32 v6, v8, v6
	v_cndmask_b32_e64 v8, v6, v9, s[18:19]
	v_cndmask_b32_e64 v6, v9, v6, s[18:19]
	v_min_u32_e32 v9, v5, v4
	v_max_u32_e32 v4, v5, v4
	v_cndmask_b32_e64 v5, v4, v9, s[18:19]
	v_cndmask_b32_e64 v4, v9, v4, s[18:19]
	v_min_u32_e32 v9, v3, v2
	ds_bpermute_b32 v11, v131, v10
	v_max_u32_e32 v2, v3, v2
	v_cndmask_b32_e64 v3, v2, v9, s[18:19]
	v_cndmask_b32_e64 v2, v9, v2, s[18:19]
	ds_bpermute_b32 v9, v131, v7
	s_waitcnt lgkmcnt(1)
	v_min_u32_e32 v12, v10, v11
	v_max_u32_e32 v10, v10, v11
	ds_bpermute_b32 v11, v131, v8
	v_cndmask_b32_e64 v10, v10, v12, s[18:19]
	s_waitcnt lgkmcnt(1)
	v_min_u32_e32 v12, v7, v9
	v_max_u32_e32 v7, v7, v9
	ds_bpermute_b32 v9, v131, v6
	v_cndmask_b32_e64 v7, v7, v12, s[18:19]
	s_waitcnt lgkmcnt(1)
	v_min_u32_e32 v12, v8, v11
	v_max_u32_e32 v8, v8, v11
	ds_bpermute_b32 v11, v131, v5
	v_cndmask_b32_e64 v8, v8, v12, s[18:19]
	s_waitcnt lgkmcnt(1)
	v_min_u32_e32 v12, v6, v9
	v_max_u32_e32 v6, v6, v9
	ds_bpermute_b32 v9, v131, v4
	v_cndmask_b32_e64 v6, v6, v12, s[18:19]
	s_waitcnt lgkmcnt(1)
	v_min_u32_e32 v12, v5, v11
	v_max_u32_e32 v5, v5, v11
	ds_bpermute_b32 v11, v131, v3
	v_cndmask_b32_e64 v5, v5, v12, s[18:19]
	s_waitcnt lgkmcnt(1)
	v_min_u32_e32 v12, v4, v9
	v_max_u32_e32 v4, v4, v9
	ds_bpermute_b32 v9, v131, v2
	v_cndmask_b32_e64 v4, v4, v12, s[18:19]
	s_waitcnt lgkmcnt(1)
	v_min_u32_e32 v12, v3, v11
	v_max_u32_e32 v3, v3, v11
	ds_bpermute_b32 v11, v130, v10
	v_cndmask_b32_e64 v3, v3, v12, s[18:19]
	s_waitcnt lgkmcnt(1)
	v_min_u32_e32 v12, v2, v9
	v_max_u32_e32 v2, v2, v9
	ds_bpermute_b32 v9, v130, v7
	v_cndmask_b32_e64 v2, v2, v12, s[18:19]
	s_waitcnt lgkmcnt(1)
	v_min_u32_e32 v12, v10, v11
	v_max_u32_e32 v10, v10, v11
	ds_bpermute_b32 v11, v130, v8
	v_cndmask_b32_e64 v10, v10, v12, s[0:1]
	s_waitcnt lgkmcnt(1)
	v_min_u32_e32 v12, v7, v9
	v_max_u32_e32 v7, v7, v9
	ds_bpermute_b32 v9, v130, v6
	v_cndmask_b32_e64 v7, v7, v12, s[0:1]
	s_waitcnt lgkmcnt(1)
	v_min_u32_e32 v12, v8, v11
	v_max_u32_e32 v8, v8, v11
	ds_bpermute_b32 v11, v130, v5
	v_cndmask_b32_e64 v8, v8, v12, s[0:1]
	s_waitcnt lgkmcnt(1)
	v_min_u32_e32 v12, v6, v9
	v_max_u32_e32 v6, v6, v9
	ds_bpermute_b32 v9, v130, v4
	v_cndmask_b32_e64 v6, v6, v12, s[0:1]
	s_waitcnt lgkmcnt(1)
	v_min_u32_e32 v12, v5, v11
	v_max_u32_e32 v5, v5, v11
	ds_bpermute_b32 v11, v130, v3
	v_cndmask_b32_e64 v5, v5, v12, s[0:1]
	s_waitcnt lgkmcnt(1)
	v_min_u32_e32 v12, v4, v9
	v_max_u32_e32 v4, v4, v9
	ds_bpermute_b32 v9, v130, v2
	v_cndmask_b32_e64 v4, v4, v12, s[0:1]
	s_waitcnt lgkmcnt(1)
	v_min_u32_e32 v12, v3, v11
	v_max_u32_e32 v3, v3, v11
	ds_bpermute_b32 v11, v129, v10
	v_cndmask_b32_e64 v3, v3, v12, s[0:1]
	s_waitcnt lgkmcnt(1)
	v_min_u32_e32 v12, v2, v9
	v_max_u32_e32 v2, v2, v9
	ds_bpermute_b32 v9, v129, v7
	v_cndmask_b32_e64 v2, v2, v12, s[0:1]
	s_waitcnt lgkmcnt(1)
	v_min_u32_e32 v12, v10, v11
	v_max_u32_e32 v10, v10, v11
	ds_bpermute_b32 v11, v129, v8
	v_cndmask_b32_e64 v10, v10, v12, s[2:3]
	s_waitcnt lgkmcnt(1)
	v_min_u32_e32 v12, v7, v9
	v_max_u32_e32 v7, v7, v9
	ds_bpermute_b32 v9, v129, v6
	v_cndmask_b32_e64 v7, v7, v12, s[2:3]
	s_waitcnt lgkmcnt(1)
	v_min_u32_e32 v12, v8, v11
	v_max_u32_e32 v8, v8, v11
	ds_bpermute_b32 v11, v129, v5
	v_cndmask_b32_e64 v8, v8, v12, s[2:3]
	s_waitcnt lgkmcnt(1)
	v_min_u32_e32 v12, v6, v9
	v_max_u32_e32 v6, v6, v9
	ds_bpermute_b32 v9, v129, v4
	v_cndmask_b32_e64 v6, v6, v12, s[2:3]
	s_waitcnt lgkmcnt(1)
; __device__ void phase_gather(const P& p, int vb, int nvb, char* smem) {
;     ...
; #pragma unroll
;       for (int k = 2; k <= 128; k <<= 1) {
; #pragma unroll
;         for (int d = k >> 1; d > 0; d >>= 1) {
;           if (d >= 8) {
; #pragma unroll
;             for (int r = 0; r < 8; r++) {
;               const uint32_t o = (uint32_t)__shfl_xor((int)ks[r], d >> 3);
;               const bool up = (((j * 8 + r) & k) == 0), lower = (((j * 8) & d) == 0);
;               const uint32_t mn = ks[r] < o ? ks[r] : o, mx = ks[r] < o ? o : ks[r];
;               ks[r] = (lower == up) ? mn : mx;
;             }
;           } else {
; #pragma unroll
;             for (int r = 0; r < 8; r++) {
;               if ((r & d) == 0) {
;                 const bool up = (((j * 8 + r) & k) == 0);
;                 const uint32_t x0 = ks[r], x1 = ks[r | d];
;                 const uint32_t mn = x0 < x1 ? x0 : x1, mx = x0 < x1 ? x1 : x0;
;                 ks[r] = up ? mn : mx; ks[r | d] = up ? mx : mn;
;               }
;             }
;           }
;         }
;       }
;       *(uint4*)(kl + g * 128 + j * 8) = make_uint4(ks[0], ks[1], ks[2], ks[3]);
;       *(uint4*)(kl + g * 128 + j * 8 + 4) = make_uint4(ks[4], ks[5], ks[6], ks[7]);
;     }
;     asm volatile("s_waitcnt lgkmcnt(0)" ::: "memory");
;     const float* sgp = selg + (size_t)rr * 128;
;     const uint32_t* mykl = kl + g * 128;
;     float* mywl = wl + g * 128;
;     float gpre[8];
; #pragma unroll
;     for (int m = 0; m < 8; m++) gpre[m] = sgp[mykl[j + 16 * m] & 127u];
	v_min_u32_e32 v12, v5, v11
	v_max_u32_e32 v5, v5, v11
	ds_bpermute_b32 v11, v129, v3
	v_cndmask_b32_e64 v5, v5, v12, s[2:3]
	s_waitcnt lgkmcnt(1)
	v_min_u32_e32 v12, v4, v9
	v_max_u32_e32 v4, v4, v9
	ds_bpermute_b32 v9, v129, v2
	v_cndmask_b32_e64 v4, v4, v12, s[2:3]
	s_waitcnt lgkmcnt(1)
	v_min_u32_e32 v12, v3, v11
	v_max_u32_e32 v3, v3, v11
	ds_bpermute_b32 v11, v128, v10
	v_cndmask_b32_e64 v3, v3, v12, s[2:3]
	s_waitcnt lgkmcnt(1)
	v_min_u32_e32 v12, v2, v9
	v_max_u32_e32 v2, v2, v9
	ds_bpermute_b32 v9, v128, v7
	v_cndmask_b32_e64 v2, v2, v12, s[2:3]
	s_waitcnt lgkmcnt(1)
	v_min_u32_e32 v12, v10, v11
	v_max_u32_e32 v10, v10, v11
	ds_bpermute_b32 v11, v128, v8
	v_cndmask_b32_e64 v10, v10, v12, s[4:5]
	s_waitcnt lgkmcnt(1)
	v_min_u32_e32 v12, v7, v9
	v_max_u32_e32 v7, v7, v9
	ds_bpermute_b32 v9, v128, v6
	v_cndmask_b32_e64 v7, v7, v12, s[4:5]
	s_waitcnt lgkmcnt(1)
	v_min_u32_e32 v12, v8, v11
	v_max_u32_e32 v8, v8, v11
	ds_bpermute_b32 v11, v128, v5
	v_cndmask_b32_e64 v8, v8, v12, s[4:5]
	s_waitcnt lgkmcnt(1)
	v_min_u32_e32 v12, v6, v9
	v_max_u32_e32 v6, v6, v9
	ds_bpermute_b32 v9, v128, v4
	v_cndmask_b32_e64 v6, v6, v12, s[4:5]
	s_waitcnt lgkmcnt(1)
	v_min_u32_e32 v12, v5, v11
	v_max_u32_e32 v5, v5, v11
	v_cndmask_b32_e64 v5, v5, v12, s[4:5]
	ds_bpermute_b32 v11, v128, v3
	s_waitcnt lgkmcnt(1)
	v_min_u32_e32 v12, v4, v9
	v_max_u32_e32 v4, v4, v9
	ds_bpermute_b32 v9, v128, v2
	v_cndmask_b32_e64 v4, v4, v12, s[4:5]
	s_waitcnt lgkmcnt(1)
	v_min_u32_e32 v12, v3, v11
	v_max_u32_e32 v3, v3, v11
	v_cndmask_b32_e64 v3, v3, v12, s[4:5]
	s_waitcnt lgkmcnt(0)
	v_min_u32_e32 v11, v2, v9
	v_max_u32_e32 v2, v2, v9
	v_cndmask_b32_e64 v2, v2, v11, s[4:5]
	v_min_u32_e32 v9, v10, v5
	v_max_u32_e32 v5, v10, v5
	v_min_u32_e32 v10, v7, v4
	v_max_u32_e32 v4, v7, v4
	v_min_u32_e32 v7, v8, v3
	v_max_u32_e32 v3, v8, v3
	v_min_u32_e32 v8, v6, v2
	v_max_u32_e32 v2, v6, v2
	v_min_u32_e32 v6, v9, v7
	v_max_u32_e32 v7, v9, v7
	v_min_u32_e32 v9, v10, v8
	v_max_u32_e32 v8, v10, v8
	v_min_u32_e32 v10, v5, v3
	v_max_u32_e32 v11, v5, v3
	v_min_u32_e32 v12, v4, v2
	v_max_u32_e32 v96, v4, v2
	v_min_u32_e32 v2, v6, v9
	v_max_u32_e32 v3, v6, v9
	v_min_u32_e32 v4, v7, v8
	v_max_u32_e32 v5, v7, v8
	v_min_u32_e32 v6, v10, v12
	v_max_u32_e32 v7, v10, v12
	v_min_u32_e32 v8, v11, v96
	v_max_u32_e32 v9, v11, v96
	ds_write_b128 v134, v[2:5]
	ds_write_b128 v134, v[6:9] offset:16
	s_waitcnt lgkmcnt(0)
	ds_read2_b32 v[2:3], v144 offset1:16
	ds_read2_b32 v[4:5], v144 offset0:32 offset1:48
	ds_read2_b32 v[8:9], v144 offset0:64 offset1:80
	ds_read2_b32 v[96:97], v144 offset0:96 offset1:112
	s_waitcnt lgkmcnt(3)
	v_and_b32_e32 v2, 0x7f, v2
	v_lshlrev_b32_e32 v12, 2, v2
	v_and_b32_e32 v2, 0x7f, v3
	v_lshl_add_u64 v[6:7], v[0:1], 0, v[12:13]
	v_lshlrev_b32_e32 v12, 2, v2
	s_waitcnt lgkmcnt(2)
	v_and_b32_e32 v4, 0x7f, v4
	v_lshl_add_u64 v[2:3], v[0:1], 0, v[12:13]
	v_lshlrev_b32_e32 v12, 2, v4
	v_and_b32_e32 v4, 0x7f, v5
	v_lshl_add_u64 v[10:11], v[0:1], 0, v[12:13]
	v_lshlrev_b32_e32 v12, 2, v4
	s_waitcnt lgkmcnt(1)
	v_and_b32_e32 v8, 0x7f, v8
	v_lshl_add_u64 v[4:5], v[0:1], 0, v[12:13]
	v_lshlrev_b32_e32 v12, 2, v8
	v_and_b32_e32 v8, 0x7f, v9
	v_lshl_add_u64 v[104:105], v[0:1], 0, v[12:13]
	v_lshlrev_b32_e32 v12, 2, v8
	v_lshl_add_u64 v[8:9], v[0:1], 0, v[12:13]
	s_waitcnt lgkmcnt(0)
	v_and_b32_e32 v12, 0x7f, v96
	v_lshlrev_b32_e32 v12, 2, v12
	v_lshl_add_u64 v[106:107], v[0:1], 0, v[12:13]
	v_and_b32_e32 v12, 0x7f, v97
	v_lshlrev_b32_e32 v12, 2, v12
	v_lshl_add_u64 v[0:1], v[0:1], 0, v[12:13]
	global_load_dword v103, v[6:7], off
	global_load_dword v102, v[2:3], off
	global_load_dword v101, v[10:11], off
	global_load_dword v100, v[4:5], off
	global_load_dword v99, v[104:105], off
	global_load_dword v98, v[8:9], off
	global_load_dword v97, v[106:107], off
	global_load_dword v96, v[0:1], off
	v_lshlrev_b32_e32 v250, 1, v132
	v_mov_b32_e32 v104, 0
	v_mov_b32_e32 v105, 0
	v_mov_b32_e32 v106, 0
	v_mov_b32_e32 v107, 0
	ds_read_b128 v[0:3], v133
	ds_read_b128 v[4:7], v133 offset:16
	ds_write_b128 v134, v[104:107] offset:2048
	ds_write_b128 v134, v[104:107] offset:2064
	s_lshl_b32 s27, s83, 22
	v_add_u32_e32 v230, s27, v250
	v_add_u32_e32 v231, v133, v142
	v_add_u32_e32 v251, v133, v142
	v_add_u32_e32 v254, 64, v133
	s_mov_b32 s26, 0
	s_mov_b32 s27, s83
	s_cmp_eq_u32 s27, 0
	s_cbranch_scc1 .Lgu_p_0
	s_cmp_eq_u32 s27, 1
	s_cbranch_scc1 .Lgu_p_1
	s_cmp_eq_u32 s27, 2
	s_cbranch_scc1 .Lgu_p_2
	v_mov_b32_e32 v214, v80
	v_mov_b32_e32 v215, v81
	v_mov_b32_e32 v216, v82
	v_mov_b32_e32 v217, v83
	v_mov_b32_e32 v218, v84
	v_mov_b32_e32 v219, v85
	v_mov_b32_e32 v220, v86
	v_mov_b32_e32 v221, v87
	v_mov_b32_e32 v222, v88
	v_mov_b32_e32 v223, v89
	v_mov_b32_e32 v224, v90
	v_mov_b32_e32 v225, v91
	v_mov_b32_e32 v226, v92
	v_mov_b32_e32 v227, v93
	v_mov_b32_e32 v228, v94
	v_mov_b32_e32 v229, v95
	s_branch .Lgu_p_x

; __device__ void phase_gather(const P& p, int vb, int nvb, char* smem) {
;     ...
;     for (int b0 = 0; b0 < 128; b0 += 8) {
;       float dp[8];
; #pragma unroll
;       for (int u = 0; u < 8; u++) {
;         const uint32_t key = mykl[b0 + u];
;         const int e = (int)(key >> 7);
;         const uint4* up = (const uint4*)(U + (size_t)e * 1024 + 16 * j);
;         uint4 uu[4];
; #pragma unroll
;         for (int i = 0; i < 4; i++) uu[i] = up[i * 16];
.Lgu_p_x:
	s_waitcnt lgkmcnt(0)
	v_and_or_b32 v8, v0, s66, v230
	global_load_dwordx4 v[150:153], v8, s[98:99]
	v_and_or_b32 v9, v1, s66, v230
	global_load_dwordx4 v[154:157], v9, s[98:99]
	v_and_or_b32 v8, v2, s66, v230
	global_load_dwordx4 v[158:161], v8, s[98:99]
	v_and_or_b32 v9, v3, s66, v230
	global_load_dwordx4 v[162:165], v9, s[98:99]
	v_and_or_b32 v8, v4, s66, v230
	global_load_dwordx4 v[166:169], v8, s[98:99]
	v_and_or_b32 v9, v5, s66, v230
	global_load_dwordx4 v[170:173], v9, s[98:99]
	v_and_or_b32 v8, v6, s66, v230
	global_load_dwordx4 v[174:177], v8, s[98:99]
	v_and_or_b32 v9, v7, s66, v230
	global_load_dwordx4 v[178:181], v9, s[98:99]
	ds_read_b128 v[0:3], v133 offset:32
	ds_read_b128 v[4:7], v133 offset:48
	s_waitcnt lgkmcnt(0)
	v_and_or_b32 v8, v0, s66, v230
	global_load_dwordx4 v[182:185], v8, s[98:99]
	v_and_or_b32 v9, v1, s66, v230
	global_load_dwordx4 v[186:189], v9, s[98:99]
	v_and_or_b32 v8, v2, s66, v230
	global_load_dwordx4 v[190:193], v8, s[98:99]
	v_and_or_b32 v9, v3, s66, v230
	global_load_dwordx4 v[194:197], v9, s[98:99]
	v_and_or_b32 v8, v4, s66, v230
	global_load_dwordx4 v[198:201], v8, s[98:99]
	v_and_or_b32 v9, v5, s66, v230
	global_load_dwordx4 v[202:205], v9, s[98:99]
	v_and_or_b32 v8, v6, s66, v230
	global_load_dwordx4 v[206:209], v8, s[98:99]
	v_and_or_b32 v9, v7, s66, v230
	global_load_dwordx4 v[210:213], v9, s[98:99]
	ds_read_b128 v[0:3], v133 offset:64
	s_branch .Lgu_body

; __device__ void phase_gather(const P& p, int vb, int nvb, char* smem) {
;     ...
; #pragma unroll 1
;     for (int b0 = 0; b0 < 128; b0 += 8) {
;       float dp[8];
; #pragma unroll
;       for (int u = 0; u < 8; u++) {
;         const uint32_t key = mykl[b0 + u];
;         const int e = (int)(key >> 7);
;         const uint4* up = (const uint4*)(U + (size_t)e * 1024 + 16 * j);
;         uint4 uu[4];
; #pragma unroll
;         for (int i = 0; i < 4; i++) uu[i] = up[i * 16];
;         f32x2 d2 = f32x2{0.f, 0.f};
; #pragma unroll
;         for (int i = 0; i < 4; i++) {
;           const uint32_t w[4] = {uu[i].x, uu[i].y, uu[i].z, uu[i].w};
; #pragma unroll
;           for (int q = 0; q < 4; q++) {
;             d2 += __builtin_amdgcn_cvt_pk_f32_fp8((int)w[q], false) * xf[i * 8 + q * 2 + 0];
;             d2 += __builtin_amdgcn_cvt_pk_f32_fp8((int)w[q], true) * xf[i * 8 + q * 2 + 1];
;           }
;         }
;         dp[u] = d2.x + d2.y;
;       }
.Lgu_s_x:
.Lgu_body:
	s_cmp_eq_u32 s26, 31
	s_cbranch_scc1 .Lgu_last
	s_waitcnt lgkmcnt(0)
	s_waitcnt vmcnt(15)
	v_cvt_pk_f32_fp8_e32 v[104:105], v150
	v_cvt_pk_f32_fp8_sdwa v[106:107], v150 src0_sel:WORD_1
	v_pk_mul_f32 v[112:113], v[104:105], v[214:215]
	v_cvt_pk_f32_fp8_e32 v[108:109], v151
	v_pk_fma_f32 v[112:113], v[106:107], v[216:217], v[112:113]
	v_cvt_pk_f32_fp8_sdwa v[110:111], v151 src0_sel:WORD_1
	v_pk_fma_f32 v[112:113], v[108:109], v[218:219], v[112:113]
	v_cvt_pk_f32_fp8_e32 v[104:105], v152
	v_pk_fma_f32 v[112:113], v[110:111], v[220:221], v[112:113]
	v_cvt_pk_f32_fp8_sdwa v[106:107], v152 src0_sel:WORD_1
	v_pk_fma_f32 v[112:113], v[104:105], v[222:223], v[112:113]
	v_cvt_pk_f32_fp8_e32 v[108:109], v153
	v_pk_fma_f32 v[112:113], v[106:107], v[224:225], v[112:113]
	v_cvt_pk_f32_fp8_sdwa v[110:111], v153 src0_sel:WORD_1
	v_pk_fma_f32 v[112:113], v[108:109], v[226:227], v[112:113]
	v_and_or_b32 v8, v0, s66, v230
	v_pk_fma_f32 v[112:113], v[110:111], v[228:229], v[112:113]
	global_load_dwordx4 v[150:153], v8, s[98:99]
	v_add_f32_e32 v116, v112, v113
	s_waitcnt vmcnt(15)
	v_cvt_pk_f32_fp8_e32 v[104:105], v154
	v_cvt_pk_f32_fp8_sdwa v[106:107], v154 src0_sel:WORD_1
	v_pk_mul_f32 v[112:113], v[104:105], v[214:215]
	v_cvt_pk_f32_fp8_e32 v[108:109], v155
	v_pk_fma_f32 v[112:113], v[106:107], v[216:217], v[112:113]
	v_cvt_pk_f32_fp8_sdwa v[110:111], v155 src0_sel:WORD_1
	v_pk_fma_f32 v[112:113], v[108:109], v[218:219], v[112:113]
	v_cvt_pk_f32_fp8_e32 v[104:105], v156
	v_pk_fma_f32 v[112:113], v[110:111], v[220:221], v[112:113]
	v_cvt_pk_f32_fp8_sdwa v[106:107], v156 src0_sel:WORD_1
	v_pk_fma_f32 v[112:113], v[104:105], v[222:223], v[112:113]
	v_cvt_pk_f32_fp8_e32 v[108:109], v157
	v_pk_fma_f32 v[112:113], v[106:107], v[224:225], v[112:113]
	v_cvt_pk_f32_fp8_sdwa v[110:111], v157 src0_sel:WORD_1
	v_pk_fma_f32 v[112:113], v[108:109], v[226:227], v[112:113]
	v_and_or_b32 v9, v1, s66, v230
	v_pk_fma_f32 v[112:113], v[110:111], v[228:229], v[112:113]
	global_load_dwordx4 v[154:157], v9, s[98:99]
	v_add_f32_e32 v117, v112, v113
	ds_read_b128 v[4:7], v254 offset:16
	s_waitcnt vmcnt(15)
	v_cvt_pk_f32_fp8_e32 v[104:105], v158
	v_cvt_pk_f32_fp8_sdwa v[106:107], v158 src0_sel:WORD_1
	v_pk_mul_f32 v[112:113], v[104:105], v[214:215]
	v_cvt_pk_f32_fp8_e32 v[108:109], v159
	v_pk_fma_f32 v[112:113], v[106:107], v[216:217], v[112:113]
	v_cvt_pk_f32_fp8_sdwa v[110:111], v159 src0_sel:WORD_1
	v_pk_fma_f32 v[112:113], v[108:109], v[218:219], v[112:113]
	v_cvt_pk_f32_fp8_e32 v[104:105], v160
	v_pk_fma_f32 v[112:113], v[110:111], v[220:221], v[112:113]
	v_cvt_pk_f32_fp8_sdwa v[106:107], v160 src0_sel:WORD_1
	v_pk_fma_f32 v[112:113], v[104:105], v[222:223], v[112:113]
	v_cvt_pk_f32_fp8_e32 v[108:109], v161
	v_pk_fma_f32 v[112:113], v[106:107], v[224:225], v[112:113]
	v_cvt_pk_f32_fp8_sdwa v[110:111], v161 src0_sel:WORD_1
	v_pk_fma_f32 v[112:113], v[108:109], v[226:227], v[112:113]
	v_and_or_b32 v8, v2, s66, v230
	v_pk_fma_f32 v[112:113], v[110:111], v[228:229], v[112:113]
	global_load_dwordx4 v[158:161], v8, s[98:99]
	v_add_f32_e32 v118, v112, v113
	s_waitcnt vmcnt(15)
	v_cvt_pk_f32_fp8_e32 v[104:105], v162
	v_cvt_pk_f32_fp8_sdwa v[106:107], v162 src0_sel:WORD_1
	v_pk_mul_f32 v[112:113], v[104:105], v[214:215]
	v_cvt_pk_f32_fp8_e32 v[108:109], v163
	v_pk_fma_f32 v[112:113], v[106:107], v[216:217], v[112:113]
	v_cvt_pk_f32_fp8_sdwa v[110:111], v163 src0_sel:WORD_1
	v_pk_fma_f32 v[112:113], v[108:109], v[218:219], v[112:113]
	v_cvt_pk_f32_fp8_e32 v[104:105], v164
	v_pk_fma_f32 v[112:113], v[110:111], v[220:221], v[112:113]
	v_cvt_pk_f32_fp8_sdwa v[106:107], v164 src0_sel:WORD_1
	v_pk_fma_f32 v[112:113], v[104:105], v[222:223], v[112:113]
	v_cvt_pk_f32_fp8_e32 v[108:109], v165
	v_pk_fma_f32 v[112:113], v[106:107], v[224:225], v[112:113]
	v_cvt_pk_f32_fp8_sdwa v[110:111], v165 src0_sel:WORD_1
	v_pk_fma_f32 v[112:113], v[108:109], v[226:227], v[112:113]
	v_and_or_b32 v9, v3, s66, v230
	v_pk_fma_f32 v[112:113], v[110:111], v[228:229], v[112:113]
	global_load_dwordx4 v[162:165], v9, s[98:99]
	v_add_f32_e32 v119, v112, v113
	s_waitcnt lgkmcnt(0)
	s_waitcnt vmcnt(15)
	v_cvt_pk_f32_fp8_e32 v[104:105], v166
	v_cvt_pk_f32_fp8_sdwa v[106:107], v166 src0_sel:WORD_1
	v_pk_mul_f32 v[112:113], v[104:105], v[214:215]
	v_cvt_pk_f32_fp8_e32 v[108:109], v167
	v_pk_fma_f32 v[112:113], v[106:107], v[216:217], v[112:113]
	v_cvt_pk_f32_fp8_sdwa v[110:111], v167 src0_sel:WORD_1
	v_pk_fma_f32 v[112:113], v[108:109], v[218:219], v[112:113]
	v_cvt_pk_f32_fp8_e32 v[104:105], v168
	v_pk_fma_f32 v[112:113], v[110:111], v[220:221], v[112:113]
	v_cvt_pk_f32_fp8_sdwa v[106:107], v168 src0_sel:WORD_1
	v_pk_fma_f32 v[112:113], v[104:105], v[222:223], v[112:113]
	v_cvt_pk_f32_fp8_e32 v[108:109], v169
	v_pk_fma_f32 v[112:113], v[106:107], v[224:225], v[112:113]
	v_cvt_pk_f32_fp8_sdwa v[110:111], v169 src0_sel:WORD_1
	v_pk_fma_f32 v[112:113], v[108:109], v[226:227], v[112:113]
	v_and_or_b32 v8, v4, s66, v230
	v_pk_fma_f32 v[112:113], v[110:111], v[228:229], v[112:113]
	global_load_dwordx4 v[166:169], v8, s[98:99]
	v_add_f32_e32 v120, v112, v113
	s_waitcnt vmcnt(15)
	v_cvt_pk_f32_fp8_e32 v[104:105], v170
	v_cvt_pk_f32_fp8_sdwa v[106:107], v170 src0_sel:WORD_1
	v_pk_mul_f32 v[112:113], v[104:105], v[214:215]
	v_cvt_pk_f32_fp8_e32 v[108:109], v171
	v_pk_fma_f32 v[112:113], v[106:107], v[216:217], v[112:113]
	v_cvt_pk_f32_fp8_sdwa v[110:111], v171 src0_sel:WORD_1
	v_pk_fma_f32 v[112:113], v[108:109], v[218:219], v[112:113]
	v_cvt_pk_f32_fp8_e32 v[104:105], v172
	v_pk_fma_f32 v[112:113], v[110:111], v[220:221], v[112:113]
	v_cvt_pk_f32_fp8_sdwa v[106:107], v172 src0_sel:WORD_1
	v_pk_fma_f32 v[112:113], v[104:105], v[222:223], v[112:113]
	v_cvt_pk_f32_fp8_e32 v[108:109], v173
	v_pk_fma_f32 v[112:113], v[106:107], v[224:225], v[112:113]
	v_cvt_pk_f32_fp8_sdwa v[110:111], v173 src0_sel:WORD_1
	v_pk_fma_f32 v[112:113], v[108:109], v[226:227], v[112:113]
	v_and_or_b32 v9, v5, s66, v230
	v_pk_fma_f32 v[112:113], v[110:111], v[228:229], v[112:113]
	global_load_dwordx4 v[170:173], v9, s[98:99]
	v_add_f32_e32 v121, v112, v113
	ds_read_b128 v[0:3], v254 offset:32
	s_waitcnt vmcnt(15)
; __device__ void phase_gather(const P& p, int vb, int nvb, char* smem) {
;     ...
; #pragma unroll 1
;     for (int b0 = 0; b0 < 128; b0 += 8) {
;       float dp[8];
; #pragma unroll
;       for (int u = 0; u < 8; u++) {
;         const uint32_t key = mykl[b0 + u];
;         const int e = (int)(key >> 7);
;         const uint4* up = (const uint4*)(U + (size_t)e * 1024 + 16 * j);
;         uint4 uu[4];
; #pragma unroll
;         for (int i = 0; i < 4; i++) uu[i] = up[i * 16];
;         f32x2 d2 = f32x2{0.f, 0.f};
; #pragma unroll
;         for (int i = 0; i < 4; i++) {
;           const uint32_t w[4] = {uu[i].x, uu[i].y, uu[i].z, uu[i].w};
; #pragma unroll
;           for (int q = 0; q < 4; q++) {
;             d2 += __builtin_amdgcn_cvt_pk_f32_fp8((int)w[q], false) * xf[i * 8 + q * 2 + 0];
;             d2 += __builtin_amdgcn_cvt_pk_f32_fp8((int)w[q], true) * xf[i * 8 + q * 2 + 1];
;           }
;         }
;         dp[u] = d2.x + d2.y;
;       }
;       const bool h8 = (j & 8) != 0, h4 = (j & 4) != 0, h2b = (j & 2) != 0;
;       float q4[4], q2[2];
; #pragma unroll
;       for (int k = 0; k < 4; k++) { const float snd = h8 ? dp[k] : dp[k + 4], kp = h8 ? dp[k + 4] : dp[k]; q4[k] = kp + __shfl_xor(snd, 8); }
; #pragma unroll
;       for (int k = 0; k < 2; k++) { const float snd = h4 ? q4[k] : q4[k + 2], kp = h4 ? q4[k + 2] : q4[k]; q2[k] = kp + __shfl_xor(snd, 4); }
;       const float snd1 = h2b ? q2[0] : q2[1], kp1 = h2b ? q2[1] : q2[0];
;       float q1 = kp1 + __shfl_xor(snd1, 2);
;       q1 += __shfl_xor(q1, 1);
;       if ((j & 1) == 0) mywl[b0 + (j >> 1)] = q1;
	v_cvt_pk_f32_fp8_e32 v[104:105], v174
	v_cvt_pk_f32_fp8_sdwa v[106:107], v174 src0_sel:WORD_1
	v_pk_mul_f32 v[112:113], v[104:105], v[214:215]
	v_cvt_pk_f32_fp8_e32 v[108:109], v175
	v_pk_fma_f32 v[112:113], v[106:107], v[216:217], v[112:113]
	v_cvt_pk_f32_fp8_sdwa v[110:111], v175 src0_sel:WORD_1
	v_pk_fma_f32 v[112:113], v[108:109], v[218:219], v[112:113]
	v_cvt_pk_f32_fp8_e32 v[104:105], v176
	v_pk_fma_f32 v[112:113], v[110:111], v[220:221], v[112:113]
	v_cvt_pk_f32_fp8_sdwa v[106:107], v176 src0_sel:WORD_1
	v_pk_fma_f32 v[112:113], v[104:105], v[222:223], v[112:113]
	v_cvt_pk_f32_fp8_e32 v[108:109], v177
	v_pk_fma_f32 v[112:113], v[106:107], v[224:225], v[112:113]
	v_cvt_pk_f32_fp8_sdwa v[110:111], v177 src0_sel:WORD_1
	v_pk_fma_f32 v[112:113], v[108:109], v[226:227], v[112:113]
	v_and_or_b32 v8, v6, s66, v230
	v_pk_fma_f32 v[112:113], v[110:111], v[228:229], v[112:113]
	global_load_dwordx4 v[174:177], v8, s[98:99]
	v_add_f32_e32 v122, v112, v113
	s_waitcnt vmcnt(15)
	v_cvt_pk_f32_fp8_e32 v[104:105], v178
	v_cvt_pk_f32_fp8_sdwa v[106:107], v178 src0_sel:WORD_1
	v_pk_mul_f32 v[112:113], v[104:105], v[214:215]
	v_cvt_pk_f32_fp8_e32 v[108:109], v179
	v_pk_fma_f32 v[112:113], v[106:107], v[216:217], v[112:113]
	v_cvt_pk_f32_fp8_sdwa v[110:111], v179 src0_sel:WORD_1
	v_pk_fma_f32 v[112:113], v[108:109], v[218:219], v[112:113]
	v_cvt_pk_f32_fp8_e32 v[104:105], v180
	v_pk_fma_f32 v[112:113], v[110:111], v[220:221], v[112:113]
	v_cvt_pk_f32_fp8_sdwa v[106:107], v180 src0_sel:WORD_1
	v_pk_fma_f32 v[112:113], v[104:105], v[222:223], v[112:113]
	v_cvt_pk_f32_fp8_e32 v[108:109], v181
	v_pk_fma_f32 v[112:113], v[106:107], v[224:225], v[112:113]
	v_cvt_pk_f32_fp8_sdwa v[110:111], v181 src0_sel:WORD_1
	v_pk_fma_f32 v[112:113], v[108:109], v[226:227], v[112:113]
	v_and_or_b32 v9, v7, s66, v230
	v_pk_fma_f32 v[112:113], v[110:111], v[228:229], v[112:113]
	global_load_dwordx4 v[178:181], v9, s[98:99]
	v_add_f32_e32 v123, v112, v113
	v_add_f32_dpp v10, v116, v116 row_ror:8 row_mask:0xf bank_mask:0x3
	v_add_f32_dpp v11, v117, v117 row_ror:8 row_mask:0xf bank_mask:0x3
	v_add_f32_dpp v12, v118, v118 row_ror:8 row_mask:0xf bank_mask:0x3
	v_add_f32_dpp v124, v119, v119 row_ror:8 row_mask:0xf bank_mask:0x3
	v_add_f32_dpp v10, v120, v120 row_ror:8 row_mask:0xf bank_mask:0xc
	v_add_f32_dpp v11, v121, v121 row_ror:8 row_mask:0xf bank_mask:0xc
	v_add_f32_dpp v12, v122, v122 row_ror:8 row_mask:0xf bank_mask:0xc
	v_add_f32_dpp v124, v123, v123 row_ror:8 row_mask:0xf bank_mask:0xc
	s_nop 0
	v_add_f32_dpp v125, v10, v10 row_shl:4 row_mask:0xf bank_mask:0x5
	v_add_f32_dpp v246, v11, v11 row_shl:4 row_mask:0xf bank_mask:0x5
	v_add_f32_dpp v125, v12, v12 row_shr:4 row_mask:0xf bank_mask:0xa
	v_add_f32_dpp v246, v124, v124 row_shr:4 row_mask:0xf bank_mask:0xa
	s_nop 1
	v_add_f32_dpp v247, v125, v125 quad_perm:[2,3,0,1] row_mask:0xf bank_mask:0xf
	v_add_f32_dpp v249, v246, v246 quad_perm:[2,3,0,1] row_mask:0xf bank_mask:0xf
	s_nop 0
	v_cndmask_b32_e64 v252, v249, v247, s[2:3]
	s_nop 1
	v_add_f32_dpp v253, v252, v252 quad_perm:[1,0,3,2] row_mask:0xf bank_mask:0xf
	s_and_saveexec_b64 s[20:21], s[4:5]
	ds_add_f32 v251, v253 offset:2048
	s_mov_b64 exec, s[20:21]
	s_waitcnt lgkmcnt(0)
	s_waitcnt vmcnt(15)
	v_cvt_pk_f32_fp8_e32 v[104:105], v182
	v_cvt_pk_f32_fp8_sdwa v[106:107], v182 src0_sel:WORD_1
	v_pk_mul_f32 v[112:113], v[104:105], v[214:215]
	v_cvt_pk_f32_fp8_e32 v[108:109], v183
	v_pk_fma_f32 v[112:113], v[106:107], v[216:217], v[112:113]
	v_cvt_pk_f32_fp8_sdwa v[110:111], v183 src0_sel:WORD_1
	v_pk_fma_f32 v[112:113], v[108:109], v[218:219], v[112:113]
	v_cvt_pk_f32_fp8_e32 v[104:105], v184
	v_pk_fma_f32 v[112:113], v[110:111], v[220:221], v[112:113]
	v_cvt_pk_f32_fp8_sdwa v[106:107], v184 src0_sel:WORD_1
	v_pk_fma_f32 v[112:113], v[104:105], v[222:223], v[112:113]
	v_cvt_pk_f32_fp8_e32 v[108:109], v185
	v_pk_fma_f32 v[112:113], v[106:107], v[224:225], v[112:113]
	v_cvt_pk_f32_fp8_sdwa v[110:111], v185 src0_sel:WORD_1
	v_pk_fma_f32 v[112:113], v[108:109], v[226:227], v[112:113]
	v_and_or_b32 v8, v0, s66, v230
	v_pk_fma_f32 v[112:113], v[110:111], v[228:229], v[112:113]
	global_load_dwordx4 v[182:185], v8, s[98:99]
	v_add_f32_e32 v116, v112, v113
	s_waitcnt vmcnt(15)
	v_cvt_pk_f32_fp8_e32 v[104:105], v186
	v_cvt_pk_f32_fp8_sdwa v[106:107], v186 src0_sel:WORD_1
	v_pk_mul_f32 v[112:113], v[104:105], v[214:215]
	v_cvt_pk_f32_fp8_e32 v[108:109], v187
	v_pk_fma_f32 v[112:113], v[106:107], v[216:217], v[112:113]
	v_cvt_pk_f32_fp8_sdwa v[110:111], v187 src0_sel:WORD_1
	v_pk_fma_f32 v[112:113], v[108:109], v[218:219], v[112:113]
	v_cvt_pk_f32_fp8_e32 v[104:105], v188
	v_pk_fma_f32 v[112:113], v[110:111], v[220:221], v[112:113]
	v_cvt_pk_f32_fp8_sdwa v[106:107], v188 src0_sel:WORD_1
	v_pk_fma_f32 v[112:113], v[104:105], v[222:223], v[112:113]
	v_cvt_pk_f32_fp8_e32 v[108:109], v189
	v_pk_fma_f32 v[112:113], v[106:107], v[224:225], v[112:113]
	v_cvt_pk_f32_fp8_sdwa v[110:111], v189 src0_sel:WORD_1
	v_pk_fma_f32 v[112:113], v[108:109], v[226:227], v[112:113]
	v_and_or_b32 v9, v1, s66, v230
	v_pk_fma_f32 v[112:113], v[110:111], v[228:229], v[112:113]
	global_load_dwordx4 v[186:189], v9, s[98:99]
	v_add_f32_e32 v117, v112, v113
	ds_read_b128 v[4:7], v254 offset:48
	s_waitcnt vmcnt(15)
; __device__ void phase_gather(const P& p, int vb, int nvb, char* smem) {
;     ...
; #pragma unroll 1
;     for (int b0 = 0; b0 < 128; b0 += 8) {
;       float dp[8];
; #pragma unroll
;       for (int u = 0; u < 8; u++) {
;         const uint32_t key = mykl[b0 + u];
;         const int e = (int)(key >> 7);
;         const uint4* up = (const uint4*)(U + (size_t)e * 1024 + 16 * j);
;         uint4 uu[4];
; #pragma unroll
;         for (int i = 0; i < 4; i++) uu[i] = up[i * 16];
;         f32x2 d2 = f32x2{0.f, 0.f};
; #pragma unroll
;         for (int i = 0; i < 4; i++) {
;           const uint32_t w[4] = {uu[i].x, uu[i].y, uu[i].z, uu[i].w};
; #pragma unroll
;           for (int q = 0; q < 4; q++) {
;             d2 += __builtin_amdgcn_cvt_pk_f32_fp8((int)w[q], false) * xf[i * 8 + q * 2 + 0];
;             d2 += __builtin_amdgcn_cvt_pk_f32_fp8((int)w[q], true) * xf[i * 8 + q * 2 + 1];
;           }
;         }
;         dp[u] = d2.x + d2.y;
;       }
	v_cvt_pk_f32_fp8_e32 v[104:105], v190
	v_cvt_pk_f32_fp8_sdwa v[106:107], v190 src0_sel:WORD_1
	v_pk_mul_f32 v[112:113], v[104:105], v[214:215]
	v_cvt_pk_f32_fp8_e32 v[108:109], v191
	v_pk_fma_f32 v[112:113], v[106:107], v[216:217], v[112:113]
	v_cvt_pk_f32_fp8_sdwa v[110:111], v191 src0_sel:WORD_1
	v_pk_fma_f32 v[112:113], v[108:109], v[218:219], v[112:113]
	v_cvt_pk_f32_fp8_e32 v[104:105], v192
	v_pk_fma_f32 v[112:113], v[110:111], v[220:221], v[112:113]
	v_cvt_pk_f32_fp8_sdwa v[106:107], v192 src0_sel:WORD_1
	v_pk_fma_f32 v[112:113], v[104:105], v[222:223], v[112:113]
	v_cvt_pk_f32_fp8_e32 v[108:109], v193
	v_pk_fma_f32 v[112:113], v[106:107], v[224:225], v[112:113]
	v_cvt_pk_f32_fp8_sdwa v[110:111], v193 src0_sel:WORD_1
	v_pk_fma_f32 v[112:113], v[108:109], v[226:227], v[112:113]
	v_and_or_b32 v8, v2, s66, v230
	v_pk_fma_f32 v[112:113], v[110:111], v[228:229], v[112:113]
	global_load_dwordx4 v[190:193], v8, s[98:99]
	v_add_f32_e32 v118, v112, v113
	s_waitcnt vmcnt(15)
	v_cvt_pk_f32_fp8_e32 v[104:105], v194
	v_cvt_pk_f32_fp8_sdwa v[106:107], v194 src0_sel:WORD_1
	v_pk_mul_f32 v[112:113], v[104:105], v[214:215]
	v_cvt_pk_f32_fp8_e32 v[108:109], v195
	v_pk_fma_f32 v[112:113], v[106:107], v[216:217], v[112:113]
	v_cvt_pk_f32_fp8_sdwa v[110:111], v195 src0_sel:WORD_1
	v_pk_fma_f32 v[112:113], v[108:109], v[218:219], v[112:113]
	v_cvt_pk_f32_fp8_e32 v[104:105], v196
	v_pk_fma_f32 v[112:113], v[110:111], v[220:221], v[112:113]
	v_cvt_pk_f32_fp8_sdwa v[106:107], v196 src0_sel:WORD_1
	v_pk_fma_f32 v[112:113], v[104:105], v[222:223], v[112:113]
	v_cvt_pk_f32_fp8_e32 v[108:109], v197
	v_pk_fma_f32 v[112:113], v[106:107], v[224:225], v[112:113]
	v_cvt_pk_f32_fp8_sdwa v[110:111], v197 src0_sel:WORD_1
	v_pk_fma_f32 v[112:113], v[108:109], v[226:227], v[112:113]
	v_and_or_b32 v9, v3, s66, v230
	v_pk_fma_f32 v[112:113], v[110:111], v[228:229], v[112:113]
	global_load_dwordx4 v[194:197], v9, s[98:99]
	v_add_f32_e32 v119, v112, v113
	s_waitcnt lgkmcnt(0)
	s_waitcnt vmcnt(15)
	v_cvt_pk_f32_fp8_e32 v[104:105], v198
	v_cvt_pk_f32_fp8_sdwa v[106:107], v198 src0_sel:WORD_1
	v_pk_mul_f32 v[112:113], v[104:105], v[214:215]
	v_cvt_pk_f32_fp8_e32 v[108:109], v199
	v_pk_fma_f32 v[112:113], v[106:107], v[216:217], v[112:113]
	v_cvt_pk_f32_fp8_sdwa v[110:111], v199 src0_sel:WORD_1
	v_pk_fma_f32 v[112:113], v[108:109], v[218:219], v[112:113]
	v_cvt_pk_f32_fp8_e32 v[104:105], v200
	v_pk_fma_f32 v[112:113], v[110:111], v[220:221], v[112:113]
	v_cvt_pk_f32_fp8_sdwa v[106:107], v200 src0_sel:WORD_1
	v_pk_fma_f32 v[112:113], v[104:105], v[222:223], v[112:113]
	v_cvt_pk_f32_fp8_e32 v[108:109], v201
	v_pk_fma_f32 v[112:113], v[106:107], v[224:225], v[112:113]
	v_cvt_pk_f32_fp8_sdwa v[110:111], v201 src0_sel:WORD_1
	v_pk_fma_f32 v[112:113], v[108:109], v[226:227], v[112:113]
	v_and_or_b32 v8, v4, s66, v230
	v_pk_fma_f32 v[112:113], v[110:111], v[228:229], v[112:113]
	global_load_dwordx4 v[198:201], v8, s[98:99]
	v_add_f32_e32 v120, v112, v113
	s_add_i32 s27, s26, 2
	s_and_b32 s27, s27, 7
	s_lshl_b32 s27, s27, 6
	v_add_u32_e32 v254, s27, v133
	s_waitcnt vmcnt(15)
	v_cvt_pk_f32_fp8_e32 v[104:105], v202
	v_cvt_pk_f32_fp8_sdwa v[106:107], v202 src0_sel:WORD_1
	v_pk_mul_f32 v[112:113], v[104:105], v[214:215]
	v_cvt_pk_f32_fp8_e32 v[108:109], v203
	v_pk_fma_f32 v[112:113], v[106:107], v[216:217], v[112:113]
	v_cvt_pk_f32_fp8_sdwa v[110:111], v203 src0_sel:WORD_1
	v_pk_fma_f32 v[112:113], v[108:109], v[218:219], v[112:113]
	v_cvt_pk_f32_fp8_e32 v[104:105], v204
	v_pk_fma_f32 v[112:113], v[110:111], v[220:221], v[112:113]
	v_cvt_pk_f32_fp8_sdwa v[106:107], v204 src0_sel:WORD_1
	v_pk_fma_f32 v[112:113], v[104:105], v[222:223], v[112:113]
	v_cvt_pk_f32_fp8_e32 v[108:109], v205
	v_pk_fma_f32 v[112:113], v[106:107], v[224:225], v[112:113]
	v_cvt_pk_f32_fp8_sdwa v[110:111], v205 src0_sel:WORD_1
	v_pk_fma_f32 v[112:113], v[108:109], v[226:227], v[112:113]
	v_and_or_b32 v9, v5, s66, v230
	v_pk_fma_f32 v[112:113], v[110:111], v[228:229], v[112:113]
	global_load_dwordx4 v[202:205], v9, s[98:99]
	v_add_f32_e32 v121, v112, v113
	ds_read_b128 v[0:3], v254
	s_waitcnt vmcnt(15)
	v_cvt_pk_f32_fp8_e32 v[104:105], v206
	v_cvt_pk_f32_fp8_sdwa v[106:107], v206 src0_sel:WORD_1
	v_pk_mul_f32 v[112:113], v[104:105], v[214:215]
	v_cvt_pk_f32_fp8_e32 v[108:109], v207
	v_pk_fma_f32 v[112:113], v[106:107], v[216:217], v[112:113]
	v_cvt_pk_f32_fp8_sdwa v[110:111], v207 src0_sel:WORD_1
	v_pk_fma_f32 v[112:113], v[108:109], v[218:219], v[112:113]
	v_cvt_pk_f32_fp8_e32 v[104:105], v208
	v_pk_fma_f32 v[112:113], v[110:111], v[220:221], v[112:113]
	v_cvt_pk_f32_fp8_sdwa v[106:107], v208 src0_sel:WORD_1
	v_pk_fma_f32 v[112:113], v[104:105], v[222:223], v[112:113]
	v_cvt_pk_f32_fp8_e32 v[108:109], v209
	v_pk_fma_f32 v[112:113], v[106:107], v[224:225], v[112:113]
	v_cvt_pk_f32_fp8_sdwa v[110:111], v209 src0_sel:WORD_1
	v_pk_fma_f32 v[112:113], v[108:109], v[226:227], v[112:113]
	v_and_or_b32 v8, v6, s66, v230
	v_pk_fma_f32 v[112:113], v[110:111], v[228:229], v[112:113]
	global_load_dwordx4 v[206:209], v8, s[98:99]
	v_add_f32_e32 v122, v112, v113
	s_waitcnt vmcnt(15)
; __device__ void phase_gather(const P& p, int vb, int nvb, char* smem) {
;     ...
; #pragma unroll 1
;     for (int b0 = 0; b0 < 128; b0 += 8) {
;       float dp[8];
; #pragma unroll
;       for (int u = 0; u < 8; u++) {
;         const uint32_t key = mykl[b0 + u];
;         const int e = (int)(key >> 7);
;         const uint4* up = (const uint4*)(U + (size_t)e * 1024 + 16 * j);
;         uint4 uu[4];
; #pragma unroll
;         for (int i = 0; i < 4; i++) uu[i] = up[i * 16];
;         f32x2 d2 = f32x2{0.f, 0.f};
; #pragma unroll
;         for (int i = 0; i < 4; i++) {
;           const uint32_t w[4] = {uu[i].x, uu[i].y, uu[i].z, uu[i].w};
; #pragma unroll
;           for (int q = 0; q < 4; q++) {
;             d2 += __builtin_amdgcn_cvt_pk_f32_fp8((int)w[q], false) * xf[i * 8 + q * 2 + 0];
;             d2 += __builtin_amdgcn_cvt_pk_f32_fp8((int)w[q], true) * xf[i * 8 + q * 2 + 1];
;           }
;         }
;         dp[u] = d2.x + d2.y;
;       }
;       const bool h8 = (j & 8) != 0, h4 = (j & 4) != 0, h2b = (j & 2) != 0;
;       float q4[4], q2[2];
; #pragma unroll
;       for (int k = 0; k < 4; k++) { const float snd = h8 ? dp[k] : dp[k + 4], kp = h8 ? dp[k + 4] : dp[k]; q4[k] = kp + __shfl_xor(snd, 8); }
; #pragma unroll
;       for (int k = 0; k < 2; k++) { const float snd = h4 ? q4[k] : q4[k + 2], kp = h4 ? q4[k + 2] : q4[k]; q2[k] = kp + __shfl_xor(snd, 4); }
;       const float snd1 = h2b ? q2[0] : q2[1], kp1 = h2b ? q2[1] : q2[0];
;       float q1 = kp1 + __shfl_xor(snd1, 2);
;       q1 += __shfl_xor(q1, 1);
;       if ((j & 1) == 0) mywl[b0 + (j >> 1)] = q1;
	v_cvt_pk_f32_fp8_e32 v[104:105], v210
	v_cvt_pk_f32_fp8_sdwa v[106:107], v210 src0_sel:WORD_1
	v_pk_mul_f32 v[112:113], v[104:105], v[214:215]
	v_cvt_pk_f32_fp8_e32 v[108:109], v211
	v_pk_fma_f32 v[112:113], v[106:107], v[216:217], v[112:113]
	v_cvt_pk_f32_fp8_sdwa v[110:111], v211 src0_sel:WORD_1
	v_pk_fma_f32 v[112:113], v[108:109], v[218:219], v[112:113]
	v_cvt_pk_f32_fp8_e32 v[104:105], v212
	v_pk_fma_f32 v[112:113], v[110:111], v[220:221], v[112:113]
	v_cvt_pk_f32_fp8_sdwa v[106:107], v212 src0_sel:WORD_1
	v_pk_fma_f32 v[112:113], v[104:105], v[222:223], v[112:113]
	v_cvt_pk_f32_fp8_e32 v[108:109], v213
	v_pk_fma_f32 v[112:113], v[106:107], v[224:225], v[112:113]
	v_cvt_pk_f32_fp8_sdwa v[110:111], v213 src0_sel:WORD_1
	v_pk_fma_f32 v[112:113], v[108:109], v[226:227], v[112:113]
	v_and_or_b32 v9, v7, s66, v230
	v_pk_fma_f32 v[112:113], v[110:111], v[228:229], v[112:113]
	global_load_dwordx4 v[210:213], v9, s[98:99]
	v_add_f32_e32 v123, v112, v113
	v_add_f32_dpp v10, v116, v116 row_ror:8 row_mask:0xf bank_mask:0x3
	v_add_f32_dpp v11, v117, v117 row_ror:8 row_mask:0xf bank_mask:0x3
	v_add_f32_dpp v12, v118, v118 row_ror:8 row_mask:0xf bank_mask:0x3
	v_add_f32_dpp v124, v119, v119 row_ror:8 row_mask:0xf bank_mask:0x3
	v_add_f32_dpp v10, v120, v120 row_ror:8 row_mask:0xf bank_mask:0xc
	v_add_f32_dpp v11, v121, v121 row_ror:8 row_mask:0xf bank_mask:0xc
	v_add_f32_dpp v12, v122, v122 row_ror:8 row_mask:0xf bank_mask:0xc
	v_add_f32_dpp v124, v123, v123 row_ror:8 row_mask:0xf bank_mask:0xc
	s_nop 0
	v_add_f32_dpp v125, v10, v10 row_shl:4 row_mask:0xf bank_mask:0x5
	v_add_f32_dpp v246, v11, v11 row_shl:4 row_mask:0xf bank_mask:0x5
	v_add_f32_dpp v125, v12, v12 row_shr:4 row_mask:0xf bank_mask:0xa
	v_add_f32_dpp v246, v124, v124 row_shr:4 row_mask:0xf bank_mask:0xa
	s_nop 1
	v_add_f32_dpp v247, v125, v125 quad_perm:[2,3,0,1] row_mask:0xf bank_mask:0xf
	v_add_f32_dpp v249, v246, v246 quad_perm:[2,3,0,1] row_mask:0xf bank_mask:0xf
	s_nop 0
	v_cndmask_b32_e64 v252, v249, v247, s[2:3]
	s_nop 1
	v_add_f32_dpp v253, v252, v252 quad_perm:[1,0,3,2] row_mask:0xf bank_mask:0xf
	s_and_saveexec_b64 s[20:21], s[4:5]
	ds_add_f32 v251, v253 offset:2080
	s_mov_b64 exec, s[20:21]
	s_add_i32 s26, s26, 1
	s_add_i32 s27, s26, 1
	s_lshr_b32 s27, s27, 3
	s_add_i32 s27, s27, s83
	s_and_b32 s27, s27, 3
	s_lshl_b32 s27, s27, 22
	v_add_u32_e32 v230, s27, v250
	s_and_b32 s27, s26, 7
	s_lshl_b32 s27, s27, 6
	v_add_u32_e32 v251, s27, v231
	s_branch .Lgu_iter
.Lgu_last:
	s_waitcnt vmcnt(15)
	v_cvt_pk_f32_fp8_e32 v[104:105], v150
	v_cvt_pk_f32_fp8_sdwa v[106:107], v150 src0_sel:WORD_1
	v_pk_mul_f32 v[112:113], v[104:105], v[214:215]
	v_cvt_pk_f32_fp8_e32 v[108:109], v151
	v_pk_fma_f32 v[112:113], v[106:107], v[216:217], v[112:113]
	v_cvt_pk_f32_fp8_sdwa v[110:111], v151 src0_sel:WORD_1
	v_pk_fma_f32 v[112:113], v[108:109], v[218:219], v[112:113]
	v_cvt_pk_f32_fp8_e32 v[104:105], v152
	v_pk_fma_f32 v[112:113], v[110:111], v[220:221], v[112:113]
	v_cvt_pk_f32_fp8_sdwa v[106:107], v152 src0_sel:WORD_1
	v_pk_fma_f32 v[112:113], v[104:105], v[222:223], v[112:113]
	v_cvt_pk_f32_fp8_e32 v[108:109], v153
	v_pk_fma_f32 v[112:113], v[106:107], v[224:225], v[112:113]
	v_cvt_pk_f32_fp8_sdwa v[110:111], v153 src0_sel:WORD_1
	v_pk_fma_f32 v[112:113], v[108:109], v[226:227], v[112:113]
	s_nop 0
	v_pk_fma_f32 v[112:113], v[110:111], v[228:229], v[112:113]
	s_nop 0
	v_add_f32_e32 v116, v112, v113
	s_waitcnt vmcnt(14)
	v_cvt_pk_f32_fp8_e32 v[104:105], v154
	v_cvt_pk_f32_fp8_sdwa v[106:107], v154 src0_sel:WORD_1
	v_pk_mul_f32 v[112:113], v[104:105], v[214:215]
	v_cvt_pk_f32_fp8_e32 v[108:109], v155
	v_pk_fma_f32 v[112:113], v[106:107], v[216:217], v[112:113]
	v_cvt_pk_f32_fp8_sdwa v[110:111], v155 src0_sel:WORD_1
	v_pk_fma_f32 v[112:113], v[108:109], v[218:219], v[112:113]
	v_cvt_pk_f32_fp8_e32 v[104:105], v156
	v_pk_fma_f32 v[112:113], v[110:111], v[220:221], v[112:113]
	v_cvt_pk_f32_fp8_sdwa v[106:107], v156 src0_sel:WORD_1
	v_pk_fma_f32 v[112:113], v[104:105], v[222:223], v[112:113]
	v_cvt_pk_f32_fp8_e32 v[108:109], v157
	v_pk_fma_f32 v[112:113], v[106:107], v[224:225], v[112:113]
	v_cvt_pk_f32_fp8_sdwa v[110:111], v157 src0_sel:WORD_1
	v_pk_fma_f32 v[112:113], v[108:109], v[226:227], v[112:113]
	s_nop 0
	v_pk_fma_f32 v[112:113], v[110:111], v[228:229], v[112:113]
	s_nop 0
	v_add_f32_e32 v117, v112, v113
	s_waitcnt vmcnt(13)
	v_cvt_pk_f32_fp8_e32 v[104:105], v158
	v_cvt_pk_f32_fp8_sdwa v[106:107], v158 src0_sel:WORD_1
	v_pk_mul_f32 v[112:113], v[104:105], v[214:215]
	v_cvt_pk_f32_fp8_e32 v[108:109], v159
	v_pk_fma_f32 v[112:113], v[106:107], v[216:217], v[112:113]
	v_cvt_pk_f32_fp8_sdwa v[110:111], v159 src0_sel:WORD_1
	v_pk_fma_f32 v[112:113], v[108:109], v[218:219], v[112:113]
	v_cvt_pk_f32_fp8_e32 v[104:105], v160
	v_pk_fma_f32 v[112:113], v[110:111], v[220:221], v[112:113]
	v_cvt_pk_f32_fp8_sdwa v[106:107], v160 src0_sel:WORD_1
	v_pk_fma_f32 v[112:113], v[104:105], v[222:223], v[112:113]
	v_cvt_pk_f32_fp8_e32 v[108:109], v161
	v_pk_fma_f32 v[112:113], v[106:107], v[224:225], v[112:113]
	v_cvt_pk_f32_fp8_sdwa v[110:111], v161 src0_sel:WORD_1
	v_pk_fma_f32 v[112:113], v[108:109], v[226:227], v[112:113]
	s_nop 0
	v_pk_fma_f32 v[112:113], v[110:111], v[228:229], v[112:113]
	s_nop 0
	v_add_f32_e32 v118, v112, v113
	s_waitcnt vmcnt(12)
; __device__ void phase_gather(const P& p, int vb, int nvb, char* smem) {
;     ...
; #pragma unroll 1
;     for (int b0 = 0; b0 < 128; b0 += 8) {
;       float dp[8];
; #pragma unroll
;       for (int u = 0; u < 8; u++) {
;         const uint32_t key = mykl[b0 + u];
;         const int e = (int)(key >> 7);
;         const uint4* up = (const uint4*)(U + (size_t)e * 1024 + 16 * j);
;         uint4 uu[4];
; #pragma unroll
;         for (int i = 0; i < 4; i++) uu[i] = up[i * 16];
;         f32x2 d2 = f32x2{0.f, 0.f};
; #pragma unroll
;         for (int i = 0; i < 4; i++) {
;           const uint32_t w[4] = {uu[i].x, uu[i].y, uu[i].z, uu[i].w};
; #pragma unroll
;           for (int q = 0; q < 4; q++) {
;             d2 += __builtin_amdgcn_cvt_pk_f32_fp8((int)w[q], false) * xf[i * 8 + q * 2 + 0];
;             d2 += __builtin_amdgcn_cvt_pk_f32_fp8((int)w[q], true) * xf[i * 8 + q * 2 + 1];
;           }
;         }
;         dp[u] = d2.x + d2.y;
;       }
;       const bool h8 = (j & 8) != 0, h4 = (j & 4) != 0, h2b = (j & 2) != 0;
;       float q4[4], q2[2];
; #pragma unroll
;       for (int k = 0; k < 4; k++) { const float snd = h8 ? dp[k] : dp[k + 4], kp = h8 ? dp[k + 4] : dp[k]; q4[k] = kp + __shfl_xor(snd, 8); }
; #pragma unroll
;       for (int k = 0; k < 2; k++) { const float snd = h4 ? q4[k] : q4[k + 2], kp = h4 ? q4[k + 2] : q4[k]; q2[k] = kp + __shfl_xor(snd, 4); }
;       const float snd1 = h2b ? q2[0] : q2[1], kp1 = h2b ? q2[1] : q2[0];
;       float q1 = kp1 + __shfl_xor(snd1, 2);
;       q1 += __shfl_xor(q1, 1);
;       if ((j & 1) == 0) mywl[b0 + (j >> 1)] = q1;
	v_cvt_pk_f32_fp8_e32 v[104:105], v162
	v_cvt_pk_f32_fp8_sdwa v[106:107], v162 src0_sel:WORD_1
	v_pk_mul_f32 v[112:113], v[104:105], v[214:215]
	v_cvt_pk_f32_fp8_e32 v[108:109], v163
	v_pk_fma_f32 v[112:113], v[106:107], v[216:217], v[112:113]
	v_cvt_pk_f32_fp8_sdwa v[110:111], v163 src0_sel:WORD_1
	v_pk_fma_f32 v[112:113], v[108:109], v[218:219], v[112:113]
	v_cvt_pk_f32_fp8_e32 v[104:105], v164
	v_pk_fma_f32 v[112:113], v[110:111], v[220:221], v[112:113]
	v_cvt_pk_f32_fp8_sdwa v[106:107], v164 src0_sel:WORD_1
	v_pk_fma_f32 v[112:113], v[104:105], v[222:223], v[112:113]
	v_cvt_pk_f32_fp8_e32 v[108:109], v165
	v_pk_fma_f32 v[112:113], v[106:107], v[224:225], v[112:113]
	v_cvt_pk_f32_fp8_sdwa v[110:111], v165 src0_sel:WORD_1
	v_pk_fma_f32 v[112:113], v[108:109], v[226:227], v[112:113]
	s_nop 0
	v_pk_fma_f32 v[112:113], v[110:111], v[228:229], v[112:113]
	s_nop 0
	v_add_f32_e32 v119, v112, v113
	s_waitcnt vmcnt(11)
	v_cvt_pk_f32_fp8_e32 v[104:105], v166
	v_cvt_pk_f32_fp8_sdwa v[106:107], v166 src0_sel:WORD_1
	v_pk_mul_f32 v[112:113], v[104:105], v[214:215]
	v_cvt_pk_f32_fp8_e32 v[108:109], v167
	v_pk_fma_f32 v[112:113], v[106:107], v[216:217], v[112:113]
	v_cvt_pk_f32_fp8_sdwa v[110:111], v167 src0_sel:WORD_1
	v_pk_fma_f32 v[112:113], v[108:109], v[218:219], v[112:113]
	v_cvt_pk_f32_fp8_e32 v[104:105], v168
	v_pk_fma_f32 v[112:113], v[110:111], v[220:221], v[112:113]
	v_cvt_pk_f32_fp8_sdwa v[106:107], v168 src0_sel:WORD_1
	v_pk_fma_f32 v[112:113], v[104:105], v[222:223], v[112:113]
	v_cvt_pk_f32_fp8_e32 v[108:109], v169
	v_pk_fma_f32 v[112:113], v[106:107], v[224:225], v[112:113]
	v_cvt_pk_f32_fp8_sdwa v[110:111], v169 src0_sel:WORD_1
	v_pk_fma_f32 v[112:113], v[108:109], v[226:227], v[112:113]
	s_nop 0
	v_pk_fma_f32 v[112:113], v[110:111], v[228:229], v[112:113]
	s_nop 0
	v_add_f32_e32 v120, v112, v113
	s_waitcnt vmcnt(10)
	v_cvt_pk_f32_fp8_e32 v[104:105], v170
	v_cvt_pk_f32_fp8_sdwa v[106:107], v170 src0_sel:WORD_1
	v_pk_mul_f32 v[112:113], v[104:105], v[214:215]
	v_cvt_pk_f32_fp8_e32 v[108:109], v171
	v_pk_fma_f32 v[112:113], v[106:107], v[216:217], v[112:113]
	v_cvt_pk_f32_fp8_sdwa v[110:111], v171 src0_sel:WORD_1
	v_pk_fma_f32 v[112:113], v[108:109], v[218:219], v[112:113]
	v_cvt_pk_f32_fp8_e32 v[104:105], v172
	v_pk_fma_f32 v[112:113], v[110:111], v[220:221], v[112:113]
	v_cvt_pk_f32_fp8_sdwa v[106:107], v172 src0_sel:WORD_1
	v_pk_fma_f32 v[112:113], v[104:105], v[222:223], v[112:113]
	v_cvt_pk_f32_fp8_e32 v[108:109], v173
	v_pk_fma_f32 v[112:113], v[106:107], v[224:225], v[112:113]
	v_cvt_pk_f32_fp8_sdwa v[110:111], v173 src0_sel:WORD_1
	v_pk_fma_f32 v[112:113], v[108:109], v[226:227], v[112:113]
	s_nop 0
	v_pk_fma_f32 v[112:113], v[110:111], v[228:229], v[112:113]
	s_nop 0
	v_add_f32_e32 v121, v112, v113
	s_waitcnt vmcnt(9)
	v_cvt_pk_f32_fp8_e32 v[104:105], v174
	v_cvt_pk_f32_fp8_sdwa v[106:107], v174 src0_sel:WORD_1
	v_pk_mul_f32 v[112:113], v[104:105], v[214:215]
	v_cvt_pk_f32_fp8_e32 v[108:109], v175
	v_pk_fma_f32 v[112:113], v[106:107], v[216:217], v[112:113]
	v_cvt_pk_f32_fp8_sdwa v[110:111], v175 src0_sel:WORD_1
	v_pk_fma_f32 v[112:113], v[108:109], v[218:219], v[112:113]
	v_cvt_pk_f32_fp8_e32 v[104:105], v176
	v_pk_fma_f32 v[112:113], v[110:111], v[220:221], v[112:113]
	v_cvt_pk_f32_fp8_sdwa v[106:107], v176 src0_sel:WORD_1
	v_pk_fma_f32 v[112:113], v[104:105], v[222:223], v[112:113]
	v_cvt_pk_f32_fp8_e32 v[108:109], v177
	v_pk_fma_f32 v[112:113], v[106:107], v[224:225], v[112:113]
	v_cvt_pk_f32_fp8_sdwa v[110:111], v177 src0_sel:WORD_1
	v_pk_fma_f32 v[112:113], v[108:109], v[226:227], v[112:113]
	s_nop 0
	v_pk_fma_f32 v[112:113], v[110:111], v[228:229], v[112:113]
	s_nop 0
	v_add_f32_e32 v122, v112, v113
	s_waitcnt vmcnt(8)
	v_cvt_pk_f32_fp8_e32 v[104:105], v178
	v_cvt_pk_f32_fp8_sdwa v[106:107], v178 src0_sel:WORD_1
	v_pk_mul_f32 v[112:113], v[104:105], v[214:215]
	v_cvt_pk_f32_fp8_e32 v[108:109], v179
	v_pk_fma_f32 v[112:113], v[106:107], v[216:217], v[112:113]
	v_cvt_pk_f32_fp8_sdwa v[110:111], v179 src0_sel:WORD_1
	v_pk_fma_f32 v[112:113], v[108:109], v[218:219], v[112:113]
	v_cvt_pk_f32_fp8_e32 v[104:105], v180
	v_pk_fma_f32 v[112:113], v[110:111], v[220:221], v[112:113]
	v_cvt_pk_f32_fp8_sdwa v[106:107], v180 src0_sel:WORD_1
	v_pk_fma_f32 v[112:113], v[104:105], v[222:223], v[112:113]
	v_cvt_pk_f32_fp8_e32 v[108:109], v181
	v_pk_fma_f32 v[112:113], v[106:107], v[224:225], v[112:113]
	v_cvt_pk_f32_fp8_sdwa v[110:111], v181 src0_sel:WORD_1
	v_pk_fma_f32 v[112:113], v[108:109], v[226:227], v[112:113]
	s_nop 0
	v_pk_fma_f32 v[112:113], v[110:111], v[228:229], v[112:113]
	s_nop 0
	v_add_f32_e32 v123, v112, v113
	v_add_f32_dpp v10, v116, v116 row_ror:8 row_mask:0xf bank_mask:0x3
	v_add_f32_dpp v11, v117, v117 row_ror:8 row_mask:0xf bank_mask:0x3
	v_add_f32_dpp v12, v118, v118 row_ror:8 row_mask:0xf bank_mask:0x3
	v_add_f32_dpp v124, v119, v119 row_ror:8 row_mask:0xf bank_mask:0x3
	v_add_f32_dpp v10, v120, v120 row_ror:8 row_mask:0xf bank_mask:0xc
	v_add_f32_dpp v11, v121, v121 row_ror:8 row_mask:0xf bank_mask:0xc
	v_add_f32_dpp v12, v122, v122 row_ror:8 row_mask:0xf bank_mask:0xc
	v_add_f32_dpp v124, v123, v123 row_ror:8 row_mask:0xf bank_mask:0xc
	s_nop 0
	v_add_f32_dpp v125, v10, v10 row_shl:4 row_mask:0xf bank_mask:0x5
	v_add_f32_dpp v246, v11, v11 row_shl:4 row_mask:0xf bank_mask:0x5
	v_add_f32_dpp v125, v12, v12 row_shr:4 row_mask:0xf bank_mask:0xa
	v_add_f32_dpp v246, v124, v124 row_shr:4 row_mask:0xf bank_mask:0xa
	s_nop 1
	v_add_f32_dpp v247, v125, v125 quad_perm:[2,3,0,1] row_mask:0xf bank_mask:0xf
	v_add_f32_dpp v249, v246, v246 quad_perm:[2,3,0,1] row_mask:0xf bank_mask:0xf
	s_nop 0
	v_cndmask_b32_e64 v252, v249, v247, s[2:3]
	s_nop 1
	v_add_f32_dpp v253, v252, v252 quad_perm:[1,0,3,2] row_mask:0xf bank_mask:0xf
	s_and_saveexec_b64 s[20:21], s[4:5]
	ds_add_f32 v251, v253 offset:2048
	s_mov_b64 exec, s[20:21]
	s_waitcnt vmcnt(7)
; __device__ void phase_gather(const P& p, int vb, int nvb, char* smem) {
;     ...
; #pragma unroll 1
;     for (int b0 = 0; b0 < 128; b0 += 8) {
;       float dp[8];
; #pragma unroll
;       for (int u = 0; u < 8; u++) {
;         const uint32_t key = mykl[b0 + u];
;         const int e = (int)(key >> 7);
;         const uint4* up = (const uint4*)(U + (size_t)e * 1024 + 16 * j);
;         uint4 uu[4];
; #pragma unroll
;         for (int i = 0; i < 4; i++) uu[i] = up[i * 16];
;         f32x2 d2 = f32x2{0.f, 0.f};
; #pragma unroll
;         for (int i = 0; i < 4; i++) {
;           const uint32_t w[4] = {uu[i].x, uu[i].y, uu[i].z, uu[i].w};
; #pragma unroll
;           for (int q = 0; q < 4; q++) {
;             d2 += __builtin_amdgcn_cvt_pk_f32_fp8((int)w[q], false) * xf[i * 8 + q * 2 + 0];
;             d2 += __builtin_amdgcn_cvt_pk_f32_fp8((int)w[q], true) * xf[i * 8 + q * 2 + 1];
;           }
;         }
;         dp[u] = d2.x + d2.y;
;       }
	v_cvt_pk_f32_fp8_e32 v[104:105], v182
	v_cvt_pk_f32_fp8_sdwa v[106:107], v182 src0_sel:WORD_1
	v_pk_mul_f32 v[112:113], v[104:105], v[214:215]
	v_cvt_pk_f32_fp8_e32 v[108:109], v183
	v_pk_fma_f32 v[112:113], v[106:107], v[216:217], v[112:113]
	v_cvt_pk_f32_fp8_sdwa v[110:111], v183 src0_sel:WORD_1
	v_pk_fma_f32 v[112:113], v[108:109], v[218:219], v[112:113]
	v_cvt_pk_f32_fp8_e32 v[104:105], v184
	v_pk_fma_f32 v[112:113], v[110:111], v[220:221], v[112:113]
	v_cvt_pk_f32_fp8_sdwa v[106:107], v184 src0_sel:WORD_1
	v_pk_fma_f32 v[112:113], v[104:105], v[222:223], v[112:113]
	v_cvt_pk_f32_fp8_e32 v[108:109], v185
	v_pk_fma_f32 v[112:113], v[106:107], v[224:225], v[112:113]
	v_cvt_pk_f32_fp8_sdwa v[110:111], v185 src0_sel:WORD_1
	v_pk_fma_f32 v[112:113], v[108:109], v[226:227], v[112:113]
	s_nop 0
	v_pk_fma_f32 v[112:113], v[110:111], v[228:229], v[112:113]
	s_nop 0
	v_add_f32_e32 v116, v112, v113
	s_waitcnt vmcnt(6)
	v_cvt_pk_f32_fp8_e32 v[104:105], v186
	v_cvt_pk_f32_fp8_sdwa v[106:107], v186 src0_sel:WORD_1
	v_pk_mul_f32 v[112:113], v[104:105], v[214:215]
	v_cvt_pk_f32_fp8_e32 v[108:109], v187
	v_pk_fma_f32 v[112:113], v[106:107], v[216:217], v[112:113]
	v_cvt_pk_f32_fp8_sdwa v[110:111], v187 src0_sel:WORD_1
	v_pk_fma_f32 v[112:113], v[108:109], v[218:219], v[112:113]
	v_cvt_pk_f32_fp8_e32 v[104:105], v188
	v_pk_fma_f32 v[112:113], v[110:111], v[220:221], v[112:113]
	v_cvt_pk_f32_fp8_sdwa v[106:107], v188 src0_sel:WORD_1
	v_pk_fma_f32 v[112:113], v[104:105], v[222:223], v[112:113]
	v_cvt_pk_f32_fp8_e32 v[108:109], v189
	v_pk_fma_f32 v[112:113], v[106:107], v[224:225], v[112:113]
	v_cvt_pk_f32_fp8_sdwa v[110:111], v189 src0_sel:WORD_1
	v_pk_fma_f32 v[112:113], v[108:109], v[226:227], v[112:113]
	s_nop 0
	v_pk_fma_f32 v[112:113], v[110:111], v[228:229], v[112:113]
	s_nop 0
	v_add_f32_e32 v117, v112, v113
	s_waitcnt vmcnt(5)
	v_cvt_pk_f32_fp8_e32 v[104:105], v190
	v_cvt_pk_f32_fp8_sdwa v[106:107], v190 src0_sel:WORD_1
	v_pk_mul_f32 v[112:113], v[104:105], v[214:215]
	v_cvt_pk_f32_fp8_e32 v[108:109], v191
	v_pk_fma_f32 v[112:113], v[106:107], v[216:217], v[112:113]
	v_cvt_pk_f32_fp8_sdwa v[110:111], v191 src0_sel:WORD_1
	v_pk_fma_f32 v[112:113], v[108:109], v[218:219], v[112:113]
	v_cvt_pk_f32_fp8_e32 v[104:105], v192
	v_pk_fma_f32 v[112:113], v[110:111], v[220:221], v[112:113]
	v_cvt_pk_f32_fp8_sdwa v[106:107], v192 src0_sel:WORD_1
	v_pk_fma_f32 v[112:113], v[104:105], v[222:223], v[112:113]
	v_cvt_pk_f32_fp8_e32 v[108:109], v193
	v_pk_fma_f32 v[112:113], v[106:107], v[224:225], v[112:113]
	v_cvt_pk_f32_fp8_sdwa v[110:111], v193 src0_sel:WORD_1
	v_pk_fma_f32 v[112:113], v[108:109], v[226:227], v[112:113]
	s_nop 0
	v_pk_fma_f32 v[112:113], v[110:111], v[228:229], v[112:113]
	s_nop 0
	v_add_f32_e32 v118, v112, v113
	s_waitcnt vmcnt(4)
	v_cvt_pk_f32_fp8_e32 v[104:105], v194
	v_cvt_pk_f32_fp8_sdwa v[106:107], v194 src0_sel:WORD_1
	v_pk_mul_f32 v[112:113], v[104:105], v[214:215]
	v_cvt_pk_f32_fp8_e32 v[108:109], v195
	v_pk_fma_f32 v[112:113], v[106:107], v[216:217], v[112:113]
	v_cvt_pk_f32_fp8_sdwa v[110:111], v195 src0_sel:WORD_1
	v_pk_fma_f32 v[112:113], v[108:109], v[218:219], v[112:113]
	v_cvt_pk_f32_fp8_e32 v[104:105], v196
	v_pk_fma_f32 v[112:113], v[110:111], v[220:221], v[112:113]
	v_cvt_pk_f32_fp8_sdwa v[106:107], v196 src0_sel:WORD_1
	v_pk_fma_f32 v[112:113], v[104:105], v[222:223], v[112:113]
	v_cvt_pk_f32_fp8_e32 v[108:109], v197
	v_pk_fma_f32 v[112:113], v[106:107], v[224:225], v[112:113]
	v_cvt_pk_f32_fp8_sdwa v[110:111], v197 src0_sel:WORD_1
	v_pk_fma_f32 v[112:113], v[108:109], v[226:227], v[112:113]
	s_nop 0
	v_pk_fma_f32 v[112:113], v[110:111], v[228:229], v[112:113]
	s_nop 0
	v_add_f32_e32 v119, v112, v113
	s_waitcnt vmcnt(3)
	v_cvt_pk_f32_fp8_e32 v[104:105], v198
	v_cvt_pk_f32_fp8_sdwa v[106:107], v198 src0_sel:WORD_1
	v_pk_mul_f32 v[112:113], v[104:105], v[214:215]
	v_cvt_pk_f32_fp8_e32 v[108:109], v199
	v_pk_fma_f32 v[112:113], v[106:107], v[216:217], v[112:113]
	v_cvt_pk_f32_fp8_sdwa v[110:111], v199 src0_sel:WORD_1
	v_pk_fma_f32 v[112:113], v[108:109], v[218:219], v[112:113]
	v_cvt_pk_f32_fp8_e32 v[104:105], v200
	v_pk_fma_f32 v[112:113], v[110:111], v[220:221], v[112:113]
	v_cvt_pk_f32_fp8_sdwa v[106:107], v200 src0_sel:WORD_1
	v_pk_fma_f32 v[112:113], v[104:105], v[222:223], v[112:113]
	v_cvt_pk_f32_fp8_e32 v[108:109], v201
	v_pk_fma_f32 v[112:113], v[106:107], v[224:225], v[112:113]
	v_cvt_pk_f32_fp8_sdwa v[110:111], v201 src0_sel:WORD_1
	v_pk_fma_f32 v[112:113], v[108:109], v[226:227], v[112:113]
	s_nop 0
	v_pk_fma_f32 v[112:113], v[110:111], v[228:229], v[112:113]
	s_nop 0
	v_add_f32_e32 v120, v112, v113
	s_waitcnt vmcnt(2)
; __device__ void phase_gather(const P& p, int vb, int nvb, char* smem) {
;     ...
; #pragma unroll 1
;     for (int b0 = 0; b0 < 128; b0 += 8) {
;       float dp[8];
; #pragma unroll
;       for (int u = 0; u < 8; u++) {
;         const uint32_t key = mykl[b0 + u];
;         const int e = (int)(key >> 7);
;         const uint4* up = (const uint4*)(U + (size_t)e * 1024 + 16 * j);
;         uint4 uu[4];
; #pragma unroll
;         for (int i = 0; i < 4; i++) uu[i] = up[i * 16];
;         f32x2 d2 = f32x2{0.f, 0.f};
; #pragma unroll
;         for (int i = 0; i < 4; i++) {
;           const uint32_t w[4] = {uu[i].x, uu[i].y, uu[i].z, uu[i].w};
; #pragma unroll
;           for (int q = 0; q < 4; q++) {
;             d2 += __builtin_amdgcn_cvt_pk_f32_fp8((int)w[q], false) * xf[i * 8 + q * 2 + 0];
;             d2 += __builtin_amdgcn_cvt_pk_f32_fp8((int)w[q], true) * xf[i * 8 + q * 2 + 1];
;           }
;         }
;         dp[u] = d2.x + d2.y;
;       }
;       const bool h8 = (j & 8) != 0, h4 = (j & 4) != 0, h2b = (j & 2) != 0;
;       float q4[4], q2[2];
; #pragma unroll
;       for (int k = 0; k < 4; k++) { const float snd = h8 ? dp[k] : dp[k + 4], kp = h8 ? dp[k + 4] : dp[k]; q4[k] = kp + __shfl_xor(snd, 8); }
; #pragma unroll
;       for (int k = 0; k < 2; k++) { const float snd = h4 ? q4[k] : q4[k + 2], kp = h4 ? q4[k + 2] : q4[k]; q2[k] = kp + __shfl_xor(snd, 4); }
;       const float snd1 = h2b ? q2[0] : q2[1], kp1 = h2b ? q2[1] : q2[0];
;       float q1 = kp1 + __shfl_xor(snd1, 2);
;       q1 += __shfl_xor(q1, 1);
;       if ((j & 1) == 0) mywl[b0 + (j >> 1)] = q1;
	v_cvt_pk_f32_fp8_e32 v[104:105], v202
	v_cvt_pk_f32_fp8_sdwa v[106:107], v202 src0_sel:WORD_1
	v_pk_mul_f32 v[112:113], v[104:105], v[214:215]
	v_cvt_pk_f32_fp8_e32 v[108:109], v203
	v_pk_fma_f32 v[112:113], v[106:107], v[216:217], v[112:113]
	v_cvt_pk_f32_fp8_sdwa v[110:111], v203 src0_sel:WORD_1
	v_pk_fma_f32 v[112:113], v[108:109], v[218:219], v[112:113]
	v_cvt_pk_f32_fp8_e32 v[104:105], v204
	v_pk_fma_f32 v[112:113], v[110:111], v[220:221], v[112:113]
	v_cvt_pk_f32_fp8_sdwa v[106:107], v204 src0_sel:WORD_1
	v_pk_fma_f32 v[112:113], v[104:105], v[222:223], v[112:113]
	v_cvt_pk_f32_fp8_e32 v[108:109], v205
	v_pk_fma_f32 v[112:113], v[106:107], v[224:225], v[112:113]
	v_cvt_pk_f32_fp8_sdwa v[110:111], v205 src0_sel:WORD_1
	v_pk_fma_f32 v[112:113], v[108:109], v[226:227], v[112:113]
	s_nop 0
	v_pk_fma_f32 v[112:113], v[110:111], v[228:229], v[112:113]
	s_nop 0
	v_add_f32_e32 v121, v112, v113
	s_waitcnt vmcnt(1)
	v_cvt_pk_f32_fp8_e32 v[104:105], v206
	v_cvt_pk_f32_fp8_sdwa v[106:107], v206 src0_sel:WORD_1
	v_pk_mul_f32 v[112:113], v[104:105], v[214:215]
	v_cvt_pk_f32_fp8_e32 v[108:109], v207
	v_pk_fma_f32 v[112:113], v[106:107], v[216:217], v[112:113]
	v_cvt_pk_f32_fp8_sdwa v[110:111], v207 src0_sel:WORD_1
	v_pk_fma_f32 v[112:113], v[108:109], v[218:219], v[112:113]
	v_cvt_pk_f32_fp8_e32 v[104:105], v208
	v_pk_fma_f32 v[112:113], v[110:111], v[220:221], v[112:113]
	v_cvt_pk_f32_fp8_sdwa v[106:107], v208 src0_sel:WORD_1
	v_pk_fma_f32 v[112:113], v[104:105], v[222:223], v[112:113]
	v_cvt_pk_f32_fp8_e32 v[108:109], v209
	v_pk_fma_f32 v[112:113], v[106:107], v[224:225], v[112:113]
	v_cvt_pk_f32_fp8_sdwa v[110:111], v209 src0_sel:WORD_1
	v_pk_fma_f32 v[112:113], v[108:109], v[226:227], v[112:113]
	s_nop 0
	v_pk_fma_f32 v[112:113], v[110:111], v[228:229], v[112:113]
	s_nop 0
	v_add_f32_e32 v122, v112, v113
	s_waitcnt vmcnt(0)
	v_cvt_pk_f32_fp8_e32 v[104:105], v210
	v_cvt_pk_f32_fp8_sdwa v[106:107], v210 src0_sel:WORD_1
	v_pk_mul_f32 v[112:113], v[104:105], v[214:215]
	v_cvt_pk_f32_fp8_e32 v[108:109], v211
	v_pk_fma_f32 v[112:113], v[106:107], v[216:217], v[112:113]
	v_cvt_pk_f32_fp8_sdwa v[110:111], v211 src0_sel:WORD_1
	v_pk_fma_f32 v[112:113], v[108:109], v[218:219], v[112:113]
	v_cvt_pk_f32_fp8_e32 v[104:105], v212
	v_pk_fma_f32 v[112:113], v[110:111], v[220:221], v[112:113]
	v_cvt_pk_f32_fp8_sdwa v[106:107], v212 src0_sel:WORD_1
	v_pk_fma_f32 v[112:113], v[104:105], v[222:223], v[112:113]
	v_cvt_pk_f32_fp8_e32 v[108:109], v213
	v_pk_fma_f32 v[112:113], v[106:107], v[224:225], v[112:113]
	v_cvt_pk_f32_fp8_sdwa v[110:111], v213 src0_sel:WORD_1
	v_pk_fma_f32 v[112:113], v[108:109], v[226:227], v[112:113]
	s_nop 0
	v_pk_fma_f32 v[112:113], v[110:111], v[228:229], v[112:113]
	s_nop 0
	v_add_f32_e32 v123, v112, v113
	v_add_f32_dpp v10, v116, v116 row_ror:8 row_mask:0xf bank_mask:0x3
	v_add_f32_dpp v11, v117, v117 row_ror:8 row_mask:0xf bank_mask:0x3
	v_add_f32_dpp v12, v118, v118 row_ror:8 row_mask:0xf bank_mask:0x3
	v_add_f32_dpp v124, v119, v119 row_ror:8 row_mask:0xf bank_mask:0x3
	v_add_f32_dpp v10, v120, v120 row_ror:8 row_mask:0xf bank_mask:0xc
	v_add_f32_dpp v11, v121, v121 row_ror:8 row_mask:0xf bank_mask:0xc
	v_add_f32_dpp v12, v122, v122 row_ror:8 row_mask:0xf bank_mask:0xc
	v_add_f32_dpp v124, v123, v123 row_ror:8 row_mask:0xf bank_mask:0xc
	s_nop 0
	v_add_f32_dpp v125, v10, v10 row_shl:4 row_mask:0xf bank_mask:0x5
	v_add_f32_dpp v246, v11, v11 row_shl:4 row_mask:0xf bank_mask:0x5
	v_add_f32_dpp v125, v12, v12 row_shr:4 row_mask:0xf bank_mask:0xa
	v_add_f32_dpp v246, v124, v124 row_shr:4 row_mask:0xf bank_mask:0xa
	s_nop 1
	v_add_f32_dpp v247, v125, v125 quad_perm:[2,3,0,1] row_mask:0xf bank_mask:0xf
	v_add_f32_dpp v249, v246, v246 quad_perm:[2,3,0,1] row_mask:0xf bank_mask:0xf
	s_nop 0
	v_cndmask_b32_e64 v252, v249, v247, s[2:3]
	s_nop 1
	v_add_f32_dpp v253, v252, v252 quad_perm:[1,0,3,2] row_mask:0xf bank_mask:0xf
	s_and_saveexec_b64 s[20:21], s[4:5]
	ds_add_f32 v251, v253 offset:2080
	s_mov_b64 exec, s[20:21]

; DEVI float gelu_exact(float x) { return 0.5f * x * (1.f + erff(x * 0.70710678118654752f)); }
; __device__ void phase_gather(const P& p, int vb, int nvb, char* smem) {
;     ...
;     asm volatile("s_waitcnt lgkmcnt(0)" ::: "memory");
; #pragma unroll
;     for (int m = 0; m < 8; m++) {
;       const int bb = j + 16 * m;
;       const float d = mywl[bb] * (1.f / USCALE);
;       mywl[bb] = gpre[m] * gelu_exact(d) * (1.f / VSCALE);
;     }
;     asm volatile("s_waitcnt lgkmcnt(0)" ::: "memory");
;     f32x2 acc[32];
; #pragma unroll
;     for (int i = 0; i < 32; i++) acc[i] = f32x2{0.f, 0.f};
; #pragma unroll 8
;     for (int bb = 0; bb < 128; bb++) {
;       const uint32_t key = mykl[bb];
;       const int e = (int)(key >> 7);
;       const float wgt = mywl[bb];
;       const uint4* vp = (const uint4*)(V + (size_t)e * 1024 + 16 * j);
;       uint4 vv[4];
; #pragma unroll
;       for (int i = 0; i < 4; i++) vv[i] = vp[i * 16];
;       const f32x2 w2 = f32x2{wgt, wgt};
; #pragma unroll
;       for (int i = 0; i < 4; i++) {
;         const uint32_t w[4] = {vv[i].x, vv[i].y, vv[i].z, vv[i].w};
; #pragma unroll
;         for (int q = 0; q < 4; q++) {
;           acc[i * 8 + q * 2 + 0] += w2 * __builtin_amdgcn_cvt_pk_f32_fp8((int)w[q], false);
;           acc[i * 8 + q * 2 + 1] += w2 * __builtin_amdgcn_cvt_pk_f32_fp8((int)w[q], true);
;         }
;       }
;     }
.LBB0_530:
	s_andn2_saveexec_b64 s[20:21], s[26:27]
	v_mul_f32_e32 v2, v1, v1
	v_fmamk_f32 v3, v2, 0xba1345e1, v145
	v_fmaak_f32 v3, v2, v3, 0xbcdac9b8
	v_fmaak_f32 v3, v2, v3, 0x3de703be
	v_fmaak_f32 v3, v2, v3, 0xbec09330
	v_fmaak_f32 v2, v2, v3, 0x3e0375d0
	v_fma_f32 v2, |v1|, v2, |v1|
	s_or_b64 exec, exec, s[20:21]
	v_bfi_b32 v1, s41, v2, v1
	v_mul_f32_e32 v0, 0.5, v0
	v_add_f32_e32 v1, 1.0, v1
	v_mul_f32_e32 v0, v0, v1
	v_mul_f32_e32 v0, v96, v0
	v_mul_f32_e32 v0, 0x3c800000, v0
	ds_write_b32 v144, v0 offset:2496
	s_waitcnt lgkmcnt(0)
	v_mov_b32_e32 v32, 0
	s_mov_b32 s20, 0
	v_mov_b32_e32 v33, v32
	v_mov_b32_e32 v34, v32
	v_mov_b32_e32 v35, v32
	v_mov_b32_e32 v36, v32
	v_mov_b32_e32 v37, v32
	v_mov_b32_e32 v38, v32
	v_mov_b32_e32 v39, v32
	v_mov_b32_e32 v40, v32
	v_mov_b32_e32 v41, v32
	v_mov_b32_e32 v42, v32
	v_mov_b32_e32 v43, v32
	v_mov_b32_e32 v44, v32
	v_mov_b32_e32 v45, v32
	v_mov_b32_e32 v46, v32
	v_mov_b32_e32 v47, v32
	v_mov_b32_e32 v48, v32
	v_mov_b32_e32 v49, v32
	v_mov_b32_e32 v50, v32
	v_mov_b32_e32 v51, v32
	v_mov_b32_e32 v52, v32
	v_mov_b32_e32 v53, v32
	v_mov_b32_e32 v54, v32
	v_mov_b32_e32 v55, v32
	v_mov_b32_e32 v56, v32
	v_mov_b32_e32 v57, v32
	v_mov_b32_e32 v58, v32
	v_mov_b32_e32 v59, v32
	v_mov_b32_e32 v60, v32
	v_mov_b32_e32 v61, v32
	v_mov_b32_e32 v64, v32
	v_mov_b32_e32 v65, v32
	v_mov_b32_e32 v62, v32
	v_mov_b32_e32 v63, v32
	v_mov_b32_e32 v66, v32
	v_mov_b32_e32 v67, v32
	v_mov_b32_e32 v68, v32
	v_mov_b32_e32 v69, v32
	v_mov_b32_e32 v70, v32
	v_mov_b32_e32 v71, v32
	v_mov_b32_e32 v72, v32
	v_mov_b32_e32 v73, v32
	v_mov_b32_e32 v74, v32
	v_mov_b32_e32 v75, v32
	v_mov_b32_e32 v76, v32
	v_mov_b32_e32 v77, v32
	v_mov_b32_e32 v78, v32
	v_mov_b32_e32 v79, v32
	v_mov_b32_e32 v80, v32
	v_mov_b32_e32 v81, v32
	v_mov_b32_e32 v82, v32
	v_mov_b32_e32 v83, v32
	v_mov_b32_e32 v84, v32
	v_mov_b32_e32 v85, v32
	v_mov_b32_e32 v86, v32
	v_mov_b32_e32 v87, v32
	v_mov_b32_e32 v88, v32
	v_mov_b32_e32 v89, v32
	v_mov_b32_e32 v90, v32
	v_mov_b32_e32 v91, v32
	v_mov_b32_e32 v92, v32
	v_mov_b32_e32 v93, v32
	v_mov_b32_e32 v94, v32
	v_mov_b32_e32 v95, v32
	v_lshlrev_b32_e32 v250, 1, v132
	s_lshl_b32 s27, s83, 22
	v_add_u32_e32 v230, s27, v250
	ds_read_b128 v[0:3], v133
	ds_read_b128 v[4:7], v133 offset:16
	v_add_u32_e32 v254, 64, v133
	v_mov_b32_e32 v255, v133
	s_mov_b32 s20, 0
	v_mov_b32_e32 v214, 0
	v_mov_b32_e32 v215, 0
	v_mov_b32_e32 v216, 0
	v_mov_b32_e32 v217, 0
	v_mov_b32_e32 v218, 0
	v_mov_b32_e32 v219, 0
	v_mov_b32_e32 v220, 0
	v_mov_b32_e32 v221, 0
	v_mov_b32_e32 v222, 0
	v_mov_b32_e32 v223, 0
	v_mov_b32_e32 v224, 0
	v_mov_b32_e32 v225, 0
	v_mov_b32_e32 v226, 0
	v_mov_b32_e32 v227, 0
	v_mov_b32_e32 v228, 0
	v_mov_b32_e32 v229, 0
	s_waitcnt lgkmcnt(0)
	v_and_or_b32 v8, v0, s66, v230
	global_load_dwordx4 v[150:153], v8, s[100:101]
	v_and_or_b32 v9, v1, s66, v230
	global_load_dwordx4 v[154:157], v9, s[100:101]
	v_and_or_b32 v8, v2, s66, v230
	global_load_dwordx4 v[158:161], v8, s[100:101]
	v_and_or_b32 v9, v3, s66, v230
	global_load_dwordx4 v[162:165], v9, s[100:101]
	v_and_or_b32 v8, v4, s66, v230
	global_load_dwordx4 v[166:169], v8, s[100:101]
	v_and_or_b32 v9, v5, s66, v230
	global_load_dwordx4 v[170:173], v9, s[100:101]
	v_and_or_b32 v8, v6, s66, v230
	global_load_dwordx4 v[174:177], v8, s[100:101]
	v_and_or_b32 v9, v7, s66, v230
	global_load_dwordx4 v[178:181], v9, s[100:101]
	ds_read_b128 v[0:3], v133 offset:32
	ds_read_b128 v[4:7], v133 offset:48
	s_waitcnt lgkmcnt(0)
	v_and_or_b32 v8, v0, s66, v230
	global_load_dwordx4 v[182:185], v8, s[100:101]
	v_and_or_b32 v9, v1, s66, v230
	global_load_dwordx4 v[186:189], v9, s[100:101]
	v_and_or_b32 v8, v2, s66, v230
	global_load_dwordx4 v[190:193], v8, s[100:101]
	v_and_or_b32 v9, v3, s66, v230
	global_load_dwordx4 v[194:197], v9, s[100:101]
	v_and_or_b32 v8, v4, s66, v230
	global_load_dwordx4 v[198:201], v8, s[100:101]
	v_and_or_b32 v9, v5, s66, v230
	global_load_dwordx4 v[202:205], v9, s[100:101]
	v_and_or_b32 v8, v6, s66, v230
	global_load_dwordx4 v[206:209], v8, s[100:101]
	v_and_or_b32 v9, v7, s66, v230
	global_load_dwordx4 v[210:213], v9, s[100:101]
	ds_read_b128 v[0:3], v133 offset:64
	ds_read_b128 v[96:99], v133 offset:2048
.Lgv_body:
	s_cmp_eq_u32 s20, 31
	s_cbranch_scc1 .Lgv_last
	s_waitcnt lgkmcnt(0)
	v_and_or_b32 v8, v0, s66, v230
	s_waitcnt vmcnt(15)
	v_cvt_pk_f32_fp8_e32 v[104:105], v150
	v_cvt_pk_f32_fp8_sdwa v[106:107], v150 src0_sel:WORD_1
	v_pk_fma_f32 v[214:215], v[96:97], v[104:105], v[214:215] op_sel_hi:[0,1,1]
	v_pk_fma_f32 v[216:217], v[96:97], v[106:107], v[216:217] op_sel_hi:[0,1,1]
	v_cvt_pk_f32_fp8_e32 v[108:109], v151
	v_cvt_pk_f32_fp8_sdwa v[110:111], v151 src0_sel:WORD_1
	v_pk_fma_f32 v[218:219], v[96:97], v[108:109], v[218:219] op_sel_hi:[0,1,1]
	v_pk_fma_f32 v[220:221], v[96:97], v[110:111], v[220:221] op_sel_hi:[0,1,1]
	v_cvt_pk_f32_fp8_e32 v[104:105], v152
	v_cvt_pk_f32_fp8_sdwa v[106:107], v152 src0_sel:WORD_1
	v_pk_fma_f32 v[222:223], v[96:97], v[104:105], v[222:223] op_sel_hi:[0,1,1]
	v_pk_fma_f32 v[224:225], v[96:97], v[106:107], v[224:225] op_sel_hi:[0,1,1]
	v_cvt_pk_f32_fp8_e32 v[108:109], v153
	v_cvt_pk_f32_fp8_sdwa v[110:111], v153 src0_sel:WORD_1
	v_pk_fma_f32 v[226:227], v[96:97], v[108:109], v[226:227] op_sel_hi:[0,1,1]
	v_pk_fma_f32 v[228:229], v[96:97], v[110:111], v[228:229] op_sel_hi:[0,1,1]
	global_load_dwordx4 v[150:153], v8, s[100:101]
	v_and_or_b32 v9, v1, s66, v230
	s_waitcnt vmcnt(15)
; __device__ void phase_gather(const P& p, int vb, int nvb, char* smem) {
;     ...
; #pragma unroll 8
;     for (int bb = 0; bb < 128; bb++) {
;       const uint32_t key = mykl[bb];
;       const int e = (int)(key >> 7);
;       const float wgt = mywl[bb];
;       const uint4* vp = (const uint4*)(V + (size_t)e * 1024 + 16 * j);
;       uint4 vv[4];
; #pragma unroll
;       for (int i = 0; i < 4; i++) vv[i] = vp[i * 16];
;       const f32x2 w2 = f32x2{wgt, wgt};
; #pragma unroll
;       for (int i = 0; i < 4; i++) {
;         const uint32_t w[4] = {vv[i].x, vv[i].y, vv[i].z, vv[i].w};
; #pragma unroll
;         for (int q = 0; q < 4; q++) {
;           acc[i * 8 + q * 2 + 0] += w2 * __builtin_amdgcn_cvt_pk_f32_fp8((int)w[q], false);
;           acc[i * 8 + q * 2 + 1] += w2 * __builtin_amdgcn_cvt_pk_f32_fp8((int)w[q], true);
;         }
;       }
;     }
	v_cvt_pk_f32_fp8_e32 v[104:105], v154
	v_cvt_pk_f32_fp8_sdwa v[106:107], v154 src0_sel:WORD_1
	v_pk_fma_f32 v[214:215], v[96:97], v[104:105], v[214:215] op_sel:[1,0,0]
	v_pk_fma_f32 v[216:217], v[96:97], v[106:107], v[216:217] op_sel:[1,0,0]
	v_cvt_pk_f32_fp8_e32 v[108:109], v155
	v_cvt_pk_f32_fp8_sdwa v[110:111], v155 src0_sel:WORD_1
	v_pk_fma_f32 v[218:219], v[96:97], v[108:109], v[218:219] op_sel:[1,0,0]
	v_pk_fma_f32 v[220:221], v[96:97], v[110:111], v[220:221] op_sel:[1,0,0]
	v_cvt_pk_f32_fp8_e32 v[104:105], v156
	v_cvt_pk_f32_fp8_sdwa v[106:107], v156 src0_sel:WORD_1
	v_pk_fma_f32 v[222:223], v[96:97], v[104:105], v[222:223] op_sel:[1,0,0]
	v_pk_fma_f32 v[224:225], v[96:97], v[106:107], v[224:225] op_sel:[1,0,0]
	v_cvt_pk_f32_fp8_e32 v[108:109], v157
	v_cvt_pk_f32_fp8_sdwa v[110:111], v157 src0_sel:WORD_1
	v_pk_fma_f32 v[226:227], v[96:97], v[108:109], v[226:227] op_sel:[1,0,0]
	v_pk_fma_f32 v[228:229], v[96:97], v[110:111], v[228:229] op_sel:[1,0,0]
	global_load_dwordx4 v[154:157], v9, s[100:101]
	ds_read_b128 v[4:7], v254 offset:16
	ds_read_b128 v[100:103], v255 offset:2064
	v_and_or_b32 v8, v2, s66, v230
	s_waitcnt vmcnt(15)
	v_cvt_pk_f32_fp8_e32 v[104:105], v158
	v_cvt_pk_f32_fp8_sdwa v[106:107], v158 src0_sel:WORD_1
	v_pk_fma_f32 v[214:215], v[98:99], v[104:105], v[214:215] op_sel_hi:[0,1,1]
	v_pk_fma_f32 v[216:217], v[98:99], v[106:107], v[216:217] op_sel_hi:[0,1,1]
	v_cvt_pk_f32_fp8_e32 v[108:109], v159
	v_cvt_pk_f32_fp8_sdwa v[110:111], v159 src0_sel:WORD_1
	v_pk_fma_f32 v[218:219], v[98:99], v[108:109], v[218:219] op_sel_hi:[0,1,1]
	v_pk_fma_f32 v[220:221], v[98:99], v[110:111], v[220:221] op_sel_hi:[0,1,1]
	v_cvt_pk_f32_fp8_e32 v[104:105], v160
	v_cvt_pk_f32_fp8_sdwa v[106:107], v160 src0_sel:WORD_1
	v_pk_fma_f32 v[222:223], v[98:99], v[104:105], v[222:223] op_sel_hi:[0,1,1]
	v_pk_fma_f32 v[224:225], v[98:99], v[106:107], v[224:225] op_sel_hi:[0,1,1]
	v_cvt_pk_f32_fp8_e32 v[108:109], v161
	v_cvt_pk_f32_fp8_sdwa v[110:111], v161 src0_sel:WORD_1
	v_pk_fma_f32 v[226:227], v[98:99], v[108:109], v[226:227] op_sel_hi:[0,1,1]
	v_pk_fma_f32 v[228:229], v[98:99], v[110:111], v[228:229] op_sel_hi:[0,1,1]
	global_load_dwordx4 v[158:161], v8, s[100:101]
	v_and_or_b32 v9, v3, s66, v230
	s_waitcnt vmcnt(15)
	v_cvt_pk_f32_fp8_e32 v[104:105], v162
	v_cvt_pk_f32_fp8_sdwa v[106:107], v162 src0_sel:WORD_1
	v_pk_fma_f32 v[214:215], v[98:99], v[104:105], v[214:215] op_sel:[1,0,0]
	v_pk_fma_f32 v[216:217], v[98:99], v[106:107], v[216:217] op_sel:[1,0,0]
	v_cvt_pk_f32_fp8_e32 v[108:109], v163
	v_cvt_pk_f32_fp8_sdwa v[110:111], v163 src0_sel:WORD_1
	v_pk_fma_f32 v[218:219], v[98:99], v[108:109], v[218:219] op_sel:[1,0,0]
	v_pk_fma_f32 v[220:221], v[98:99], v[110:111], v[220:221] op_sel:[1,0,0]
	v_cvt_pk_f32_fp8_e32 v[104:105], v164
	v_cvt_pk_f32_fp8_sdwa v[106:107], v164 src0_sel:WORD_1
	v_pk_fma_f32 v[222:223], v[98:99], v[104:105], v[222:223] op_sel:[1,0,0]
	v_pk_fma_f32 v[224:225], v[98:99], v[106:107], v[224:225] op_sel:[1,0,0]
	v_cvt_pk_f32_fp8_e32 v[108:109], v165
	v_cvt_pk_f32_fp8_sdwa v[110:111], v165 src0_sel:WORD_1
	v_pk_fma_f32 v[226:227], v[98:99], v[108:109], v[226:227] op_sel:[1,0,0]
	v_pk_fma_f32 v[228:229], v[98:99], v[110:111], v[228:229] op_sel:[1,0,0]
	global_load_dwordx4 v[162:165], v9, s[100:101]
	s_waitcnt lgkmcnt(0)
	v_and_or_b32 v8, v4, s66, v230
	s_waitcnt vmcnt(15)
	v_cvt_pk_f32_fp8_e32 v[104:105], v166
	v_cvt_pk_f32_fp8_sdwa v[106:107], v166 src0_sel:WORD_1
	v_pk_fma_f32 v[214:215], v[100:101], v[104:105], v[214:215] op_sel_hi:[0,1,1]
	v_pk_fma_f32 v[216:217], v[100:101], v[106:107], v[216:217] op_sel_hi:[0,1,1]
	v_cvt_pk_f32_fp8_e32 v[108:109], v167
	v_cvt_pk_f32_fp8_sdwa v[110:111], v167 src0_sel:WORD_1
	v_pk_fma_f32 v[218:219], v[100:101], v[108:109], v[218:219] op_sel_hi:[0,1,1]
	v_pk_fma_f32 v[220:221], v[100:101], v[110:111], v[220:221] op_sel_hi:[0,1,1]
	v_cvt_pk_f32_fp8_e32 v[104:105], v168
	v_cvt_pk_f32_fp8_sdwa v[106:107], v168 src0_sel:WORD_1
	v_pk_fma_f32 v[222:223], v[100:101], v[104:105], v[222:223] op_sel_hi:[0,1,1]
	v_pk_fma_f32 v[224:225], v[100:101], v[106:107], v[224:225] op_sel_hi:[0,1,1]
	v_cvt_pk_f32_fp8_e32 v[108:109], v169
	v_cvt_pk_f32_fp8_sdwa v[110:111], v169 src0_sel:WORD_1
	v_pk_fma_f32 v[226:227], v[100:101], v[108:109], v[226:227] op_sel_hi:[0,1,1]
	v_pk_fma_f32 v[228:229], v[100:101], v[110:111], v[228:229] op_sel_hi:[0,1,1]
	global_load_dwordx4 v[166:169], v8, s[100:101]
	v_and_or_b32 v9, v5, s66, v230
	s_waitcnt vmcnt(15)
	v_cvt_pk_f32_fp8_e32 v[104:105], v170
	v_cvt_pk_f32_fp8_sdwa v[106:107], v170 src0_sel:WORD_1
	v_pk_fma_f32 v[214:215], v[100:101], v[104:105], v[214:215] op_sel:[1,0,0]
	v_pk_fma_f32 v[216:217], v[100:101], v[106:107], v[216:217] op_sel:[1,0,0]
	v_cvt_pk_f32_fp8_e32 v[108:109], v171
	v_cvt_pk_f32_fp8_sdwa v[110:111], v171 src0_sel:WORD_1
	v_pk_fma_f32 v[218:219], v[100:101], v[108:109], v[218:219] op_sel:[1,0,0]
	v_pk_fma_f32 v[220:221], v[100:101], v[110:111], v[220:221] op_sel:[1,0,0]
	v_cvt_pk_f32_fp8_e32 v[104:105], v172
	v_cvt_pk_f32_fp8_sdwa v[106:107], v172 src0_sel:WORD_1
	v_pk_fma_f32 v[222:223], v[100:101], v[104:105], v[222:223] op_sel:[1,0,0]
	v_pk_fma_f32 v[224:225], v[100:101], v[106:107], v[224:225] op_sel:[1,0,0]
	v_cvt_pk_f32_fp8_e32 v[108:109], v173
	v_cvt_pk_f32_fp8_sdwa v[110:111], v173 src0_sel:WORD_1
	v_pk_fma_f32 v[226:227], v[100:101], v[108:109], v[226:227] op_sel:[1,0,0]
	v_pk_fma_f32 v[228:229], v[100:101], v[110:111], v[228:229] op_sel:[1,0,0]
	global_load_dwordx4 v[170:173], v9, s[100:101]
	ds_read_b128 v[0:3], v254 offset:32
	ds_read_b128 v[96:99], v255 offset:2080
	v_and_or_b32 v8, v6, s66, v230
	s_waitcnt vmcnt(15)
; __device__ void phase_gather(const P& p, int vb, int nvb, char* smem) {
;     ...
; #pragma unroll 8
;     for (int bb = 0; bb < 128; bb++) {
;       const uint32_t key = mykl[bb];
;       const int e = (int)(key >> 7);
;       const float wgt = mywl[bb];
;       const uint4* vp = (const uint4*)(V + (size_t)e * 1024 + 16 * j);
;       uint4 vv[4];
; #pragma unroll
;       for (int i = 0; i < 4; i++) vv[i] = vp[i * 16];
;       const f32x2 w2 = f32x2{wgt, wgt};
; #pragma unroll
;       for (int i = 0; i < 4; i++) {
;         const uint32_t w[4] = {vv[i].x, vv[i].y, vv[i].z, vv[i].w};
; #pragma unroll
;         for (int q = 0; q < 4; q++) {
;           acc[i * 8 + q * 2 + 0] += w2 * __builtin_amdgcn_cvt_pk_f32_fp8((int)w[q], false);
;           acc[i * 8 + q * 2 + 1] += w2 * __builtin_amdgcn_cvt_pk_f32_fp8((int)w[q], true);
;         }
;       }
;     }
	v_cvt_pk_f32_fp8_e32 v[104:105], v174
	v_cvt_pk_f32_fp8_sdwa v[106:107], v174 src0_sel:WORD_1
	v_pk_fma_f32 v[214:215], v[102:103], v[104:105], v[214:215] op_sel_hi:[0,1,1]
	v_pk_fma_f32 v[216:217], v[102:103], v[106:107], v[216:217] op_sel_hi:[0,1,1]
	v_cvt_pk_f32_fp8_e32 v[108:109], v175
	v_cvt_pk_f32_fp8_sdwa v[110:111], v175 src0_sel:WORD_1
	v_pk_fma_f32 v[218:219], v[102:103], v[108:109], v[218:219] op_sel_hi:[0,1,1]
	v_pk_fma_f32 v[220:221], v[102:103], v[110:111], v[220:221] op_sel_hi:[0,1,1]
	v_cvt_pk_f32_fp8_e32 v[104:105], v176
	v_cvt_pk_f32_fp8_sdwa v[106:107], v176 src0_sel:WORD_1
	v_pk_fma_f32 v[222:223], v[102:103], v[104:105], v[222:223] op_sel_hi:[0,1,1]
	v_pk_fma_f32 v[224:225], v[102:103], v[106:107], v[224:225] op_sel_hi:[0,1,1]
	v_cvt_pk_f32_fp8_e32 v[108:109], v177
	v_cvt_pk_f32_fp8_sdwa v[110:111], v177 src0_sel:WORD_1
	v_pk_fma_f32 v[226:227], v[102:103], v[108:109], v[226:227] op_sel_hi:[0,1,1]
	v_pk_fma_f32 v[228:229], v[102:103], v[110:111], v[228:229] op_sel_hi:[0,1,1]
	global_load_dwordx4 v[174:177], v8, s[100:101]
	v_and_or_b32 v9, v7, s66, v230
	s_waitcnt vmcnt(15)
	v_cvt_pk_f32_fp8_e32 v[104:105], v178
	v_cvt_pk_f32_fp8_sdwa v[106:107], v178 src0_sel:WORD_1
	v_pk_fma_f32 v[214:215], v[102:103], v[104:105], v[214:215] op_sel:[1,0,0]
	v_pk_fma_f32 v[216:217], v[102:103], v[106:107], v[216:217] op_sel:[1,0,0]
	v_cvt_pk_f32_fp8_e32 v[108:109], v179
	v_cvt_pk_f32_fp8_sdwa v[110:111], v179 src0_sel:WORD_1
	v_pk_fma_f32 v[218:219], v[102:103], v[108:109], v[218:219] op_sel:[1,0,0]
	v_pk_fma_f32 v[220:221], v[102:103], v[110:111], v[220:221] op_sel:[1,0,0]
	v_cvt_pk_f32_fp8_e32 v[104:105], v180
	v_cvt_pk_f32_fp8_sdwa v[106:107], v180 src0_sel:WORD_1
	v_pk_fma_f32 v[222:223], v[102:103], v[104:105], v[222:223] op_sel:[1,0,0]
	v_pk_fma_f32 v[224:225], v[102:103], v[106:107], v[224:225] op_sel:[1,0,0]
	v_cvt_pk_f32_fp8_e32 v[108:109], v181
	v_cvt_pk_f32_fp8_sdwa v[110:111], v181 src0_sel:WORD_1
	v_pk_fma_f32 v[226:227], v[102:103], v[108:109], v[226:227] op_sel:[1,0,0]
	v_pk_fma_f32 v[228:229], v[102:103], v[110:111], v[228:229] op_sel:[1,0,0]
	global_load_dwordx4 v[178:181], v9, s[100:101]
	s_waitcnt lgkmcnt(0)
	v_and_or_b32 v8, v0, s66, v230
	s_waitcnt vmcnt(15)
	v_cvt_pk_f32_fp8_e32 v[104:105], v182
	v_cvt_pk_f32_fp8_sdwa v[106:107], v182 src0_sel:WORD_1
	v_pk_fma_f32 v[214:215], v[96:97], v[104:105], v[214:215] op_sel_hi:[0,1,1]
	v_pk_fma_f32 v[216:217], v[96:97], v[106:107], v[216:217] op_sel_hi:[0,1,1]
	v_cvt_pk_f32_fp8_e32 v[108:109], v183
	v_cvt_pk_f32_fp8_sdwa v[110:111], v183 src0_sel:WORD_1
	v_pk_fma_f32 v[218:219], v[96:97], v[108:109], v[218:219] op_sel_hi:[0,1,1]
	v_pk_fma_f32 v[220:221], v[96:97], v[110:111], v[220:221] op_sel_hi:[0,1,1]
	v_cvt_pk_f32_fp8_e32 v[104:105], v184
	v_cvt_pk_f32_fp8_sdwa v[106:107], v184 src0_sel:WORD_1
	v_pk_fma_f32 v[222:223], v[96:97], v[104:105], v[222:223] op_sel_hi:[0,1,1]
	v_pk_fma_f32 v[224:225], v[96:97], v[106:107], v[224:225] op_sel_hi:[0,1,1]
	v_cvt_pk_f32_fp8_e32 v[108:109], v185
	v_cvt_pk_f32_fp8_sdwa v[110:111], v185 src0_sel:WORD_1
	v_pk_fma_f32 v[226:227], v[96:97], v[108:109], v[226:227] op_sel_hi:[0,1,1]
	v_pk_fma_f32 v[228:229], v[96:97], v[110:111], v[228:229] op_sel_hi:[0,1,1]
	global_load_dwordx4 v[182:185], v8, s[100:101]
	v_and_or_b32 v9, v1, s66, v230
	s_waitcnt vmcnt(15)
	v_cvt_pk_f32_fp8_e32 v[104:105], v186
	v_cvt_pk_f32_fp8_sdwa v[106:107], v186 src0_sel:WORD_1
	v_pk_fma_f32 v[214:215], v[96:97], v[104:105], v[214:215] op_sel:[1,0,0]
	v_pk_fma_f32 v[216:217], v[96:97], v[106:107], v[216:217] op_sel:[1,0,0]
	v_cvt_pk_f32_fp8_e32 v[108:109], v187
	v_cvt_pk_f32_fp8_sdwa v[110:111], v187 src0_sel:WORD_1
	v_pk_fma_f32 v[218:219], v[96:97], v[108:109], v[218:219] op_sel:[1,0,0]
	v_pk_fma_f32 v[220:221], v[96:97], v[110:111], v[220:221] op_sel:[1,0,0]
	v_cvt_pk_f32_fp8_e32 v[104:105], v188
	v_cvt_pk_f32_fp8_sdwa v[106:107], v188 src0_sel:WORD_1
	v_pk_fma_f32 v[222:223], v[96:97], v[104:105], v[222:223] op_sel:[1,0,0]
	v_pk_fma_f32 v[224:225], v[96:97], v[106:107], v[224:225] op_sel:[1,0,0]
	v_cvt_pk_f32_fp8_e32 v[108:109], v189
	v_cvt_pk_f32_fp8_sdwa v[110:111], v189 src0_sel:WORD_1
	v_pk_fma_f32 v[226:227], v[96:97], v[108:109], v[226:227] op_sel:[1,0,0]
	v_pk_fma_f32 v[228:229], v[96:97], v[110:111], v[228:229] op_sel:[1,0,0]
	global_load_dwordx4 v[186:189], v9, s[100:101]
	ds_read_b128 v[4:7], v254 offset:48
	ds_read_b128 v[100:103], v255 offset:2096
	v_and_or_b32 v8, v2, s66, v230
	s_waitcnt vmcnt(15)
	v_cvt_pk_f32_fp8_e32 v[104:105], v190
	v_cvt_pk_f32_fp8_sdwa v[106:107], v190 src0_sel:WORD_1
	v_pk_fma_f32 v[214:215], v[98:99], v[104:105], v[214:215] op_sel_hi:[0,1,1]
	v_pk_fma_f32 v[216:217], v[98:99], v[106:107], v[216:217] op_sel_hi:[0,1,1]
	v_cvt_pk_f32_fp8_e32 v[108:109], v191
	v_cvt_pk_f32_fp8_sdwa v[110:111], v191 src0_sel:WORD_1
	v_pk_fma_f32 v[218:219], v[98:99], v[108:109], v[218:219] op_sel_hi:[0,1,1]
	v_pk_fma_f32 v[220:221], v[98:99], v[110:111], v[220:221] op_sel_hi:[0,1,1]
	v_cvt_pk_f32_fp8_e32 v[104:105], v192
	v_cvt_pk_f32_fp8_sdwa v[106:107], v192 src0_sel:WORD_1
	v_pk_fma_f32 v[222:223], v[98:99], v[104:105], v[222:223] op_sel_hi:[0,1,1]
	v_pk_fma_f32 v[224:225], v[98:99], v[106:107], v[224:225] op_sel_hi:[0,1,1]
	v_cvt_pk_f32_fp8_e32 v[108:109], v193
	v_cvt_pk_f32_fp8_sdwa v[110:111], v193 src0_sel:WORD_1
	v_pk_fma_f32 v[226:227], v[98:99], v[108:109], v[226:227] op_sel_hi:[0,1,1]
	v_pk_fma_f32 v[228:229], v[98:99], v[110:111], v[228:229] op_sel_hi:[0,1,1]
	global_load_dwordx4 v[190:193], v8, s[100:101]
	v_and_or_b32 v9, v3, s66, v230
	s_waitcnt vmcnt(15)
; __device__ void phase_gather(const P& p, int vb, int nvb, char* smem) {
;     ...
; #pragma unroll 8
;     for (int bb = 0; bb < 128; bb++) {
;       const uint32_t key = mykl[bb];
;       const int e = (int)(key >> 7);
;       const float wgt = mywl[bb];
;       const uint4* vp = (const uint4*)(V + (size_t)e * 1024 + 16 * j);
;       uint4 vv[4];
; #pragma unroll
;       for (int i = 0; i < 4; i++) vv[i] = vp[i * 16];
;       const f32x2 w2 = f32x2{wgt, wgt};
; #pragma unroll
;       for (int i = 0; i < 4; i++) {
;         const uint32_t w[4] = {vv[i].x, vv[i].y, vv[i].z, vv[i].w};
; #pragma unroll
;         for (int q = 0; q < 4; q++) {
;           acc[i * 8 + q * 2 + 0] += w2 * __builtin_amdgcn_cvt_pk_f32_fp8((int)w[q], false);
;           acc[i * 8 + q * 2 + 1] += w2 * __builtin_amdgcn_cvt_pk_f32_fp8((int)w[q], true);
;         }
;       }
;     }
	v_cvt_pk_f32_fp8_e32 v[104:105], v194
	v_cvt_pk_f32_fp8_sdwa v[106:107], v194 src0_sel:WORD_1
	v_pk_fma_f32 v[214:215], v[98:99], v[104:105], v[214:215] op_sel:[1,0,0]
	v_pk_fma_f32 v[216:217], v[98:99], v[106:107], v[216:217] op_sel:[1,0,0]
	v_cvt_pk_f32_fp8_e32 v[108:109], v195
	v_cvt_pk_f32_fp8_sdwa v[110:111], v195 src0_sel:WORD_1
	v_pk_fma_f32 v[218:219], v[98:99], v[108:109], v[218:219] op_sel:[1,0,0]
	v_pk_fma_f32 v[220:221], v[98:99], v[110:111], v[220:221] op_sel:[1,0,0]
	v_cvt_pk_f32_fp8_e32 v[104:105], v196
	v_cvt_pk_f32_fp8_sdwa v[106:107], v196 src0_sel:WORD_1
	v_pk_fma_f32 v[222:223], v[98:99], v[104:105], v[222:223] op_sel:[1,0,0]
	v_pk_fma_f32 v[224:225], v[98:99], v[106:107], v[224:225] op_sel:[1,0,0]
	v_cvt_pk_f32_fp8_e32 v[108:109], v197
	v_cvt_pk_f32_fp8_sdwa v[110:111], v197 src0_sel:WORD_1
	v_pk_fma_f32 v[226:227], v[98:99], v[108:109], v[226:227] op_sel:[1,0,0]
	v_pk_fma_f32 v[228:229], v[98:99], v[110:111], v[228:229] op_sel:[1,0,0]
	global_load_dwordx4 v[194:197], v9, s[100:101]
	s_waitcnt lgkmcnt(0)
	v_and_or_b32 v8, v4, s66, v230
	s_waitcnt vmcnt(15)
	v_cvt_pk_f32_fp8_e32 v[104:105], v198
	v_cvt_pk_f32_fp8_sdwa v[106:107], v198 src0_sel:WORD_1
	v_pk_fma_f32 v[214:215], v[100:101], v[104:105], v[214:215] op_sel_hi:[0,1,1]
	v_pk_fma_f32 v[216:217], v[100:101], v[106:107], v[216:217] op_sel_hi:[0,1,1]
	v_cvt_pk_f32_fp8_e32 v[108:109], v199
	v_cvt_pk_f32_fp8_sdwa v[110:111], v199 src0_sel:WORD_1
	v_pk_fma_f32 v[218:219], v[100:101], v[108:109], v[218:219] op_sel_hi:[0,1,1]
	v_pk_fma_f32 v[220:221], v[100:101], v[110:111], v[220:221] op_sel_hi:[0,1,1]
	v_cvt_pk_f32_fp8_e32 v[104:105], v200
	v_cvt_pk_f32_fp8_sdwa v[106:107], v200 src0_sel:WORD_1
	v_pk_fma_f32 v[222:223], v[100:101], v[104:105], v[222:223] op_sel_hi:[0,1,1]
	v_pk_fma_f32 v[224:225], v[100:101], v[106:107], v[224:225] op_sel_hi:[0,1,1]
	v_cvt_pk_f32_fp8_e32 v[108:109], v201
	v_cvt_pk_f32_fp8_sdwa v[110:111], v201 src0_sel:WORD_1
	v_pk_fma_f32 v[226:227], v[100:101], v[108:109], v[226:227] op_sel_hi:[0,1,1]
	v_pk_fma_f32 v[228:229], v[100:101], v[110:111], v[228:229] op_sel_hi:[0,1,1]
	global_load_dwordx4 v[198:201], v8, s[100:101]
	s_add_i32 s27, s20, 2
	s_and_b32 s27, s27, 7
	s_lshl_b32 s27, s27, 6
	v_add_u32_e32 v254, s27, v133
	s_add_i32 s27, s20, 1
	s_and_b32 s27, s27, 7
	s_lshl_b32 s27, s27, 6
	v_add_u32_e32 v255, s27, v133
	v_and_or_b32 v9, v5, s66, v230
	s_waitcnt vmcnt(15)
	v_cvt_pk_f32_fp8_e32 v[104:105], v202
	v_cvt_pk_f32_fp8_sdwa v[106:107], v202 src0_sel:WORD_1
	v_pk_fma_f32 v[214:215], v[100:101], v[104:105], v[214:215] op_sel:[1,0,0]
	v_pk_fma_f32 v[216:217], v[100:101], v[106:107], v[216:217] op_sel:[1,0,0]
	v_cvt_pk_f32_fp8_e32 v[108:109], v203
	v_cvt_pk_f32_fp8_sdwa v[110:111], v203 src0_sel:WORD_1
	v_pk_fma_f32 v[218:219], v[100:101], v[108:109], v[218:219] op_sel:[1,0,0]
	v_pk_fma_f32 v[220:221], v[100:101], v[110:111], v[220:221] op_sel:[1,0,0]
	v_cvt_pk_f32_fp8_e32 v[104:105], v204
	v_cvt_pk_f32_fp8_sdwa v[106:107], v204 src0_sel:WORD_1
	v_pk_fma_f32 v[222:223], v[100:101], v[104:105], v[222:223] op_sel:[1,0,0]
	v_pk_fma_f32 v[224:225], v[100:101], v[106:107], v[224:225] op_sel:[1,0,0]
	v_cvt_pk_f32_fp8_e32 v[108:109], v205
	v_cvt_pk_f32_fp8_sdwa v[110:111], v205 src0_sel:WORD_1
	v_pk_fma_f32 v[226:227], v[100:101], v[108:109], v[226:227] op_sel:[1,0,0]
	v_pk_fma_f32 v[228:229], v[100:101], v[110:111], v[228:229] op_sel:[1,0,0]
	global_load_dwordx4 v[202:205], v9, s[100:101]
	ds_read_b128 v[0:3], v254
	ds_read_b128 v[96:99], v255 offset:2048
	v_and_or_b32 v8, v6, s66, v230
	s_waitcnt vmcnt(15)
	v_cvt_pk_f32_fp8_e32 v[104:105], v206
	v_cvt_pk_f32_fp8_sdwa v[106:107], v206 src0_sel:WORD_1
	v_pk_fma_f32 v[214:215], v[102:103], v[104:105], v[214:215] op_sel_hi:[0,1,1]
	v_pk_fma_f32 v[216:217], v[102:103], v[106:107], v[216:217] op_sel_hi:[0,1,1]
	v_cvt_pk_f32_fp8_e32 v[108:109], v207
	v_cvt_pk_f32_fp8_sdwa v[110:111], v207 src0_sel:WORD_1
	v_pk_fma_f32 v[218:219], v[102:103], v[108:109], v[218:219] op_sel_hi:[0,1,1]
	v_pk_fma_f32 v[220:221], v[102:103], v[110:111], v[220:221] op_sel_hi:[0,1,1]
	v_cvt_pk_f32_fp8_e32 v[104:105], v208
	v_cvt_pk_f32_fp8_sdwa v[106:107], v208 src0_sel:WORD_1
	v_pk_fma_f32 v[222:223], v[102:103], v[104:105], v[222:223] op_sel_hi:[0,1,1]
	v_pk_fma_f32 v[224:225], v[102:103], v[106:107], v[224:225] op_sel_hi:[0,1,1]
	v_cvt_pk_f32_fp8_e32 v[108:109], v209
	v_cvt_pk_f32_fp8_sdwa v[110:111], v209 src0_sel:WORD_1
	v_pk_fma_f32 v[226:227], v[102:103], v[108:109], v[226:227] op_sel_hi:[0,1,1]
	v_pk_fma_f32 v[228:229], v[102:103], v[110:111], v[228:229] op_sel_hi:[0,1,1]
	global_load_dwordx4 v[206:209], v8, s[100:101]
	v_and_or_b32 v9, v7, s66, v230
	s_waitcnt vmcnt(15)
	v_cvt_pk_f32_fp8_e32 v[104:105], v210
	v_cvt_pk_f32_fp8_sdwa v[106:107], v210 src0_sel:WORD_1
	v_pk_fma_f32 v[214:215], v[102:103], v[104:105], v[214:215] op_sel:[1,0,0]
	v_pk_fma_f32 v[216:217], v[102:103], v[106:107], v[216:217] op_sel:[1,0,0]
	v_cvt_pk_f32_fp8_e32 v[108:109], v211
	v_cvt_pk_f32_fp8_sdwa v[110:111], v211 src0_sel:WORD_1
	v_pk_fma_f32 v[218:219], v[102:103], v[108:109], v[218:219] op_sel:[1,0,0]
	v_pk_fma_f32 v[220:221], v[102:103], v[110:111], v[220:221] op_sel:[1,0,0]
	v_cvt_pk_f32_fp8_e32 v[104:105], v212
	v_cvt_pk_f32_fp8_sdwa v[106:107], v212 src0_sel:WORD_1
	v_pk_fma_f32 v[222:223], v[102:103], v[104:105], v[222:223] op_sel:[1,0,0]
	v_pk_fma_f32 v[224:225], v[102:103], v[106:107], v[224:225] op_sel:[1,0,0]
	v_cvt_pk_f32_fp8_e32 v[108:109], v213
	v_cvt_pk_f32_fp8_sdwa v[110:111], v213 src0_sel:WORD_1
	v_pk_fma_f32 v[226:227], v[102:103], v[108:109], v[226:227] op_sel:[1,0,0]
	v_pk_fma_f32 v[228:229], v[102:103], v[110:111], v[228:229] op_sel:[1,0,0]
	global_load_dwordx4 v[210:213], v9, s[100:101]
	s_add_i32 s20, s20, 1
	s_add_i32 s27, s20, 1
	s_lshr_b32 s27, s27, 3
	s_add_i32 s27, s27, s83
	s_and_b32 s27, s27, 3
	s_lshl_b32 s27, s27, 22
	v_add_u32_e32 v230, s27, v250
	s_and_b32 s27, s20, 7
	s_cmp_lg_u32 s27, 0
	s_cbranch_scc1 .Lgv_body
	s_lshr_b32 s27, s20, 3
	s_add_i32 s27, s27, s83
	s_add_i32 s27, s27, 3
	s_and_b32 s27, s27, 3
	s_cmp_eq_u32 s27, 0
	s_cbranch_scc1 .Lgv_s_0
	s_cmp_eq_u32 s27, 1
	s_cbranch_scc1 .Lgv_s_1
	s_cmp_eq_u32 s27, 2
	s_cbranch_scc1 .Lgv_s_2
	v_mov_b32_e32 v46, v214
	v_mov_b32_e32 v47, v215
	v_mov_b32_e32 v44, v216
	v_mov_b32_e32 v45, v217
	v_mov_b32_e32 v42, v218
	v_mov_b32_e32 v43, v219
	v_mov_b32_e32 v40, v220
	v_mov_b32_e32 v41, v221
	v_mov_b32_e32 v38, v222
	v_mov_b32_e32 v39, v223
	v_mov_b32_e32 v36, v224
	v_mov_b32_e32 v37, v225
	v_mov_b32_e32 v34, v226
	v_mov_b32_e32 v35, v227
	v_mov_b32_e32 v32, v228
	v_mov_b32_e32 v33, v229
	s_branch .Lgv_s_x
